# v23: v20 + top-k: wave max key computed once per row, bit-passes whose candidate exceeds it are skipped (count would be 0)
# speedup vs baseline: 1.0026x; 1.0026x over previous
; DI size_t sc_row_off(int b, int s) { const int qb = s >> 7; return ((size_t)(b * 2080 + ((qb * (qb + 1)) >> 1))) * 16384 + (size_t)(s & 127) * ((qb + 1) * 128); }
; DI unsigned f2key(float f) { const unsigned u = __float_as_uint(f); return (u & 0x80000000u) ? ~u : (u | 0x80000000u); }
; template <int NV>
; DI void topk_row(const float* row, int s, LAS int* lst, int lane) {
;     ...
;     { const unsigned long long ra = (unsigned long long)row; const unsigned rlo = __builtin_amdgcn_readfirstlane((unsigned)ra), rhi = __builtin_amdgcn_readfirstlane((unsigned)(ra >> 32));
;       row = (const float*)(((unsigned long long)rhi << 32) | rlo); }
; #pragma unroll
;     for (int jo = 0; jo < NV / 16; ++jo) { const float* rb = row + jo * 1024;
; #pragma unroll
;         for (int ji = 0; ji < 16; ++ji) { const int j = jo * 16 + ji; const unsigned u = f2key(rb[ji * 64 + lane]); key[j] = (j * 64 + lane <= s) ? u : 0u; } }
; DI void topk_phase(const float* SC, unsigned short* IDX, LAS unsigned char* lds, int tid, int bid, int G) {
;     ...
;             const float* row = SC + sc_row_off(b, s);
;             if (s < 2048) topk_row<32>(row, s, lst, lane);
;             else if (s < 4096) topk_row<64>(row, s, lst, lane);
;             else if (s < 6144) topk_row<96>(row, s, lst, lane);
;             else topk_row<128>(row, s, lst, lane);
.LBB0_1965:
	s_lshr_b32 s1, s85, 7
	s_add_i32 s2, s1, 1
	s_ashr_i32 s0, s8, 13
	s_mul_i32 s1, s2, s1
	s_mulk_i32 s0, 0x820
	s_lshr_b32 s1, s1, 1
	s_add_i32 s0, s1, s0
	s_ashr_i32 s1, s0, 31
	s_lshl_b32 s3, s8, 7
	s_and_b32 s3, s3, 0x3f80
	s_lshl_b64 s[0:1], s[0:1], 16
	s_mul_i32 s2, s2, s3
	s_add_u32 s0, s14, s0
	s_addc_u32 s1, s15, s1
	s_lshl_b32 s2, s2, 2
	s_add_u32 s12, s0, s2
	s_addc_u32 s13, s1, 0
	s_cmpk_gt_u32 s85, 0x7ff
	v_sub_u32_e32 v161, s85, v2
	s_cbranch_scc0 .LBB0_2481
	s_cmpk_gt_u32 s85, 0xfff
	s_cbranch_scc0 .LBB0_2482
	s_cmpk_gt_u32 s85, 0x17ff
	s_cbranch_scc0 .LBB0_2483
	v_lshlrev_b32_e32 v0, 2, v2
	v_lshl_add_u64 v[40:41], s[12:13], 0, v[0:1]
	flat_load_dword v48, v[40:41]
	flat_load_dword v49, v[40:41] offset:256
	flat_load_dword v50, v[40:41] offset:512
	flat_load_dword v51, v[40:41] offset:768
	flat_load_dword v52, v[40:41] offset:1024
	flat_load_dword v53, v[40:41] offset:1280
	flat_load_dword v54, v[40:41] offset:1536
	flat_load_dword v55, v[40:41] offset:1792
	flat_load_dword v56, v[40:41] offset:2048
	flat_load_dword v57, v[40:41] offset:2304
	flat_load_dword v58, v[40:41] offset:2560
	flat_load_dword v59, v[40:41] offset:2816
	flat_load_dword v60, v[40:41] offset:3072
	flat_load_dword v128, v[40:41] offset:3328
	flat_load_dword v129, v[40:41] offset:3584
	flat_load_dword v130, v[40:41] offset:3840
	s_add_u32 s0, s12, 0x1000
	s_addc_u32 s1, s13, 0
	v_lshlrev_b32_e32 v38, 2, v4
	v_mov_b32_e32 v39, v1
	v_lshlrev_b32_e32 v36, 2, v6
	v_mov_b32_e32 v37, v1
	v_lshlrev_b32_e32 v34, 2, v8
	v_mov_b32_e32 v35, v1
	v_lshl_add_u64 v[40:41], s[0:1], 0, v[0:1]
	v_lshl_add_u64 v[42:43], s[0:1], 0, v[38:39]
	v_lshl_add_u64 v[44:45], s[0:1], 0, v[36:37]
	v_lshl_add_u64 v[46:47], s[0:1], 0, v[34:35]
	flat_load_dword v131, v[40:41]
	flat_load_dword v162, v[42:43]
	flat_load_dword v164, v[44:45]
	flat_load_dword v165, v[46:47]
	s_movk_i32 s2, 0x17ff
	s_waitcnt vmcnt(0) lgkmcnt(0)
	v_not_b32_e32 v40, v48
	v_or_b32_e32 v41, 0x80000000, v48
	v_cmp_gt_i32_e32 vcc, 0, v48
	v_not_b32_e32 v42, v49
	v_or_b32_e32 v43, 0x80000000, v49
	v_cndmask_b32_e32 v141, v41, v40, vcc
	v_cmp_gt_i32_e32 vcc, 0, v49
	v_not_b32_e32 v44, v50
	v_or_b32_e32 v45, 0x80000000, v50
	v_cndmask_b32_e32 v140, v43, v42, vcc
	v_cmp_gt_i32_e32 vcc, 0, v50
	v_not_b32_e32 v46, v51
	v_or_b32_e32 v47, 0x80000000, v51
	v_cndmask_b32_e32 v139, v45, v44, vcc
	v_cmp_gt_i32_e32 vcc, 0, v51
	v_not_b32_e32 v61, v52
	v_or_b32_e32 v62, 0x80000000, v52
	v_cndmask_b32_e32 v138, v47, v46, vcc
	v_cmp_gt_i32_e32 vcc, 0, v52
	v_not_b32_e32 v63, v53
	v_or_b32_e32 v132, 0x80000000, v53
	v_cndmask_b32_e32 v137, v62, v61, vcc
	v_cmp_gt_i32_e32 vcc, 0, v53
	v_not_b32_e32 v133, v54
	v_or_b32_e32 v134, 0x80000000, v54
	v_cndmask_b32_e32 v136, v132, v63, vcc
	v_cmp_gt_i32_e32 vcc, 0, v54
	v_not_b32_e32 v163, v55
	v_or_b32_e32 v166, 0x80000000, v55
	v_cndmask_b32_e32 v135, v134, v133, vcc
	v_cmp_gt_i32_e32 vcc, 0, v55
	v_not_b32_e32 v167, v56
	v_or_b32_e32 v168, 0x80000000, v56
	v_cndmask_b32_e32 v134, v166, v163, vcc
	v_cmp_gt_i32_e32 vcc, 0, v56
	v_not_b32_e32 v169, v57
	v_or_b32_e32 v170, 0x80000000, v57
	v_cndmask_b32_e32 v133, v168, v167, vcc
	v_cmp_gt_i32_e32 vcc, 0, v57
	v_not_b32_e32 v171, v58
	v_or_b32_e32 v172, 0x80000000, v58
	v_cndmask_b32_e32 v132, v170, v169, vcc
	v_cmp_gt_i32_e32 vcc, 0, v58
	v_not_b32_e32 v173, v59
	v_or_b32_e32 v174, 0x80000000, v59
	v_cndmask_b32_e32 v251, v172, v171, vcc
	v_cmp_gt_i32_e32 vcc, 0, v59
	v_lshlrev_b32_e32 v62, 2, v10
	v_mov_b32_e32 v63, v1
	v_not_b32_e32 v175, v60
	v_or_b32_e32 v176, 0x80000000, v60
	v_cndmask_b32_e32 v248, v174, v173, vcc
	v_lshl_add_u64 v[40:41], s[0:1], 0, v[62:63]
	v_cmp_gt_i32_e32 vcc, 0, v60
	v_lshlrev_b32_e32 v60, 2, v12
	v_mov_b32_e32 v61, v1
	flat_load_dword v166, v[40:41]
	v_lshl_add_u64 v[40:41], s[0:1], 0, v[60:61]
	flat_load_dword v167, v[40:41]
	v_lshlrev_b32_e32 v58, 2, v14
	v_mov_b32_e32 v59, v1
	v_lshl_add_u64 v[40:41], s[0:1], 0, v[58:59]
	flat_load_dword v168, v[40:41]
	v_lshlrev_b32_e32 v56, 2, v16
	v_mov_b32_e32 v57, v1
	v_lshl_add_u64 v[40:41], s[0:1], 0, v[56:57]
	flat_load_dword v169, v[40:41]
	v_lshlrev_b32_e32 v52, 2, v18
	v_mov_b32_e32 v53, v1
	v_cndmask_b32_e32 v247, v176, v175, vcc
	v_not_b32_e32 v42, v128
	v_or_b32_e32 v43, 0x80000000, v128
	v_cmp_gt_i32_e32 vcc, 0, v128
	v_lshl_add_u64 v[40:41], s[0:1], 0, v[52:53]
	flat_load_dword v170, v[40:41]
	v_cndmask_b32_e32 v253, v43, v42, vcc
	v_not_b32_e32 v42, v129
	v_or_b32_e32 v40, 0x80000000, v129
	v_cmp_gt_i32_e32 vcc, 0, v129
	v_lshlrev_b32_e32 v54, 2, v20
	v_mov_b32_e32 v55, v1
	v_cndmask_b32_e32 v249, v40, v42, vcc
	v_lshl_add_u64 v[40:41], s[0:1], 0, v[54:55]
	flat_load_dword v171, v[40:41]
	v_lshlrev_b32_e32 v50, 2, v22
	v_mov_b32_e32 v51, v1
	v_lshl_add_u64 v[40:41], s[0:1], 0, v[50:51]
	flat_load_dword v172, v[40:41]
	v_lshlrev_b32_e32 v48, 2, v24
	v_mov_b32_e32 v49, v1
	v_lshl_add_u64 v[40:41], s[0:1], 0, v[48:49]
	flat_load_dword v173, v[40:41]
	v_lshlrev_b32_e32 v46, 2, v26
	v_mov_b32_e32 v47, v1
	v_lshl_add_u64 v[40:41], s[0:1], 0, v[46:47]
	flat_load_dword v174, v[40:41]
	v_lshlrev_b32_e32 v44, 2, v28
	v_mov_b32_e32 v45, v1
	v_lshl_add_u64 v[40:41], s[0:1], 0, v[44:45]
	flat_load_dword v175, v[40:41]
	v_not_b32_e32 v42, v130
	v_or_b32_e32 v43, 0x80000000, v130
	v_cmp_gt_i32_e32 vcc, 0, v130
	v_not_b32_e32 v129, v162
	v_or_b32_e32 v130, 0x80000000, v162
	v_cndmask_b32_e32 v252, v43, v42, vcc
	v_not_b32_e32 v42, v131
	v_or_b32_e32 v43, 0x80000000, v131
	v_cmp_gt_i32_e32 vcc, 0, v131
	v_or_b32_e32 v131, 0x80000000, v164
	s_nop 0
	v_cndmask_b32_e32 v128, v43, v42, vcc
	v_lshlrev_b32_e32 v42, 2, v30
	v_mov_b32_e32 v43, v1
	v_lshl_add_u64 v[40:41], s[0:1], 0, v[42:43]
	flat_load_dword v176, v[40:41]
	v_lshlrev_b32_e32 v40, 2, v32
	v_mov_b32_e32 v41, v1
	v_cmp_gt_i32_e32 vcc, 0, v162
	v_lshl_add_u64 v[162:163], s[0:1], 0, v[40:41]
	s_add_u32 s0, s12, 0x2000
	flat_load_dword v177, v[162:163]
	s_addc_u32 s1, s13, 0
	v_lshl_add_u64 v[162:163], s[0:1], 0, v[0:1]
	v_cndmask_b32_e32 v130, v130, v129, vcc
	v_not_b32_e32 v129, v164
	flat_load_dword v178, v[162:163]
	v_cmp_gt_i32_e32 vcc, 0, v164
	v_or_b32_e32 v164, 0x80000000, v165
	v_lshl_add_u64 v[162:163], s[0:1], 0, v[38:39]
	v_cndmask_b32_e32 v131, v131, v129, vcc
	v_not_b32_e32 v129, v165
	v_cmp_gt_i32_e32 vcc, 0, v165
	flat_load_dword v179, v[162:163]
	v_lshl_add_u64 v[162:163], s[0:1], 0, v[36:37]
	v_cndmask_b32_e32 v129, v164, v129, vcc
	s_waitcnt vmcnt(0) lgkmcnt(0)
; DI unsigned f2key(float f) { const unsigned u = __float_as_uint(f); return (u & 0x80000000u) ? ~u : (u | 0x80000000u); }
; template <int NV>
; DI void topk_row(const float* row, int s, LAS int* lst, int lane) {
;     ...
;     for (int jo = 0; jo < NV / 16; ++jo) { const float* rb = row + jo * 1024;
; #pragma unroll
;         for (int ji = 0; ji < 16; ++ji) { const int j = jo * 16 + ji; const unsigned u = f2key(rb[ji * 64 + lane]); key[j] = (j * 64 + lane <= s) ? u : 0u; } }
	v_not_b32_e32 v164, v166
	v_or_b32_e32 v165, 0x80000000, v166
	v_cmp_gt_i32_e32 vcc, 0, v166
	flat_load_dword v180, v[162:163]
	v_not_b32_e32 v162, v167
	v_cndmask_b32_e32 v250, v165, v164, vcc
	v_or_b32_e32 v163, 0x80000000, v167
	v_cmp_gt_i32_e32 vcc, 0, v167
	v_not_b32_e32 v164, v168
	s_nop 0
	v_cndmask_b32_e32 v246, v163, v162, vcc
	v_lshl_add_u64 v[162:163], s[0:1], 0, v[34:35]
	flat_load_dword v165, v[162:163]
	v_or_b32_e32 v162, 0x80000000, v168
	v_cmp_gt_i32_e32 vcc, 0, v168
	v_or_b32_e32 v168, 0x80000000, v170
	s_nop 0
	v_cndmask_b32_e32 v245, v162, v164, vcc
	v_lshl_add_u64 v[162:163], s[0:1], 0, v[62:63]
	v_not_b32_e32 v164, v169
	flat_load_dword v166, v[162:163]
	v_or_b32_e32 v162, 0x80000000, v169
	v_cmp_gt_i32_e32 vcc, 0, v169
	s_nop 1
	v_cndmask_b32_e32 v244, v162, v164, vcc
	v_lshl_add_u64 v[162:163], s[0:1], 0, v[60:61]
	flat_load_dword v167, v[162:163]
	v_lshl_add_u64 v[162:163], s[0:1], 0, v[58:59]
	flat_load_dword v169, v[162:163]
	v_lshl_add_u64 v[162:163], s[0:1], 0, v[56:57]
	v_not_b32_e32 v164, v170
	v_cmp_gt_i32_e32 vcc, 0, v170
	flat_load_dword v170, v[162:163]
	v_lshl_add_u64 v[162:163], s[0:1], 0, v[52:53]
	v_cndmask_b32_e32 v243, v168, v164, vcc
	v_not_b32_e32 v164, v171
	v_or_b32_e32 v168, 0x80000000, v171
	v_cmp_gt_i32_e32 vcc, 0, v171
	flat_load_dword v171, v[162:163]
	v_lshl_add_u64 v[162:163], s[0:1], 0, v[54:55]
	v_cndmask_b32_e32 v242, v168, v164, vcc
	v_not_b32_e32 v164, v172
	v_or_b32_e32 v168, 0x80000000, v172
	v_cmp_gt_i32_e32 vcc, 0, v172
	flat_load_dword v172, v[162:163]
	v_lshl_add_u64 v[162:163], s[0:1], 0, v[50:51]
	v_cndmask_b32_e32 v241, v168, v164, vcc
	v_not_b32_e32 v164, v173
	v_or_b32_e32 v168, 0x80000000, v173
	v_cmp_gt_i32_e32 vcc, 0, v173
	flat_load_dword v173, v[162:163]
	v_lshl_add_u64 v[162:163], s[0:1], 0, v[48:49]
	v_cndmask_b32_e32 v240, v168, v164, vcc
	v_not_b32_e32 v164, v174
	v_or_b32_e32 v168, 0x80000000, v174
	v_cmp_gt_i32_e32 vcc, 0, v174
	flat_load_dword v174, v[162:163]
	v_lshl_add_u64 v[162:163], s[0:1], 0, v[46:47]
	v_cndmask_b32_e32 v239, v168, v164, vcc
	v_not_b32_e32 v164, v175
	v_or_b32_e32 v168, 0x80000000, v175
	v_cmp_gt_i32_e32 vcc, 0, v175
	flat_load_dword v175, v[162:163]
	v_lshl_add_u64 v[162:163], s[0:1], 0, v[44:45]
	v_cndmask_b32_e32 v238, v168, v164, vcc
	v_not_b32_e32 v164, v176
	v_or_b32_e32 v168, 0x80000000, v176
	v_cmp_gt_i32_e32 vcc, 0, v176
	flat_load_dword v176, v[162:163]
	v_lshl_add_u64 v[162:163], s[0:1], 0, v[42:43]
	v_cndmask_b32_e32 v237, v168, v164, vcc
	v_not_b32_e32 v164, v177
	v_or_b32_e32 v168, 0x80000000, v177
	v_cmp_gt_i32_e32 vcc, 0, v177
	flat_load_dword v177, v[162:163]
	v_lshl_add_u64 v[162:163], s[0:1], 0, v[40:41]
	v_cndmask_b32_e32 v236, v168, v164, vcc
	v_not_b32_e32 v164, v178
	v_or_b32_e32 v168, 0x80000000, v178
	v_cmp_gt_i32_e32 vcc, 0, v178
	flat_load_dword v178, v[162:163]
	s_add_u32 s0, s12, 0x3000
	s_addc_u32 s1, s13, 0
	v_cndmask_b32_e32 v235, v168, v164, vcc
	v_not_b32_e32 v164, v179
	v_or_b32_e32 v168, 0x80000000, v179
	v_cmp_gt_i32_e32 vcc, 0, v179
	v_lshl_add_u64 v[162:163], s[0:1], 0, v[0:1]
	s_waitcnt vmcnt(0) lgkmcnt(0)
	v_or_b32_e32 v179, 0x80000000, v165
	v_cndmask_b32_e32 v234, v168, v164, vcc
	flat_load_dword v168, v[162:163]
	v_not_b32_e32 v164, v180
	v_or_b32_e32 v162, 0x80000000, v180
	v_cmp_gt_i32_e32 vcc, 0, v180
	s_nop 1
	v_cndmask_b32_e32 v233, v162, v164, vcc
	v_not_b32_e32 v164, v165
	v_lshl_add_u64 v[162:163], s[0:1], 0, v[38:39]
	v_cmp_gt_i32_e32 vcc, 0, v165
	flat_load_dword v180, v[162:163]
	v_or_b32_e32 v165, 0x80000000, v166
	v_cndmask_b32_e32 v232, v179, v164, vcc
	v_not_b32_e32 v164, v166
	v_lshl_add_u64 v[162:163], s[0:1], 0, v[36:37]
	v_cmp_gt_i32_e32 vcc, 0, v166
	flat_load_dword v179, v[162:163]
	v_not_b32_e32 v162, v167
	v_cndmask_b32_e32 v231, v165, v164, vcc
	v_or_b32_e32 v163, 0x80000000, v167
	v_cmp_gt_i32_e32 vcc, 0, v167
	v_not_b32_e32 v164, v169
	s_nop 0
	v_cndmask_b32_e32 v230, v163, v162, vcc
	v_lshl_add_u64 v[162:163], s[0:1], 0, v[34:35]
	flat_load_dword v165, v[162:163]
	v_or_b32_e32 v162, 0x80000000, v169
	v_cmp_gt_i32_e32 vcc, 0, v169
	s_nop 1
	v_cndmask_b32_e32 v229, v162, v164, vcc
	v_lshl_add_u64 v[162:163], s[0:1], 0, v[62:63]
	v_not_b32_e32 v164, v170
	flat_load_dword v166, v[162:163]
	v_or_b32_e32 v162, 0x80000000, v170
	v_cmp_gt_i32_e32 vcc, 0, v170
	s_nop 1
	v_cndmask_b32_e32 v228, v162, v164, vcc
	v_lshl_add_u64 v[162:163], s[0:1], 0, v[60:61]
	v_not_b32_e32 v164, v171
	flat_load_dword v167, v[162:163]
	v_or_b32_e32 v162, 0x80000000, v171
	v_cmp_gt_i32_e32 vcc, 0, v171
	s_nop 1
	v_cndmask_b32_e32 v227, v162, v164, vcc
	v_lshl_add_u64 v[162:163], s[0:1], 0, v[58:59]
	v_not_b32_e32 v164, v172
	flat_load_dword v169, v[162:163]
	v_or_b32_e32 v162, 0x80000000, v172
	v_cmp_gt_i32_e32 vcc, 0, v172
	s_nop 1
	v_cndmask_b32_e32 v226, v162, v164, vcc
	v_lshl_add_u64 v[162:163], s[0:1], 0, v[56:57]
	v_not_b32_e32 v164, v173
	flat_load_dword v170, v[162:163]
	v_or_b32_e32 v162, 0x80000000, v173
	v_cmp_gt_i32_e32 vcc, 0, v173
	s_nop 1
	v_cndmask_b32_e32 v225, v162, v164, vcc
	v_lshl_add_u64 v[162:163], s[0:1], 0, v[52:53]
	v_not_b32_e32 v164, v174
	flat_load_dword v171, v[162:163]
	v_or_b32_e32 v162, 0x80000000, v174
	v_cmp_gt_i32_e32 vcc, 0, v174
	s_nop 1
	v_cndmask_b32_e32 v224, v162, v164, vcc
	v_lshl_add_u64 v[162:163], s[0:1], 0, v[54:55]
	v_not_b32_e32 v164, v175
	flat_load_dword v172, v[162:163]
	v_or_b32_e32 v162, 0x80000000, v175
	v_cmp_gt_i32_e32 vcc, 0, v175
	s_nop 1
	v_cndmask_b32_e32 v223, v162, v164, vcc
	v_lshl_add_u64 v[162:163], s[0:1], 0, v[50:51]
	flat_load_dword v173, v[162:163]
	v_not_b32_e32 v164, v176
	v_or_b32_e32 v162, 0x80000000, v176
	v_cmp_gt_i32_e32 vcc, 0, v176
	s_nop 1
	v_cndmask_b32_e32 v222, v162, v164, vcc
	v_lshl_add_u64 v[162:163], s[0:1], 0, v[48:49]
	v_not_b32_e32 v164, v177
	flat_load_dword v174, v[162:163]
	v_or_b32_e32 v162, 0x80000000, v177
	v_cmp_gt_i32_e32 vcc, 0, v177
	s_waitcnt vmcnt(0) lgkmcnt(0)
; DI unsigned f2key(float f) { const unsigned u = __float_as_uint(f); return (u & 0x80000000u) ? ~u : (u | 0x80000000u); }
; template <int NV>
; DI void topk_row(const float* row, int s, LAS int* lst, int lane) {
;     ...
;     for (int jo = 0; jo < NV / 16; ++jo) { const float* rb = row + jo * 1024;
; #pragma unroll
;         for (int ji = 0; ji < 16; ++ji) { const int j = jo * 16 + ji; const unsigned u = f2key(rb[ji * 64 + lane]); key[j] = (j * 64 + lane <= s) ? u : 0u; } }
	v_or_b32_e32 v177, 0x80000000, v168
	v_cndmask_b32_e32 v221, v162, v164, vcc
	v_lshl_add_u64 v[162:163], s[0:1], 0, v[46:47]
	v_not_b32_e32 v164, v178
	flat_load_dword v175, v[162:163]
	v_or_b32_e32 v162, 0x80000000, v178
	v_cmp_gt_i32_e32 vcc, 0, v178
	s_nop 1
	v_cndmask_b32_e32 v220, v162, v164, vcc
	v_lshl_add_u64 v[162:163], s[0:1], 0, v[44:45]
	flat_load_dword v176, v[162:163]
	v_lshl_add_u64 v[162:163], s[0:1], 0, v[42:43]
	flat_load_dword v178, v[162:163]
	v_not_b32_e32 v164, v168
	v_cmp_gt_i32_e32 vcc, 0, v168
	v_lshl_add_u64 v[162:163], s[0:1], 0, v[40:41]
	s_add_u32 s0, s12, 0x4000
	v_cndmask_b32_e32 v219, v177, v164, vcc
	flat_load_dword v177, v[162:163]
	s_addc_u32 s1, s13, 0
	v_not_b32_e32 v164, v180
	v_or_b32_e32 v168, 0x80000000, v180
	v_cmp_gt_i32_e32 vcc, 0, v180
	v_lshl_add_u64 v[162:163], s[0:1], 0, v[0:1]
	s_nop 0
	v_cndmask_b32_e32 v218, v168, v164, vcc
	v_not_b32_e32 v164, v179
	flat_load_dword v168, v[162:163]
	v_or_b32_e32 v162, 0x80000000, v179
	v_cmp_gt_i32_e32 vcc, 0, v179
	s_nop 1
	v_cndmask_b32_e32 v217, v162, v164, vcc
	v_lshl_add_u64 v[162:163], s[0:1], 0, v[38:39]
	v_not_b32_e32 v164, v165
	flat_load_dword v179, v[162:163]
	v_or_b32_e32 v162, 0x80000000, v165
	v_cmp_gt_i32_e32 vcc, 0, v165
	s_nop 1
	v_cndmask_b32_e32 v216, v162, v164, vcc
	v_lshl_add_u64 v[162:163], s[0:1], 0, v[36:37]
	v_not_b32_e32 v164, v166
	flat_load_dword v165, v[162:163]
	v_or_b32_e32 v162, 0x80000000, v166
	v_cmp_gt_i32_e32 vcc, 0, v166
	s_nop 1
	v_cndmask_b32_e32 v215, v162, v164, vcc
	v_lshl_add_u64 v[162:163], s[0:1], 0, v[34:35]
	v_not_b32_e32 v164, v167
	flat_load_dword v166, v[162:163]
	v_or_b32_e32 v162, 0x80000000, v167
	v_cmp_gt_i32_e32 vcc, 0, v167
	v_or_b32_e32 v167, 0x80000000, v169
	s_nop 0
	v_cndmask_b32_e32 v214, v162, v164, vcc
	v_lshl_add_u64 v[162:163], s[0:1], 0, v[62:63]
	flat_load_dword v180, v[162:163]
	v_not_b32_e32 v164, v169
	v_cmp_gt_i32_e32 vcc, 0, v169
	v_lshl_add_u64 v[162:163], s[0:1], 0, v[60:61]
	v_or_b32_e32 v169, 0x80000000, v171
	v_cndmask_b32_e32 v213, v167, v164, vcc
	v_not_b32_e32 v164, v170
	flat_load_dword v167, v[162:163]
	v_or_b32_e32 v162, 0x80000000, v170
	v_cmp_gt_i32_e32 vcc, 0, v170
	s_nop 1
	v_cndmask_b32_e32 v212, v162, v164, vcc
	v_lshl_add_u64 v[162:163], s[0:1], 0, v[58:59]
	flat_load_dword v170, v[162:163]
	v_lshl_add_u64 v[162:163], s[0:1], 0, v[56:57]
	v_not_b32_e32 v164, v171
	v_cmp_gt_i32_e32 vcc, 0, v171
	flat_load_dword v171, v[162:163]
	v_lshl_add_u64 v[162:163], s[0:1], 0, v[52:53]
	v_cndmask_b32_e32 v211, v169, v164, vcc
	v_not_b32_e32 v164, v172
	v_or_b32_e32 v169, 0x80000000, v172
	v_cmp_gt_i32_e32 vcc, 0, v172
	flat_load_dword v172, v[162:163]
	v_lshl_add_u64 v[162:163], s[0:1], 0, v[54:55]
	v_cndmask_b32_e32 v210, v169, v164, vcc
	v_not_b32_e32 v164, v173
	v_or_b32_e32 v169, 0x80000000, v173
	v_cmp_gt_i32_e32 vcc, 0, v173
	flat_load_dword v173, v[162:163]
	v_lshl_add_u64 v[162:163], s[0:1], 0, v[50:51]
	v_cndmask_b32_e32 v209, v169, v164, vcc
	v_not_b32_e32 v164, v174
	v_or_b32_e32 v169, 0x80000000, v174
	v_cmp_gt_i32_e32 vcc, 0, v174
	flat_load_dword v174, v[162:163]
	s_waitcnt vmcnt(0) lgkmcnt(0)
	v_not_b32_e32 v162, v176
	v_cndmask_b32_e32 v208, v169, v164, vcc
	v_not_b32_e32 v164, v175
	v_or_b32_e32 v169, 0x80000000, v175
	v_cmp_gt_i32_e32 vcc, 0, v175
	v_or_b32_e32 v163, 0x80000000, v176
	s_nop 0
	v_cndmask_b32_e32 v207, v169, v164, vcc
	v_cmp_gt_i32_e32 vcc, 0, v176
	v_not_b32_e32 v164, v178
	s_nop 0
	v_cndmask_b32_e32 v206, v163, v162, vcc
	v_lshl_add_u64 v[162:163], s[0:1], 0, v[48:49]
	flat_load_dword v169, v[162:163]
	v_or_b32_e32 v162, 0x80000000, v178
	v_cmp_gt_i32_e32 vcc, 0, v178
	s_nop 1
	v_cndmask_b32_e32 v205, v162, v164, vcc
	v_lshl_add_u64 v[162:163], s[0:1], 0, v[46:47]
	v_not_b32_e32 v164, v177
	flat_load_dword v175, v[162:163]
	v_or_b32_e32 v162, 0x80000000, v177
	v_cmp_gt_i32_e32 vcc, 0, v177
	v_or_b32_e32 v177, 0x80000000, v165
	s_nop 0
	v_cndmask_b32_e32 v204, v162, v164, vcc
	v_lshl_add_u64 v[162:163], s[0:1], 0, v[44:45]
	flat_load_dword v176, v[162:163]
	v_not_b32_e32 v164, v168
	v_or_b32_e32 v162, 0x80000000, v168
	v_cmp_gt_i32_e32 vcc, 0, v168
	s_nop 1
	v_cndmask_b32_e32 v203, v162, v164, vcc
	v_lshl_add_u64 v[162:163], s[0:1], 0, v[42:43]
	v_not_b32_e32 v164, v179
	flat_load_dword v168, v[162:163]
	v_or_b32_e32 v162, 0x80000000, v179
	v_cmp_gt_i32_e32 vcc, 0, v179
	s_nop 1
	v_cndmask_b32_e32 v202, v162, v164, vcc
	v_lshl_add_u64 v[162:163], s[0:1], 0, v[40:41]
	s_add_u32 s0, s12, 0x5000
	s_addc_u32 s1, s13, 0
	v_not_b32_e32 v164, v165
	flat_load_dword v178, v[162:163]
	v_cmp_gt_i32_e32 vcc, 0, v165
	v_lshl_add_u64 v[162:163], s[0:1], 0, v[0:1]
	flat_load_dword v165, v[162:163]
	v_cndmask_b32_e32 v201, v177, v164, vcc
	v_not_b32_e32 v164, v166
	v_or_b32_e32 v162, 0x80000000, v166
	v_cmp_gt_i32_e32 vcc, 0, v166
	v_or_b32_e32 v163, 0x80000000, v180
	v_or_b32_e32 v177, 0x80000000, v167
	v_cndmask_b32_e32 v200, v162, v164, vcc
	v_not_b32_e32 v162, v180
	v_cmp_gt_i32_e32 vcc, 0, v180
	v_not_b32_e32 v164, v167
	s_nop 0
	v_cndmask_b32_e32 v199, v163, v162, vcc
	v_lshl_add_u64 v[162:163], s[0:1], 0, v[38:39]
	flat_load_dword v166, v[162:163]
	v_lshl_add_u64 v[162:163], s[0:1], 0, v[36:37]
	flat_load_dword v179, v[162:163]
	v_cmp_gt_i32_e32 vcc, 0, v167
	v_lshl_add_u64 v[162:163], s[0:1], 0, v[34:35]
	v_or_b32_e32 v167, 0x80000000, v170
	v_cndmask_b32_e32 v198, v177, v164, vcc
	v_not_b32_e32 v164, v170
	flat_load_dword v177, v[162:163]
	v_cmp_gt_i32_e32 vcc, 0, v170
	v_lshl_add_u64 v[162:163], s[0:1], 0, v[62:63]
	flat_load_dword v170, v[162:163]
	v_cndmask_b32_e32 v197, v167, v164, vcc
	v_not_b32_e32 v164, v171
	v_or_b32_e32 v167, 0x80000000, v171
	v_cmp_gt_i32_e32 vcc, 0, v171
	v_lshl_add_u64 v[162:163], s[0:1], 0, v[60:61]
	s_nop 0
	v_cndmask_b32_e32 v196, v167, v164, vcc
	v_not_b32_e32 v164, v172
	flat_load_dword v167, v[162:163]
	v_or_b32_e32 v162, 0x80000000, v172
	v_cmp_gt_i32_e32 vcc, 0, v172
	s_nop 1
	v_cndmask_b32_e32 v195, v162, v164, vcc
	v_lshl_add_u64 v[162:163], s[0:1], 0, v[58:59]
	v_not_b32_e32 v164, v173
	flat_load_dword v171, v[162:163]
	v_or_b32_e32 v162, 0x80000000, v173
	v_cmp_gt_i32_e32 vcc, 0, v173
	v_or_b32_e32 v173, 0x80000000, v174
	s_nop 0
	v_cndmask_b32_e32 v194, v162, v164, vcc
	v_lshl_add_u64 v[162:163], s[0:1], 0, v[56:57]
	flat_load_dword v172, v[162:163]
	v_lshl_add_u64 v[162:163], s[0:1], 0, v[52:53]
	flat_load_dword v142, v[162:163]
	v_not_b32_e32 v164, v174
	v_cmp_gt_i32_e32 vcc, 0, v174
	v_lshl_add_u64 v[162:163], s[0:1], 0, v[54:55]
	flat_load_dword v174, v[162:163]
	v_cndmask_b32_e32 v193, v173, v164, vcc
	s_waitcnt vmcnt(0) lgkmcnt(0)
; DI unsigned f2key(float f) { const unsigned u = __float_as_uint(f); return (u & 0x80000000u) ? ~u : (u | 0x80000000u); }
; template <int NV>
; DI void topk_row(const float* row, int s, LAS int* lst, int lane) {
;     ...
;     for (int jo = 0; jo < NV / 16; ++jo) { const float* rb = row + jo * 1024;
; #pragma unroll
;         for (int ji = 0; ji < 16; ++ji) { const int j = jo * 16 + ji; const unsigned u = f2key(rb[ji * 64 + lane]); key[j] = (j * 64 + lane <= s) ? u : 0u; } }
	v_not_b32_e32 v164, v169
	v_or_b32_e32 v173, 0x80000000, v169
	v_cmp_gt_i32_e32 vcc, 0, v169
	v_lshl_add_u64 v[162:163], s[0:1], 0, v[50:51]
	v_or_b32_e32 v169, 0x80000000, v175
	v_cndmask_b32_e32 v192, v173, v164, vcc
	v_not_b32_e32 v164, v175
	flat_load_dword v173, v[162:163]
	v_cmp_gt_i32_e32 vcc, 0, v175
	v_lshl_add_u64 v[162:163], s[0:1], 0, v[48:49]
	s_nop 0
	v_cndmask_b32_e32 v191, v169, v164, vcc
	v_not_b32_e32 v164, v176
	flat_load_dword v169, v[162:163]
	v_or_b32_e32 v162, 0x80000000, v176
	v_cmp_gt_i32_e32 vcc, 0, v176
	v_or_b32_e32 v176, 0x80000000, v168
	s_nop 0
	v_cndmask_b32_e32 v190, v162, v164, vcc
	v_lshl_add_u64 v[162:163], s[0:1], 0, v[46:47]
	flat_load_dword v175, v[162:163]
	v_lshl_add_u64 v[162:163], s[0:1], 0, v[44:45]
	flat_load_dword v143, v[162:163]
	v_lshl_add_u64 v[162:163], s[0:1], 0, v[42:43]
	flat_load_dword v144, v[162:163]
	v_lshl_add_u64 v[162:163], s[0:1], 0, v[40:41]
	flat_load_dword v145, v[162:163]
	s_add_u32 s0, s12, 0x6000
	v_not_b32_e32 v164, v168
	v_cmp_gt_i32_e32 vcc, 0, v168
	s_addc_u32 s1, s13, 0
	v_or_b32_e32 v168, 0x80000000, v178
	v_cndmask_b32_e32 v189, v176, v164, vcc
	v_not_b32_e32 v164, v178
	v_cmp_gt_i32_e32 vcc, 0, v178
	v_lshl_add_u64 v[162:163], s[0:1], 0, v[0:1]
	flat_load_dword v146, v[162:163]
	v_cndmask_b32_e32 v187, v168, v164, vcc
	v_not_b32_e32 v164, v165
	v_or_b32_e32 v168, 0x80000000, v165
	v_cmp_gt_i32_e32 vcc, 0, v165
	v_not_b32_e32 v162, v166
	v_or_b32_e32 v163, 0x80000000, v166
	v_cndmask_b32_e32 v188, v168, v164, vcc
	v_cmp_gt_i32_e32 vcc, 0, v166
	v_not_b32_e32 v164, v179
	v_or_b32_e32 v166, 0x80000000, v177
	v_cndmask_b32_e32 v186, v163, v162, vcc
	v_lshl_add_u64 v[162:163], s[0:1], 0, v[38:39]
	flat_load_dword v165, v[162:163]
	v_or_b32_e32 v162, 0x80000000, v179
	v_cmp_gt_i32_e32 vcc, 0, v179
	s_nop 1
	v_cndmask_b32_e32 v185, v162, v164, vcc
	v_not_b32_e32 v164, v177
	v_lshl_add_u64 v[162:163], s[0:1], 0, v[36:37]
	v_cmp_gt_i32_e32 vcc, 0, v177
	flat_load_dword v168, v[162:163]
	v_not_b32_e32 v162, v170
	v_cndmask_b32_e32 v184, v166, v164, vcc
	v_or_b32_e32 v163, 0x80000000, v170
	v_cmp_gt_i32_e32 vcc, 0, v170
	v_not_b32_e32 v164, v167
	s_nop 0
	v_cndmask_b32_e32 v183, v163, v162, vcc
	v_lshl_add_u64 v[162:163], s[0:1], 0, v[34:35]
	flat_load_dword v166, v[162:163]
	v_or_b32_e32 v162, 0x80000000, v167
	v_cmp_gt_i32_e32 vcc, 0, v167
	v_or_b32_e32 v167, 0x80000000, v171
	s_nop 0
	v_cndmask_b32_e32 v182, v162, v164, vcc
	v_not_b32_e32 v164, v171
	v_lshl_add_u64 v[162:163], s[0:1], 0, v[62:63]
	v_cmp_gt_i32_e32 vcc, 0, v171
	flat_load_dword v147, v[162:163]
	v_not_b32_e32 v162, v172
	v_cndmask_b32_e32 v181, v167, v164, vcc
	v_or_b32_e32 v163, 0x80000000, v172
	v_cmp_gt_i32_e32 vcc, 0, v172
	v_not_b32_e32 v164, v142
	s_nop 0
	v_cndmask_b32_e32 v180, v163, v162, vcc
	v_lshl_add_u64 v[162:163], s[0:1], 0, v[60:61]
	flat_load_dword v167, v[162:163]
	v_or_b32_e32 v162, 0x80000000, v142
	v_cmp_gt_i32_e32 vcc, 0, v142
	v_not_b32_e32 v142, v174
	s_nop 0
	v_cndmask_b32_e32 v179, v162, v164, vcc
	v_lshl_add_u64 v[162:163], s[0:1], 0, v[58:59]
	flat_load_dword v148, v[162:163]
	v_or_b32_e32 v164, 0x80000000, v174
	v_cmp_gt_i32_e32 vcc, 0, v174
	s_waitcnt vmcnt(0) lgkmcnt(0)
	v_or_b32_e32 v162, 0x80000000, v173
	v_cndmask_b32_e32 v178, v164, v142, vcc
	v_not_b32_e32 v142, v173
	v_cmp_gt_i32_e32 vcc, 0, v173
	v_or_b32_e32 v164, 0x80000000, v169
	s_nop 0
	v_cndmask_b32_e32 v177, v162, v142, vcc
	v_not_b32_e32 v142, v169
	v_lshl_add_u64 v[162:163], s[0:1], 0, v[56:57]
	v_cmp_gt_i32_e32 vcc, 0, v169
	flat_load_dword v149, v[162:163]
	v_or_b32_e32 v162, 0x80000000, v175
	v_cndmask_b32_e32 v176, v164, v142, vcc
	v_not_b32_e32 v142, v175
	v_cmp_gt_i32_e32 vcc, 0, v175
	s_nop 1
	v_cndmask_b32_e32 v175, v162, v142, vcc
	v_lshl_add_u64 v[162:163], s[0:1], 0, v[52:53]
	v_not_b32_e32 v142, v143
	flat_load_dword v150, v[162:163]
	v_or_b32_e32 v162, 0x80000000, v143
	v_cmp_gt_i32_e32 vcc, 0, v143
	s_nop 1
	v_cndmask_b32_e32 v174, v162, v142, vcc
	v_lshl_add_u64 v[162:163], s[0:1], 0, v[54:55]
	v_not_b32_e32 v142, v144
	flat_load_dword v143, v[162:163]
	v_or_b32_e32 v162, 0x80000000, v144
	v_cmp_gt_i32_e32 vcc, 0, v144
	v_or_b32_e32 v144, 0x80000000, v145
	s_nop 0
	v_cndmask_b32_e32 v173, v162, v142, vcc
	v_not_b32_e32 v142, v145
	v_cmp_gt_i32_e32 vcc, 0, v145
	v_lshl_add_u64 v[162:163], s[0:1], 0, v[50:51]
	v_or_b32_e32 v145, 0x80000000, v146
	v_cndmask_b32_e32 v172, v144, v142, vcc
	flat_load_dword v144, v[162:163]
	v_not_b32_e32 v142, v146
	v_cmp_gt_i32_e32 vcc, 0, v146
	v_lshl_add_u64 v[162:163], s[0:1], 0, v[48:49]
	v_or_b32_e32 v146, 0x80000000, v165
	v_cndmask_b32_e32 v142, v145, v142, vcc
	flat_load_dword v145, v[162:163]
	v_cmp_lt_u32_e32 vcc, s2, v161
	s_movk_i32 s2, 0x183f
	v_lshl_add_u64 v[162:163], s[0:1], 0, v[46:47]
	v_cndmask_b32_e32 v171, 0, v142, vcc
	v_not_b32_e32 v142, v165
	v_cmp_gt_i32_e32 vcc, 0, v165
	flat_load_dword v151, v[162:163]
	v_lshl_add_u64 v[162:163], s[0:1], 0, v[44:45]
	v_cndmask_b32_e32 v142, v146, v142, vcc
	v_cmp_lt_u32_e32 vcc, s2, v161
	v_or_b32_e32 v146, 0x80000000, v168
	s_movk_i32 s2, 0x187f
	v_cndmask_b32_e32 v170, 0, v142, vcc
	v_not_b32_e32 v142, v168
	v_cmp_gt_i32_e32 vcc, 0, v168
	flat_load_dword v152, v[162:163]
	v_lshl_add_u64 v[162:163], s[0:1], 0, v[42:43]
	v_cndmask_b32_e32 v142, v146, v142, vcc
	v_cmp_lt_u32_e32 vcc, s2, v161
	v_or_b32_e32 v146, 0x80000000, v166
	s_movk_i32 s2, 0x18bf
	v_cndmask_b32_e32 v169, 0, v142, vcc
	v_not_b32_e32 v142, v166
	v_cmp_gt_i32_e32 vcc, 0, v166
	s_nop 1
	v_cndmask_b32_e32 v142, v146, v142, vcc
	v_cmp_lt_u32_e32 vcc, s2, v161
	v_or_b32_e32 v146, 0x80000000, v147
	s_movk_i32 s2, 0x18ff
	v_cndmask_b32_e32 v168, 0, v142, vcc
	v_not_b32_e32 v142, v147
	v_cmp_gt_i32_e32 vcc, 0, v147
	v_or_b32_e32 v147, 0x80000000, v167
	s_nop 0
	v_cndmask_b32_e32 v142, v146, v142, vcc
	flat_load_dword v146, v[162:163]
	v_cmp_lt_u32_e32 vcc, s2, v161
	v_lshl_add_u64 v[162:163], s[0:1], 0, v[40:41]
	s_movk_i32 s0, 0x193f
	v_cndmask_b32_e32 v166, 0, v142, vcc
	v_not_b32_e32 v142, v167
	v_cmp_gt_i32_e32 vcc, 0, v167
	s_movk_i32 s2, 0x197f
	s_nop 0
	v_cndmask_b32_e32 v142, v147, v142, vcc
	v_cmp_lt_u32_e32 vcc, s0, v161
	s_add_u32 s0, s12, 0x7000
	flat_load_dword v147, v[162:163]
	s_addc_u32 s1, s13, 0
	v_lshl_add_u64 v[38:39], s[0:1], 0, v[38:39]
	v_cndmask_b32_e32 v164, 0, v142, vcc
	v_not_b32_e32 v142, v148
	v_cmp_gt_i32_e32 vcc, 0, v148
	flat_load_dword v38, v[38:39]
	v_or_b32_e32 v162, 0x80000000, v148
	v_cndmask_b32_e32 v142, v162, v142, vcc
	v_lshl_add_u64 v[162:163], s[0:1], 0, v[0:1]
	flat_load_dword v0, v[162:163]
	v_cmp_lt_u32_e32 vcc, s2, v161
	s_waitcnt vmcnt(0) lgkmcnt(0)
; DI unsigned f2key(float f) { const unsigned u = __float_as_uint(f); return (u & 0x80000000u) ? ~u : (u | 0x80000000u); }
; template <int NV>
; DI void topk_row(const float* row, int s, LAS int* lst, int lane) {
;     ...
;     for (int jo = 0; jo < NV / 16; ++jo) { const float* rb = row + jo * 1024;
; #pragma unroll
;         for (int ji = 0; ji < 16; ++ji) { const int j = jo * 16 + ji; const unsigned u = f2key(rb[ji * 64 + lane]); key[j] = (j * 64 + lane <= s) ? u : 0u; } }
	v_or_b32_e32 v148, 0x80000000, v149
	s_movk_i32 s2, 0x19bf
	v_cndmask_b32_e32 v167, 0, v142, vcc
	v_not_b32_e32 v142, v149
	v_cmp_gt_i32_e32 vcc, 0, v149
	v_lshl_add_u64 v[36:37], s[0:1], 0, v[36:37]
	flat_load_dword v36, v[36:37]
	v_cndmask_b32_e32 v142, v148, v142, vcc
	v_cmp_lt_u32_e32 vcc, s2, v161
	v_not_b32_e32 v39, v150
	s_movk_i32 s2, 0x19ff
	v_cndmask_b32_e32 v165, 0, v142, vcc
	v_or_b32_e32 v142, 0x80000000, v150
	v_cmp_gt_i32_e32 vcc, 0, v150
	v_or_b32_e32 v37, 0x80000000, v143
	v_lshl_add_u64 v[34:35], s[0:1], 0, v[34:35]
	v_cndmask_b32_e32 v39, v142, v39, vcc
	v_cmp_lt_u32_e32 vcc, s2, v161
	s_movk_i32 s2, 0x1a3f
	v_or_b32_e32 v142, 0x80000000, v144
	v_cndmask_b32_e32 v162, 0, v39, vcc
	v_not_b32_e32 v39, v143
	v_cmp_gt_i32_e32 vcc, 0, v143
	s_nop 1
	v_cndmask_b32_e32 v37, v37, v39, vcc
	flat_load_dword v39, v[34:35]
	v_cmp_lt_u32_e32 vcc, s2, v161
	v_lshl_add_u64 v[34:35], s[0:1], 0, v[62:63]
	s_movk_i32 s2, 0x1a7f
	v_cndmask_b32_e32 v163, 0, v37, vcc
	v_not_b32_e32 v37, v144
	v_cmp_gt_i32_e32 vcc, 0, v144
	flat_load_dword v63, v[34:35]
	s_nop 0
	v_cndmask_b32_e32 v34, v142, v37, vcc
	v_cmp_lt_u32_e32 vcc, s2, v161
	v_not_b32_e32 v37, v145
	s_movk_i32 s2, 0x1abf
	v_cndmask_b32_e32 v62, 0, v34, vcc
	v_lshl_add_u64 v[34:35], s[0:1], 0, v[60:61]
	flat_load_dword v60, v[34:35]
	v_or_b32_e32 v34, 0x80000000, v145
	v_cmp_gt_i32_e32 vcc, 0, v145
	v_or_b32_e32 v61, 0x80000000, v151
	s_nop 0
	v_cndmask_b32_e32 v37, v34, v37, vcc
	v_lshl_add_u64 v[34:35], s[0:1], 0, v[58:59]
	flat_load_dword v59, v[34:35]
	v_cmp_lt_u32_e32 vcc, s2, v161
	v_lshl_add_u64 v[34:35], s[0:1], 0, v[56:57]
	s_movk_i32 s2, 0x1aff
	v_cndmask_b32_e32 v58, 0, v37, vcc
	v_not_b32_e32 v37, v151
	v_cmp_gt_i32_e32 vcc, 0, v151
	flat_load_dword v57, v[34:35]
	s_nop 0
	v_cndmask_b32_e32 v34, v61, v37, vcc
	v_cmp_lt_u32_e32 vcc, s2, v161
	v_not_b32_e32 v37, v152
	s_movk_i32 s2, 0x1b3f
	v_cndmask_b32_e32 v56, 0, v34, vcc
	v_lshl_add_u64 v[34:35], s[0:1], 0, v[52:53]
	flat_load_dword v53, v[34:35]
	v_or_b32_e32 v34, 0x80000000, v152
	v_cmp_gt_i32_e32 vcc, 0, v152
	s_nop 1
	v_cndmask_b32_e32 v37, v34, v37, vcc
	v_lshl_add_u64 v[34:35], s[0:1], 0, v[54:55]
	flat_load_dword v54, v[34:35]
	v_cmp_lt_u32_e32 vcc, s2, v161
	v_or_b32_e32 v55, 0x80000000, v146
	v_lshl_add_u64 v[34:35], s[0:1], 0, v[50:51]
	v_cndmask_b32_e32 v52, 0, v37, vcc
	v_not_b32_e32 v37, v146
	v_cmp_gt_i32_e32 vcc, 0, v146
	s_movk_i32 s2, 0x1b7f
	flat_load_dword v61, v[34:35]
	v_cndmask_b32_e32 v34, v55, v37, vcc
	v_cmp_lt_u32_e32 vcc, s2, v161
	v_not_b32_e32 v37, v147
	s_movk_i32 s2, 0x1bbf
	v_cndmask_b32_e32 v50, 0, v34, vcc
	v_lshl_add_u64 v[34:35], s[0:1], 0, v[48:49]
	flat_load_dword v55, v[34:35]
	v_or_b32_e32 v34, 0x80000000, v147
	v_cmp_gt_i32_e32 vcc, 0, v147
	s_nop 1
	v_cndmask_b32_e32 v37, v34, v37, vcc
	v_lshl_add_u64 v[34:35], s[0:1], 0, v[46:47]
	flat_load_dword v142, v[34:35]
	v_cmp_lt_u32_e32 vcc, s2, v161
	v_lshl_add_u64 v[34:35], s[0:1], 0, v[44:45]
	v_or_b32_e32 v46, 0x80000000, v0
	v_cndmask_b32_e32 v49, 0, v37, vcc
	v_not_b32_e32 v37, v0
	flat_load_dword v143, v[34:35]
	v_cmp_gt_i32_e32 vcc, 0, v0
	s_movk_i32 s2, 0x1bff
	v_lshl_add_u64 v[34:35], s[0:1], 0, v[42:43]
	v_cndmask_b32_e32 v0, v46, v37, vcc
	v_cmp_lt_u32_e32 vcc, s2, v161
	flat_load_dword v144, v[34:35]
	v_or_b32_e32 v34, 0x80000000, v38
	v_cndmask_b32_e32 v48, 0, v0, vcc
	v_not_b32_e32 v0, v38
	v_cmp_gt_i32_e32 vcc, 0, v38
	s_nop 1
	v_cndmask_b32_e32 v0, v34, v0, vcc
	v_lshl_add_u64 v[34:35], s[0:1], 0, v[40:41]
	flat_load_dword v34, v[34:35]
	s_movk_i32 s0, 0x1c3f
	v_cmp_lt_u32_e32 vcc, s0, v161
	s_waitcnt vmcnt(0) lgkmcnt(0)
	v_or_b32_e32 v35, 0x80000000, v36
	s_movk_i32 s0, 0x1c7f
	v_cndmask_b32_e32 v51, 0, v0, vcc
	v_not_b32_e32 v0, v36
	v_cmp_gt_i32_e32 vcc, 0, v36
	s_nop 1
	v_cndmask_b32_e32 v0, v35, v0, vcc
	v_cmp_lt_u32_e32 vcc, s0, v161
	v_or_b32_e32 v35, 0x80000000, v39
	s_movk_i32 s0, 0x1cbf
	v_cndmask_b32_e32 v47, 0, v0, vcc
	v_not_b32_e32 v0, v39
	v_cmp_gt_i32_e32 vcc, 0, v39
	s_nop 1
	v_cndmask_b32_e32 v0, v35, v0, vcc
	v_cmp_lt_u32_e32 vcc, s0, v161
	v_or_b32_e32 v35, 0x80000000, v63
	s_movk_i32 s0, 0x1cff
	v_cndmask_b32_e32 v46, 0, v0, vcc
	v_not_b32_e32 v0, v63
	v_cmp_gt_i32_e32 vcc, 0, v63
	s_nop 1
	v_cndmask_b32_e32 v0, v35, v0, vcc
	v_cmp_lt_u32_e32 vcc, s0, v161
	v_or_b32_e32 v35, 0x80000000, v60
	s_movk_i32 s0, 0x1d3f
	v_cndmask_b32_e32 v45, 0, v0, vcc
	v_not_b32_e32 v0, v60
	v_cmp_gt_i32_e32 vcc, 0, v60
	s_nop 1
	v_cndmask_b32_e32 v0, v35, v0, vcc
	v_cmp_lt_u32_e32 vcc, s0, v161
	v_or_b32_e32 v35, 0x80000000, v59
	s_movk_i32 s0, 0x1d7f
	v_cndmask_b32_e32 v44, 0, v0, vcc
	v_not_b32_e32 v0, v59
	v_cmp_gt_i32_e32 vcc, 0, v59
	s_nop 1
	v_cndmask_b32_e32 v0, v35, v0, vcc
	v_cmp_lt_u32_e32 vcc, s0, v161
	v_or_b32_e32 v35, 0x80000000, v57
	s_movk_i32 s0, 0x1dbf
	v_cndmask_b32_e32 v43, 0, v0, vcc
	v_not_b32_e32 v0, v57
	v_cmp_gt_i32_e32 vcc, 0, v57
	s_nop 1
	v_cndmask_b32_e32 v0, v35, v0, vcc
	v_cmp_lt_u32_e32 vcc, s0, v161
	v_or_b32_e32 v35, 0x80000000, v53
	s_movk_i32 s0, 0x1dff
	v_cndmask_b32_e32 v42, 0, v0, vcc
	v_not_b32_e32 v0, v53
	v_cmp_gt_i32_e32 vcc, 0, v53
	v_or_b32_e32 v53, 0x80000000, v34
	s_nop 0
	v_cndmask_b32_e32 v0, v35, v0, vcc
	v_cmp_lt_u32_e32 vcc, s0, v161
	v_or_b32_e32 v35, 0x80000000, v54
	s_movk_i32 s0, 0x1e3f
	v_cndmask_b32_e32 v41, 0, v0, vcc
	v_not_b32_e32 v0, v54
	v_cmp_gt_i32_e32 vcc, 0, v54
	s_nop 1
	v_cndmask_b32_e32 v0, v35, v0, vcc
	v_cmp_lt_u32_e32 vcc, s0, v161
	v_or_b32_e32 v35, 0x80000000, v61
	s_movk_i32 s0, 0x1e7f
	v_cndmask_b32_e32 v40, 0, v0, vcc
	v_not_b32_e32 v0, v61
	v_cmp_gt_i32_e32 vcc, 0, v61
	s_nop 1
	v_cndmask_b32_e32 v0, v35, v0, vcc
	v_cmp_lt_u32_e32 vcc, s0, v161
; DI unsigned f2key(float f) { const unsigned u = __float_as_uint(f); return (u & 0x80000000u) ? ~u : (u | 0x80000000u); }
; template <int NV>
; DI void topk_row(const float* row, int s, LAS int* lst, int lane) {
;     ...
;     for (int jo = 0; jo < NV / 16; ++jo) { const float* rb = row + jo * 1024;
; #pragma unroll
;         for (int ji = 0; ji < 16; ++ji) { const int j = jo * 16 + ji; const unsigned u = f2key(rb[ji * 64 + lane]); key[j] = (j * 64 + lane <= s) ? u : 0u; } }
;     unsigned T = 0u;
; #pragma unroll 1
	v_or_b32_e32 v35, 0x80000000, v55
	s_movk_i32 s0, 0x1ebf
	v_cndmask_b32_e32 v39, 0, v0, vcc
	v_not_b32_e32 v0, v55
	v_cmp_gt_i32_e32 vcc, 0, v55
	s_nop 1
	v_cndmask_b32_e32 v0, v35, v0, vcc
	v_cmp_lt_u32_e32 vcc, s0, v161
	v_or_b32_e32 v35, 0x80000000, v142
	s_movk_i32 s0, 0x1eff
	v_cndmask_b32_e32 v38, 0, v0, vcc
	v_not_b32_e32 v0, v142
	v_cmp_gt_i32_e32 vcc, 0, v142
	s_nop 1
	v_cndmask_b32_e32 v0, v35, v0, vcc
	v_cmp_lt_u32_e32 vcc, s0, v161
	v_or_b32_e32 v35, 0x80000000, v143
	s_movk_i32 s0, 0x1f3f
	v_cndmask_b32_e32 v37, 0, v0, vcc
	v_not_b32_e32 v0, v143
	v_cmp_gt_i32_e32 vcc, 0, v143
	s_nop 1
	v_cndmask_b32_e32 v0, v35, v0, vcc
	v_cmp_lt_u32_e32 vcc, s0, v161
	v_or_b32_e32 v35, 0x80000000, v144
	s_movk_i32 s0, 0x1f7f
	v_cndmask_b32_e32 v36, 0, v0, vcc
	v_not_b32_e32 v0, v144
	v_cmp_gt_i32_e32 vcc, 0, v144
	s_nop 1
	v_cndmask_b32_e32 v0, v35, v0, vcc
	v_cmp_lt_u32_e32 vcc, s0, v161
	s_movk_i32 s0, 0x1fbf
	s_nop 0
	v_cndmask_b32_e32 v35, 0, v0, vcc
	v_not_b32_e32 v0, v34
	v_cmp_gt_i32_e32 vcc, 0, v34
	v_mov_b32_e32 v34, 0
	s_nop 0
	v_cndmask_b32_e32 v0, v53, v0, vcc
	v_cmp_lt_u32_e32 vcc, s0, v161
	v_mov_b32_e32 v53, 31
	s_nop 0
	v_cndmask_b32_e32 v0, 0, v0, vcc
	v_max_u32_e32 v255, v141, v140
	v_max_u32_e32 v255, v255, v139
	v_max_u32_e32 v255, v255, v138
	v_max_u32_e32 v255, v255, v137
	v_max_u32_e32 v255, v255, v136
	v_max_u32_e32 v255, v255, v135
	v_max_u32_e32 v255, v255, v134
	v_max_u32_e32 v255, v255, v133
	v_max_u32_e32 v255, v255, v132
	v_max_u32_e32 v255, v255, v251
	v_max_u32_e32 v255, v255, v248
	v_max_u32_e32 v255, v255, v247
	v_max_u32_e32 v255, v255, v253
	v_max_u32_e32 v255, v255, v249
	v_max_u32_e32 v255, v255, v252
	v_max_u32_e32 v255, v255, v128
	v_max_u32_e32 v255, v255, v130
	v_max_u32_e32 v255, v255, v131
	v_max_u32_e32 v255, v255, v129
	v_max_u32_e32 v255, v255, v250
	v_max_u32_e32 v255, v255, v246
	v_max_u32_e32 v255, v255, v245
	v_max_u32_e32 v255, v255, v244
	v_max_u32_e32 v255, v255, v243
	v_max_u32_e32 v255, v255, v242
	v_max_u32_e32 v255, v255, v241
	v_max_u32_e32 v255, v255, v240
	v_max_u32_e32 v255, v255, v239
	v_max_u32_e32 v255, v255, v238
	v_max_u32_e32 v255, v255, v237
	v_max_u32_e32 v255, v255, v236
	v_max_u32_e32 v255, v255, v235
	v_max_u32_e32 v255, v255, v234
	v_max_u32_e32 v255, v255, v233
	v_max_u32_e32 v255, v255, v232
	v_max_u32_e32 v255, v255, v231
	v_max_u32_e32 v255, v255, v230
	v_max_u32_e32 v255, v255, v229
	v_max_u32_e32 v255, v255, v228
	v_max_u32_e32 v255, v255, v227
	v_max_u32_e32 v255, v255, v226
	v_max_u32_e32 v255, v255, v225
	v_max_u32_e32 v255, v255, v224
	v_max_u32_e32 v255, v255, v223
	v_max_u32_e32 v255, v255, v222
	v_max_u32_e32 v255, v255, v221
	v_max_u32_e32 v255, v255, v220
	v_max_u32_e32 v255, v255, v219
	v_max_u32_e32 v255, v255, v218
	v_max_u32_e32 v255, v255, v217
	v_max_u32_e32 v255, v255, v216
	v_max_u32_e32 v255, v255, v215
	v_max_u32_e32 v255, v255, v214
	v_max_u32_e32 v255, v255, v213
	v_max_u32_e32 v255, v255, v212
	v_max_u32_e32 v255, v255, v211
	v_max_u32_e32 v255, v255, v210
	v_max_u32_e32 v255, v255, v209
	v_max_u32_e32 v255, v255, v208
	v_max_u32_e32 v255, v255, v207
	v_max_u32_e32 v255, v255, v206
	v_max_u32_e32 v255, v255, v205
	v_max_u32_e32 v255, v255, v204
	v_max_u32_e32 v255, v255, v203
	v_max_u32_e32 v255, v255, v202
	v_max_u32_e32 v255, v255, v201
	v_max_u32_e32 v255, v255, v200
	v_max_u32_e32 v255, v255, v199
	v_max_u32_e32 v255, v255, v198
	v_max_u32_e32 v255, v255, v197
	v_max_u32_e32 v255, v255, v196
	v_max_u32_e32 v255, v255, v195
	v_max_u32_e32 v255, v255, v194
	v_max_u32_e32 v255, v255, v193
	v_max_u32_e32 v255, v255, v192
	v_max_u32_e32 v255, v255, v191
	v_max_u32_e32 v255, v255, v190
	v_max_u32_e32 v255, v255, v189
	v_max_u32_e32 v255, v255, v187
	v_max_u32_e32 v255, v255, v188
	v_max_u32_e32 v255, v255, v186
	v_max_u32_e32 v255, v255, v185
	v_max_u32_e32 v255, v255, v184
	v_max_u32_e32 v255, v255, v183
	v_max_u32_e32 v255, v255, v182
	v_max_u32_e32 v255, v255, v181
	v_max_u32_e32 v255, v255, v180
	v_max_u32_e32 v255, v255, v179
	v_max_u32_e32 v255, v255, v178
	v_max_u32_e32 v255, v255, v177
	v_max_u32_e32 v255, v255, v176
	v_max_u32_e32 v255, v255, v175
	v_max_u32_e32 v255, v255, v174
	v_max_u32_e32 v255, v255, v173
	v_max_u32_e32 v255, v255, v172
	v_max_u32_e32 v255, v255, v171
	v_max_u32_e32 v255, v255, v170
	v_max_u32_e32 v255, v255, v169
	v_max_u32_e32 v255, v255, v168
	v_max_u32_e32 v255, v255, v166
	v_max_u32_e32 v255, v255, v164
	v_max_u32_e32 v255, v255, v167
	v_max_u32_e32 v255, v255, v165
	v_max_u32_e32 v255, v255, v162
	v_max_u32_e32 v255, v255, v163
	v_max_u32_e32 v255, v255, v62
	v_max_u32_e32 v255, v255, v58
	v_max_u32_e32 v255, v255, v56
	v_max_u32_e32 v255, v255, v52
	v_max_u32_e32 v255, v255, v50
	v_max_u32_e32 v255, v255, v49
	v_max_u32_e32 v255, v255, v48
	v_max_u32_e32 v255, v255, v51
	v_max_u32_e32 v255, v255, v47
	v_max_u32_e32 v255, v255, v46
	v_max_u32_e32 v255, v255, v45
	v_max_u32_e32 v255, v255, v44
	v_max_u32_e32 v255, v255, v43
	v_max_u32_e32 v255, v255, v42
	v_max_u32_e32 v255, v255, v41
	v_max_u32_e32 v255, v255, v40
	v_max_u32_e32 v255, v255, v39
	v_max_u32_e32 v255, v255, v38
	v_max_u32_e32 v255, v255, v37
	v_max_u32_e32 v255, v255, v36
	v_max_u32_e32 v255, v255, v35
	v_max_u32_e32 v255, v255, v0
	s_nop 1
	v_max_u32_dpp v255, v255, v255 quad_perm:[1,0,3,2] row_mask:0xf bank_mask:0xf bound_ctrl:1
	s_nop 1
	v_max_u32_dpp v255, v255, v255 quad_perm:[2,3,0,1] row_mask:0xf bank_mask:0xf bound_ctrl:1
	s_nop 1
	v_max_u32_dpp v255, v255, v255 row_half_mirror row_mask:0xf bank_mask:0xf bound_ctrl:1
	s_nop 1
	v_max_u32_dpp v255, v255, v255 row_mirror row_mask:0xf bank_mask:0xf bound_ctrl:1
	s_nop 0
	v_readlane_b32 s99, v255, 0
	v_readlane_b32 s100, v255, 16
	s_max_u32 s99, s99, s100
	v_readlane_b32 s100, v255, 32
	s_max_u32 s99, s99, s100
	v_readlane_b32 s100, v255, 48
	s_max_u32 s99, s99, s100
; DI int wave_sum_i(int v) {
;     v += __builtin_amdgcn_update_dpp(0, v, 0xB1, 0xF, 0xF, true);
;     v += __builtin_amdgcn_update_dpp(0, v, 0x4E, 0xF, 0xF, true);
;     v += __builtin_amdgcn_update_dpp(0, v, 0x141, 0xF, 0xF, true);
;     v += __builtin_amdgcn_update_dpp(0, v, 0x140, 0xF, 0xF, true);
;     return __builtin_amdgcn_readlane(v, 0) + __builtin_amdgcn_readlane(v, 16) + __builtin_amdgcn_readlane(v, 32) + __builtin_amdgcn_readlane(v, 48);
; template <int NV>
; DI void topk_row(const float* row, int s, LAS int* lst, int lane) {
;     ...
;         const unsigned cand = T | (1u << bit); int c = 0;
; #pragma unroll
;         for (int j = 0; j < NV; ++j) asm volatile("v_cmp_le_u32 vcc, %2, %1\n\tv_addc_co_u32 %0, vcc, 0, %0, vcc" : "+v"(c) : "v"(key[j]), "s"(cand) : "vcc");
;         const int tot = wave_sum_i(c);
;         if (tot >= 256) T = cand;
;         if (tot == 256) break;
;     }
.LBB0_1969:
	v_lshlrev_b32_e64 v54, v53, 1
	v_mov_b32_e32 v55, 0
	v_or_b32_e32 v54, v54, v34
	s_nop 0
	v_readfirstlane_b32 s100, v54
	s_mov_b32 s0, 0
	s_cmp_gt_u32 s100, s99
	s_cbranch_scc1 .Lp12_skip_1969
	v_cmp_le_u32 vcc, v54, v141
	v_addc_co_u32 v55, vcc, 0, v55, vcc
	s_nop 0
	v_cmp_le_u32 vcc, v54, v140
	v_addc_co_u32 v55, vcc, 0, v55, vcc
	s_nop 0
	v_cmp_le_u32 vcc, v54, v139
	v_addc_co_u32 v55, vcc, 0, v55, vcc
	s_nop 0
	v_cmp_le_u32 vcc, v54, v138
	v_addc_co_u32 v55, vcc, 0, v55, vcc
	s_nop 0
	v_cmp_le_u32 vcc, v54, v137
	v_addc_co_u32 v55, vcc, 0, v55, vcc
	s_nop 0
	v_cmp_le_u32 vcc, v54, v136
	v_addc_co_u32 v55, vcc, 0, v55, vcc
	s_nop 0
	v_cmp_le_u32 vcc, v54, v135
	v_addc_co_u32 v55, vcc, 0, v55, vcc
	s_nop 0
	v_cmp_le_u32 vcc, v54, v134
	v_addc_co_u32 v55, vcc, 0, v55, vcc
	s_nop 0
	v_cmp_le_u32 vcc, v54, v133
	v_addc_co_u32 v55, vcc, 0, v55, vcc
	s_nop 0
	v_cmp_le_u32 vcc, v54, v132
	v_addc_co_u32 v55, vcc, 0, v55, vcc
	s_nop 0
	v_cmp_le_u32 vcc, v54, v251
	v_addc_co_u32 v55, vcc, 0, v55, vcc
	s_nop 0
	v_cmp_le_u32 vcc, v54, v248
	v_addc_co_u32 v55, vcc, 0, v55, vcc
	s_nop 0
	v_cmp_le_u32 vcc, v54, v247
	v_addc_co_u32 v55, vcc, 0, v55, vcc
	s_nop 0
	v_cmp_le_u32 vcc, v54, v253
	v_addc_co_u32 v55, vcc, 0, v55, vcc
	s_nop 0
	v_cmp_le_u32 vcc, v54, v249
	v_addc_co_u32 v55, vcc, 0, v55, vcc
	s_nop 0
	v_cmp_le_u32 vcc, v54, v252
	v_addc_co_u32 v55, vcc, 0, v55, vcc
	s_nop 0
	v_cmp_le_u32 vcc, v54, v128
	v_addc_co_u32 v55, vcc, 0, v55, vcc
	s_nop 0
	v_cmp_le_u32 vcc, v54, v130
	v_addc_co_u32 v55, vcc, 0, v55, vcc
	s_nop 0
	v_cmp_le_u32 vcc, v54, v131
	v_addc_co_u32 v55, vcc, 0, v55, vcc
	s_nop 0
	v_cmp_le_u32 vcc, v54, v129
	v_addc_co_u32 v55, vcc, 0, v55, vcc
	s_nop 0
	v_cmp_le_u32 vcc, v54, v250
	v_addc_co_u32 v55, vcc, 0, v55, vcc
	s_nop 0
	v_cmp_le_u32 vcc, v54, v246
	v_addc_co_u32 v55, vcc, 0, v55, vcc
	s_nop 0
	v_cmp_le_u32 vcc, v54, v245
	v_addc_co_u32 v55, vcc, 0, v55, vcc
	s_nop 0
	v_cmp_le_u32 vcc, v54, v244
	v_addc_co_u32 v55, vcc, 0, v55, vcc
	s_nop 0
	v_cmp_le_u32 vcc, v54, v243
	v_addc_co_u32 v55, vcc, 0, v55, vcc
	s_nop 0
	v_cmp_le_u32 vcc, v54, v242
	v_addc_co_u32 v55, vcc, 0, v55, vcc
	s_nop 0
	v_cmp_le_u32 vcc, v54, v241
	v_addc_co_u32 v55, vcc, 0, v55, vcc
	s_nop 0
	v_cmp_le_u32 vcc, v54, v240
	v_addc_co_u32 v55, vcc, 0, v55, vcc
	s_nop 0
	v_cmp_le_u32 vcc, v54, v239
	v_addc_co_u32 v55, vcc, 0, v55, vcc
	s_nop 0
	v_cmp_le_u32 vcc, v54, v238
	v_addc_co_u32 v55, vcc, 0, v55, vcc
	s_nop 0
	v_cmp_le_u32 vcc, v54, v237
	v_addc_co_u32 v55, vcc, 0, v55, vcc
	s_nop 0
	v_cmp_le_u32 vcc, v54, v236
	v_addc_co_u32 v55, vcc, 0, v55, vcc
	s_nop 0
	v_cmp_le_u32 vcc, v54, v235
	v_addc_co_u32 v55, vcc, 0, v55, vcc
	s_nop 0
	v_cmp_le_u32 vcc, v54, v234
	v_addc_co_u32 v55, vcc, 0, v55, vcc
	s_nop 0
	v_cmp_le_u32 vcc, v54, v233
	v_addc_co_u32 v55, vcc, 0, v55, vcc
	s_nop 0
	v_cmp_le_u32 vcc, v54, v232
	v_addc_co_u32 v55, vcc, 0, v55, vcc
	s_nop 0
	v_cmp_le_u32 vcc, v54, v231
	v_addc_co_u32 v55, vcc, 0, v55, vcc
	s_nop 0
	v_cmp_le_u32 vcc, v54, v230
	v_addc_co_u32 v55, vcc, 0, v55, vcc
	s_nop 0
	v_cmp_le_u32 vcc, v54, v229
	v_addc_co_u32 v55, vcc, 0, v55, vcc
	s_nop 0
	v_cmp_le_u32 vcc, v54, v228
	v_addc_co_u32 v55, vcc, 0, v55, vcc
	s_nop 0
	v_cmp_le_u32 vcc, v54, v227
	v_addc_co_u32 v55, vcc, 0, v55, vcc
	s_nop 0
	v_cmp_le_u32 vcc, v54, v226
	v_addc_co_u32 v55, vcc, 0, v55, vcc
	s_nop 0
	v_cmp_le_u32 vcc, v54, v225
	v_addc_co_u32 v55, vcc, 0, v55, vcc
	s_nop 0
	v_cmp_le_u32 vcc, v54, v224
	v_addc_co_u32 v55, vcc, 0, v55, vcc
	s_nop 0
	v_cmp_le_u32 vcc, v54, v223
	v_addc_co_u32 v55, vcc, 0, v55, vcc
	s_nop 0
	v_cmp_le_u32 vcc, v54, v222
	v_addc_co_u32 v55, vcc, 0, v55, vcc
	s_nop 0
	v_cmp_le_u32 vcc, v54, v221
	v_addc_co_u32 v55, vcc, 0, v55, vcc
	s_nop 0
	v_cmp_le_u32 vcc, v54, v220
	v_addc_co_u32 v55, vcc, 0, v55, vcc
	s_nop 0
	v_cmp_le_u32 vcc, v54, v219
	v_addc_co_u32 v55, vcc, 0, v55, vcc
	s_nop 0
	v_cmp_le_u32 vcc, v54, v218
	v_addc_co_u32 v55, vcc, 0, v55, vcc
	s_nop 0
	v_cmp_le_u32 vcc, v54, v217
	v_addc_co_u32 v55, vcc, 0, v55, vcc
	s_nop 0
	v_cmp_le_u32 vcc, v54, v216
	v_addc_co_u32 v55, vcc, 0, v55, vcc
	s_nop 0
	v_cmp_le_u32 vcc, v54, v215
	v_addc_co_u32 v55, vcc, 0, v55, vcc
	s_nop 0
	v_cmp_le_u32 vcc, v54, v214
	v_addc_co_u32 v55, vcc, 0, v55, vcc
	s_nop 0
	v_cmp_le_u32 vcc, v54, v213
	v_addc_co_u32 v55, vcc, 0, v55, vcc
	s_nop 0
	v_cmp_le_u32 vcc, v54, v212
	v_addc_co_u32 v55, vcc, 0, v55, vcc
	s_nop 0
	v_cmp_le_u32 vcc, v54, v211
	v_addc_co_u32 v55, vcc, 0, v55, vcc
	s_nop 0
	v_cmp_le_u32 vcc, v54, v210
	v_addc_co_u32 v55, vcc, 0, v55, vcc
	s_nop 0
	v_cmp_le_u32 vcc, v54, v209
	v_addc_co_u32 v55, vcc, 0, v55, vcc
	s_nop 0
	v_cmp_le_u32 vcc, v54, v208
	v_addc_co_u32 v55, vcc, 0, v55, vcc
	s_nop 0
	v_cmp_le_u32 vcc, v54, v207
	v_addc_co_u32 v55, vcc, 0, v55, vcc
	s_nop 0
	v_cmp_le_u32 vcc, v54, v206
	v_addc_co_u32 v55, vcc, 0, v55, vcc
	s_nop 0
	v_cmp_le_u32 vcc, v54, v205
	v_addc_co_u32 v55, vcc, 0, v55, vcc
	s_nop 0
	v_cmp_le_u32 vcc, v54, v204
	v_addc_co_u32 v55, vcc, 0, v55, vcc
	s_nop 0
	v_cmp_le_u32 vcc, v54, v203
	v_addc_co_u32 v55, vcc, 0, v55, vcc
	s_nop 0
	v_cmp_le_u32 vcc, v54, v202
	v_addc_co_u32 v55, vcc, 0, v55, vcc
	s_nop 0
	v_cmp_le_u32 vcc, v54, v201
	v_addc_co_u32 v55, vcc, 0, v55, vcc
	s_nop 0
	v_cmp_le_u32 vcc, v54, v200
	v_addc_co_u32 v55, vcc, 0, v55, vcc
	s_nop 0
	v_cmp_le_u32 vcc, v54, v199
	v_addc_co_u32 v55, vcc, 0, v55, vcc
	s_nop 0
	v_cmp_le_u32 vcc, v54, v198
	v_addc_co_u32 v55, vcc, 0, v55, vcc
	s_nop 0
	v_cmp_le_u32 vcc, v54, v197
	v_addc_co_u32 v55, vcc, 0, v55, vcc
	s_nop 0
	v_cmp_le_u32 vcc, v54, v196
; DI int wave_sum_i(int v) {
;     v += __builtin_amdgcn_update_dpp(0, v, 0xB1, 0xF, 0xF, true);
;     v += __builtin_amdgcn_update_dpp(0, v, 0x4E, 0xF, 0xF, true);
;     v += __builtin_amdgcn_update_dpp(0, v, 0x141, 0xF, 0xF, true);
;     v += __builtin_amdgcn_update_dpp(0, v, 0x140, 0xF, 0xF, true);
;     return __builtin_amdgcn_readlane(v, 0) + __builtin_amdgcn_readlane(v, 16) + __builtin_amdgcn_readlane(v, 32) + __builtin_amdgcn_readlane(v, 48);
; template <int NV>
; DI void topk_row(const float* row, int s, LAS int* lst, int lane) {
;     ...
;         const unsigned cand = T | (1u << bit); int c = 0;
; #pragma unroll
;         for (int j = 0; j < NV; ++j) asm volatile("v_cmp_le_u32 vcc, %2, %1\n\tv_addc_co_u32 %0, vcc, 0, %0, vcc" : "+v"(c) : "v"(key[j]), "s"(cand) : "vcc");
;         const int tot = wave_sum_i(c);
;         if (tot >= 256) T = cand;
;         if (tot == 256) break;
;     }
	v_addc_co_u32 v55, vcc, 0, v55, vcc
	s_nop 0
	v_cmp_le_u32 vcc, v54, v195
	v_addc_co_u32 v55, vcc, 0, v55, vcc
	s_nop 0
	v_cmp_le_u32 vcc, v54, v194
	v_addc_co_u32 v55, vcc, 0, v55, vcc
	s_nop 0
	v_cmp_le_u32 vcc, v54, v193
	v_addc_co_u32 v55, vcc, 0, v55, vcc
	s_nop 0
	v_cmp_le_u32 vcc, v54, v192
	v_addc_co_u32 v55, vcc, 0, v55, vcc
	s_nop 0
	v_cmp_le_u32 vcc, v54, v191
	v_addc_co_u32 v55, vcc, 0, v55, vcc
	s_nop 0
	v_cmp_le_u32 vcc, v54, v190
	v_addc_co_u32 v55, vcc, 0, v55, vcc
	s_nop 0
	v_cmp_le_u32 vcc, v54, v189
	v_addc_co_u32 v55, vcc, 0, v55, vcc
	s_nop 0
	v_cmp_le_u32 vcc, v54, v187
	v_addc_co_u32 v55, vcc, 0, v55, vcc
	s_nop 0
	v_cmp_le_u32 vcc, v54, v188
	v_addc_co_u32 v55, vcc, 0, v55, vcc
	s_nop 0
	v_cmp_le_u32 vcc, v54, v186
	v_addc_co_u32 v55, vcc, 0, v55, vcc
	s_nop 0
	v_cmp_le_u32 vcc, v54, v185
	v_addc_co_u32 v55, vcc, 0, v55, vcc
	s_nop 0
	v_cmp_le_u32 vcc, v54, v184
	v_addc_co_u32 v55, vcc, 0, v55, vcc
	s_nop 0
	v_cmp_le_u32 vcc, v54, v183
	v_addc_co_u32 v55, vcc, 0, v55, vcc
	s_nop 0
	v_cmp_le_u32 vcc, v54, v182
	v_addc_co_u32 v55, vcc, 0, v55, vcc
	s_nop 0
	v_cmp_le_u32 vcc, v54, v181
	v_addc_co_u32 v55, vcc, 0, v55, vcc
	s_nop 0
	v_cmp_le_u32 vcc, v54, v180
	v_addc_co_u32 v55, vcc, 0, v55, vcc
	s_nop 0
	v_cmp_le_u32 vcc, v54, v179
	v_addc_co_u32 v55, vcc, 0, v55, vcc
	s_nop 0
	v_cmp_le_u32 vcc, v54, v178
	v_addc_co_u32 v55, vcc, 0, v55, vcc
	s_nop 0
	v_cmp_le_u32 vcc, v54, v177
	v_addc_co_u32 v55, vcc, 0, v55, vcc
	s_nop 0
	v_cmp_le_u32 vcc, v54, v176
	v_addc_co_u32 v55, vcc, 0, v55, vcc
	s_nop 0
	v_cmp_le_u32 vcc, v54, v175
	v_addc_co_u32 v55, vcc, 0, v55, vcc
	s_nop 0
	v_cmp_le_u32 vcc, v54, v174
	v_addc_co_u32 v55, vcc, 0, v55, vcc
	s_nop 0
	v_cmp_le_u32 vcc, v54, v173
	v_addc_co_u32 v55, vcc, 0, v55, vcc
	s_nop 0
	v_cmp_le_u32 vcc, v54, v172
	v_addc_co_u32 v55, vcc, 0, v55, vcc
	s_nop 0
	v_cmp_le_u32 vcc, v54, v171
	v_addc_co_u32 v55, vcc, 0, v55, vcc
	s_nop 0
	v_cmp_le_u32 vcc, v54, v170
	v_addc_co_u32 v55, vcc, 0, v55, vcc
	s_nop 0
	v_cmp_le_u32 vcc, v54, v169
	v_addc_co_u32 v55, vcc, 0, v55, vcc
	s_nop 0
	v_cmp_le_u32 vcc, v54, v168
	v_addc_co_u32 v55, vcc, 0, v55, vcc
	s_nop 0
	v_cmp_le_u32 vcc, v54, v166
	v_addc_co_u32 v55, vcc, 0, v55, vcc
	s_nop 0
	v_cmp_le_u32 vcc, v54, v164
	v_addc_co_u32 v55, vcc, 0, v55, vcc
	s_nop 0
	v_cmp_le_u32 vcc, v54, v167
	v_addc_co_u32 v55, vcc, 0, v55, vcc
	s_nop 0
	v_cmp_le_u32 vcc, v54, v165
	v_addc_co_u32 v55, vcc, 0, v55, vcc
	s_nop 0
	v_cmp_le_u32 vcc, v54, v162
	v_addc_co_u32 v55, vcc, 0, v55, vcc
	s_nop 0
	v_cmp_le_u32 vcc, v54, v163
	v_addc_co_u32 v55, vcc, 0, v55, vcc
	s_nop 0
	v_cmp_le_u32 vcc, v54, v62
	v_addc_co_u32 v55, vcc, 0, v55, vcc
	s_nop 0
	v_cmp_le_u32 vcc, v54, v58
	v_addc_co_u32 v55, vcc, 0, v55, vcc
	s_nop 0
	v_cmp_le_u32 vcc, v54, v56
	v_addc_co_u32 v55, vcc, 0, v55, vcc
	s_nop 0
	v_cmp_le_u32 vcc, v54, v52
	v_addc_co_u32 v55, vcc, 0, v55, vcc
	s_nop 0
	v_cmp_le_u32 vcc, v54, v50
	v_addc_co_u32 v55, vcc, 0, v55, vcc
	s_nop 0
	v_cmp_le_u32 vcc, v54, v49
	v_addc_co_u32 v55, vcc, 0, v55, vcc
	s_nop 0
	v_cmp_le_u32 vcc, v54, v48
	v_addc_co_u32 v55, vcc, 0, v55, vcc
	s_nop 0
	v_cmp_le_u32 vcc, v54, v51
	v_addc_co_u32 v55, vcc, 0, v55, vcc
	s_nop 0
	v_cmp_le_u32 vcc, v54, v47
	v_addc_co_u32 v55, vcc, 0, v55, vcc
	s_nop 0
	v_cmp_le_u32 vcc, v54, v46
	v_addc_co_u32 v55, vcc, 0, v55, vcc
	s_nop 0
	v_cmp_le_u32 vcc, v54, v45
	v_addc_co_u32 v55, vcc, 0, v55, vcc
	s_nop 0
	v_cmp_le_u32 vcc, v54, v44
	v_addc_co_u32 v55, vcc, 0, v55, vcc
	s_nop 0
	v_cmp_le_u32 vcc, v54, v43
	v_addc_co_u32 v55, vcc, 0, v55, vcc
	s_nop 0
	v_cmp_le_u32 vcc, v54, v42
	v_addc_co_u32 v55, vcc, 0, v55, vcc
	s_nop 0
	v_cmp_le_u32 vcc, v54, v41
	v_addc_co_u32 v55, vcc, 0, v55, vcc
	s_nop 0
	v_cmp_le_u32 vcc, v54, v40
	v_addc_co_u32 v55, vcc, 0, v55, vcc
	s_nop 0
	v_cmp_le_u32 vcc, v54, v39
	v_addc_co_u32 v55, vcc, 0, v55, vcc
	s_nop 0
	v_cmp_le_u32 vcc, v54, v38
	v_addc_co_u32 v55, vcc, 0, v55, vcc
	s_nop 0
	v_cmp_le_u32 vcc, v54, v37
	v_addc_co_u32 v55, vcc, 0, v55, vcc
	s_nop 0
	v_cmp_le_u32 vcc, v54, v36
	v_addc_co_u32 v55, vcc, 0, v55, vcc
	s_nop 0
	v_cmp_le_u32 vcc, v54, v35
	v_addc_co_u32 v55, vcc, 0, v55, vcc
	s_nop 0
	v_cmp_le_u32 vcc, v54, v0
	v_addc_co_u32 v55, vcc, 0, v55, vcc
	s_nop 1
	v_add_u32_dpp v55, v55, v55 quad_perm:[1,0,3,2] row_mask:0xf bank_mask:0xf bound_ctrl:1
	s_nop 1
	v_add_u32_dpp v55, v55, v55 quad_perm:[2,3,0,1] row_mask:0xf bank_mask:0xf bound_ctrl:1
	s_nop 1
	v_add_u32_dpp v55, v55, v55 row_half_mirror row_mask:0xf bank_mask:0xf bound_ctrl:1
	s_nop 1
	v_add_u32_dpp v55, v55, v55 row_mirror row_mask:0xf bank_mask:0xf bound_ctrl:1
	s_nop 0
	v_readlane_b32 s0, v55, 0
	v_readlane_b32 s1, v55, 16
	s_add_i32 s0, s1, s0
	v_readlane_b32 s1, v55, 32
	s_add_i32 s0, s0, s1
	v_readlane_b32 s1, v55, 48
	s_add_i32 s0, s0, s1
.Lp12_skip_1969:
	s_cmpk_gt_i32 s0, 0xff
	s_cselect_b64 vcc, -1, 0
	s_cmpk_eq_i32 s0, 0x100
	v_cndmask_b32_e32 v34, v34, v54, vcc
	s_cselect_b64 s[0:1], -1, 0
	v_subrev_co_u32_e32 v53, vcc, 1, v53
	s_or_b64 s[0:1], s[0:1], vcc
	s_andn2_b64 vcc, exec, s[0:1]
	s_cbranch_vccnz .LBB0_1969
	v_cmp_gt_u32_e32 vcc, v141, v34
	s_and_saveexec_b64 s[0:1], vcc
	s_nop 0
	v_mbcnt_lo_u32_b32 v53, vcc_lo, 0
	v_mbcnt_hi_u32_b32 v53, vcc_hi, v53
	v_lshl_add_u32 v53, v53, 2, s20
	ds_write_b32 v53, v2
	s_or_b64 exec, exec, s[0:1]
	s_bcnt1_i32_b64 s2, vcc
	v_cmp_gt_u32_e32 vcc, v140, v34
	s_and_saveexec_b64 s[0:1], vcc
	s_cbranch_execz .LBB0_1974
	s_lshl_b32 s3, s2, 2
	v_mbcnt_lo_u32_b32 v53, vcc_lo, 0
	s_add_i32 s3, s20, s3
	v_mbcnt_hi_u32_b32 v53, vcc_hi, v53
	v_lshl_add_u32 v53, v53, 2, s3
	ds_write_b32 v53, v4

; DI unsigned f2key(float f) { const unsigned u = __float_as_uint(f); return (u & 0x80000000u) ? ~u : (u | 0x80000000u); }
; template <int NV>
; DI void topk_row(const float* row, int s, LAS int* lst, int lane) {
;     ...
;     for (int jo = 0; jo < NV / 16; ++jo) { const float* rb = row + jo * 1024;
; #pragma unroll
;         for (int ji = 0; ji < 16; ++ji) { const int j = jo * 16 + ji; const unsigned u = f2key(rb[ji * 64 + lane]); key[j] = (j * 64 + lane <= s) ? u : 0u; } }
; DI void topk_phase(const float* SC, unsigned short* IDX, LAS unsigned char* lds, int tid, int bid, int G) {
;     ...
;             else if (s < 4096) topk_row<64>(row, s, lst, lane);
;             else if (s < 6144) topk_row<96>(row, s, lst, lane);
;             else topk_row<128>(row, s, lst, lane);
.LBB0_2483:
	s_mov_b64 s[0:1], 0
	v_mov_b32_e32 v34, v159
	s_cbranch_execz .LBB0_2869
	v_lshlrev_b32_e32 v0, 2, v2
	v_lshl_add_u64 v[40:41], s[12:13], 0, v[0:1]
	flat_load_dword v48, v[40:41]
	flat_load_dword v49, v[40:41] offset:256
	flat_load_dword v50, v[40:41] offset:512
	flat_load_dword v51, v[40:41] offset:768
	flat_load_dword v52, v[40:41] offset:1024
	flat_load_dword v53, v[40:41] offset:1280
	flat_load_dword v54, v[40:41] offset:1536
	flat_load_dword v55, v[40:41] offset:1792
	flat_load_dword v56, v[40:41] offset:2048
	flat_load_dword v57, v[40:41] offset:2304
	flat_load_dword v58, v[40:41] offset:2560
	flat_load_dword v59, v[40:41] offset:2816
	flat_load_dword v60, v[40:41] offset:3072
	flat_load_dword v128, v[40:41] offset:3328
	s_add_u32 s0, s12, 0x1000
	s_addc_u32 s1, s13, 0
	v_lshlrev_b32_e32 v38, 2, v4
	v_mov_b32_e32 v39, v1
	v_lshlrev_b32_e32 v36, 2, v6
	v_mov_b32_e32 v37, v1
	v_lshlrev_b32_e32 v34, 2, v8
	flat_load_dword v129, v[40:41] offset:3584
	flat_load_dword v130, v[40:41] offset:3840
	v_mov_b32_e32 v35, v1
	v_lshl_add_u64 v[40:41], s[0:1], 0, v[0:1]
	v_lshl_add_u64 v[42:43], s[0:1], 0, v[38:39]
	v_lshl_add_u64 v[44:45], s[0:1], 0, v[36:37]
	v_lshl_add_u64 v[46:47], s[0:1], 0, v[34:35]
	flat_load_dword v131, v[40:41]
	flat_load_dword v132, v[42:43]
	flat_load_dword v133, v[44:45]
	flat_load_dword v134, v[46:47]
	s_movk_i32 s2, 0xfff
	s_waitcnt vmcnt(0) lgkmcnt(0)
	v_not_b32_e32 v40, v48
	v_or_b32_e32 v41, 0x80000000, v48
	v_cmp_gt_i32_e32 vcc, 0, v48
	v_not_b32_e32 v42, v49
	v_or_b32_e32 v43, 0x80000000, v49
	v_cndmask_b32_e32 v221, v41, v40, vcc
	v_cmp_gt_i32_e32 vcc, 0, v49
	v_not_b32_e32 v44, v50
	v_or_b32_e32 v45, 0x80000000, v50
	v_cndmask_b32_e32 v220, v43, v42, vcc
	v_cmp_gt_i32_e32 vcc, 0, v50
	v_not_b32_e32 v46, v51
	v_or_b32_e32 v47, 0x80000000, v51
	v_cndmask_b32_e32 v219, v45, v44, vcc
	v_cmp_gt_i32_e32 vcc, 0, v51
	v_not_b32_e32 v61, v52
	v_or_b32_e32 v62, 0x80000000, v52
	v_cndmask_b32_e32 v218, v47, v46, vcc
	v_cmp_gt_i32_e32 vcc, 0, v52
	v_not_b32_e32 v63, v53
	v_or_b32_e32 v135, 0x80000000, v53
	v_cndmask_b32_e32 v217, v62, v61, vcc
	v_cmp_gt_i32_e32 vcc, 0, v53
	v_not_b32_e32 v136, v54
	v_or_b32_e32 v137, 0x80000000, v54
	v_cndmask_b32_e32 v216, v135, v63, vcc
	v_cmp_gt_i32_e32 vcc, 0, v54
	v_not_b32_e32 v138, v55
	v_or_b32_e32 v139, 0x80000000, v55
	v_cndmask_b32_e32 v215, v137, v136, vcc
	v_cmp_gt_i32_e32 vcc, 0, v55
	v_not_b32_e32 v140, v56
	v_or_b32_e32 v141, 0x80000000, v56
	v_cndmask_b32_e32 v214, v139, v138, vcc
	v_cmp_gt_i32_e32 vcc, 0, v56
	v_not_b32_e32 v162, v57
	v_or_b32_e32 v163, 0x80000000, v57
	v_cndmask_b32_e32 v213, v141, v140, vcc
	v_cmp_gt_i32_e32 vcc, 0, v57
	v_not_b32_e32 v164, v58
	v_or_b32_e32 v165, 0x80000000, v58
	v_cndmask_b32_e32 v211, v163, v162, vcc
	v_cmp_gt_i32_e32 vcc, 0, v58
	v_lshlrev_b32_e32 v62, 2, v10
	v_mov_b32_e32 v63, v1
	v_not_b32_e32 v166, v59
	v_or_b32_e32 v167, 0x80000000, v59
	v_cndmask_b32_e32 v206, v165, v164, vcc
	v_cmp_gt_i32_e32 vcc, 0, v59
	v_lshl_add_u64 v[40:41], s[0:1], 0, v[62:63]
	v_not_b32_e32 v168, v60
	v_or_b32_e32 v169, 0x80000000, v60
	v_cndmask_b32_e32 v203, v167, v166, vcc
	flat_load_dword v135, v[40:41]
	v_cmp_gt_i32_e32 vcc, 0, v60
	v_lshlrev_b32_e32 v60, 2, v12
	v_mov_b32_e32 v61, v1
	v_lshl_add_u64 v[40:41], s[0:1], 0, v[60:61]
	flat_load_dword v136, v[40:41]
	v_lshlrev_b32_e32 v58, 2, v14
	v_mov_b32_e32 v59, v1
	v_lshl_add_u64 v[40:41], s[0:1], 0, v[58:59]
	v_lshlrev_b32_e32 v56, 2, v16
	v_mov_b32_e32 v57, v1
	flat_load_dword v137, v[40:41]
	v_lshl_add_u64 v[40:41], s[0:1], 0, v[56:57]
	flat_load_dword v138, v[40:41]
	v_lshlrev_b32_e32 v54, 2, v18
	v_mov_b32_e32 v55, v1
	v_lshl_add_u64 v[40:41], s[0:1], 0, v[54:55]
	v_lshlrev_b32_e32 v52, 2, v20
	v_mov_b32_e32 v53, v1
	flat_load_dword v139, v[40:41]
	v_lshl_add_u64 v[40:41], s[0:1], 0, v[52:53]
	flat_load_dword v140, v[40:41]
	v_lshlrev_b32_e32 v50, 2, v22
	v_mov_b32_e32 v51, v1
	v_lshl_add_u64 v[40:41], s[0:1], 0, v[50:51]
	flat_load_dword v141, v[40:41]
	v_cndmask_b32_e32 v200, v169, v168, vcc
	v_not_b32_e32 v42, v128
	v_or_b32_e32 v43, 0x80000000, v128
	v_cmp_gt_i32_e32 vcc, 0, v128
	v_lshlrev_b32_e32 v48, 2, v24
	v_mov_b32_e32 v49, v1
	v_cndmask_b32_e32 v202, v43, v42, vcc
	v_not_b32_e32 v42, v129
	v_or_b32_e32 v43, 0x80000000, v129
	v_cmp_gt_i32_e32 vcc, 0, v129
	v_lshl_add_u64 v[40:41], s[0:1], 0, v[48:49]
	v_lshlrev_b32_e32 v46, 2, v26
	v_mov_b32_e32 v47, v1
	v_cndmask_b32_e32 v204, v43, v42, vcc
	v_not_b32_e32 v42, v130
	v_or_b32_e32 v43, 0x80000000, v130
	v_cmp_gt_i32_e32 vcc, 0, v130
	flat_load_dword v130, v[40:41]
	v_lshl_add_u64 v[40:41], s[0:1], 0, v[46:47]
	v_lshlrev_b32_e32 v44, 2, v28
	v_mov_b32_e32 v45, v1
	v_cndmask_b32_e32 v207, v43, v42, vcc
	v_not_b32_e32 v42, v131
	v_or_b32_e32 v43, 0x80000000, v131
	flat_load_dword v162, v[40:41]
	v_cmp_gt_i32_e32 vcc, 0, v131
	v_lshl_add_u64 v[40:41], s[0:1], 0, v[44:45]
	flat_load_dword v163, v[40:41]
	v_cndmask_b32_e32 v208, v43, v42, vcc
	v_lshlrev_b32_e32 v42, 2, v30
	v_mov_b32_e32 v43, v1
	v_lshl_add_u64 v[40:41], s[0:1], 0, v[42:43]
	flat_load_dword v164, v[40:41]
	v_lshlrev_b32_e32 v40, 2, v32
	v_mov_b32_e32 v41, v1
	v_lshl_add_u64 v[128:129], s[0:1], 0, v[40:41]
	s_add_u32 s0, s12, 0x2000
	flat_load_dword v166, v[128:129]
	s_addc_u32 s1, s13, 0
	v_not_b32_e32 v131, v132
	v_or_b32_e32 v165, 0x80000000, v132
	v_cmp_gt_i32_e32 vcc, 0, v132
	v_lshl_add_u64 v[128:129], s[0:1], 0, v[0:1]
	flat_load_dword v132, v[128:129]
	v_cndmask_b32_e32 v212, v165, v131, vcc
	v_not_b32_e32 v131, v133
	v_or_b32_e32 v128, 0x80000000, v133
	v_cmp_gt_i32_e32 vcc, 0, v133
	s_nop 1
	v_cndmask_b32_e32 v210, v128, v131, vcc
	v_lshl_add_u64 v[128:129], s[0:1], 0, v[38:39]
	v_not_b32_e32 v131, v134
	flat_load_dword v133, v[128:129]
	v_or_b32_e32 v128, 0x80000000, v134
	v_cmp_gt_i32_e32 vcc, 0, v134
	s_nop 1
	v_cndmask_b32_e32 v209, v128, v131, vcc
	v_lshl_add_u64 v[128:129], s[0:1], 0, v[36:37]
	s_waitcnt vmcnt(0) lgkmcnt(0)
; DI unsigned f2key(float f) { const unsigned u = __float_as_uint(f); return (u & 0x80000000u) ? ~u : (u | 0x80000000u); }
; template <int NV>
; DI void topk_row(const float* row, int s, LAS int* lst, int lane) {
;     ...
;     for (int jo = 0; jo < NV / 16; ++jo) { const float* rb = row + jo * 1024;
; #pragma unroll
;         for (int ji = 0; ji < 16; ++ji) { const int j = jo * 16 + ji; const unsigned u = f2key(rb[ji * 64 + lane]); key[j] = (j * 64 + lane <= s) ? u : 0u; } }
	v_not_b32_e32 v131, v135
	flat_load_dword v134, v[128:129]
	v_or_b32_e32 v128, 0x80000000, v135
	v_cmp_gt_i32_e32 vcc, 0, v135
	s_nop 1
	v_cndmask_b32_e32 v205, v128, v131, vcc
	v_lshl_add_u64 v[128:129], s[0:1], 0, v[34:35]
	v_not_b32_e32 v131, v136
	flat_load_dword v135, v[128:129]
	v_or_b32_e32 v128, 0x80000000, v136
	v_cmp_gt_i32_e32 vcc, 0, v136
	v_or_b32_e32 v136, 0x80000000, v137
	s_nop 0
	v_cndmask_b32_e32 v201, v128, v131, vcc
	v_lshl_add_u64 v[128:129], s[0:1], 0, v[62:63]
	flat_load_dword v165, v[128:129]
	v_not_b32_e32 v131, v137
	v_cmp_gt_i32_e32 vcc, 0, v137
	v_lshl_add_u64 v[128:129], s[0:1], 0, v[60:61]
	v_or_b32_e32 v137, 0x80000000, v139
	v_cndmask_b32_e32 v199, v136, v131, vcc
	v_not_b32_e32 v131, v138
	flat_load_dword v136, v[128:129]
	v_or_b32_e32 v128, 0x80000000, v138
	v_cmp_gt_i32_e32 vcc, 0, v138
	s_nop 1
	v_cndmask_b32_e32 v198, v128, v131, vcc
	v_lshl_add_u64 v[128:129], s[0:1], 0, v[58:59]
	flat_load_dword v138, v[128:129]
	v_lshl_add_u64 v[128:129], s[0:1], 0, v[56:57]
	v_not_b32_e32 v131, v139
	v_cmp_gt_i32_e32 vcc, 0, v139
	flat_load_dword v139, v[128:129]
	v_lshl_add_u64 v[128:129], s[0:1], 0, v[54:55]
	v_cndmask_b32_e32 v197, v137, v131, vcc
	v_not_b32_e32 v131, v140
	v_or_b32_e32 v137, 0x80000000, v140
	v_cmp_gt_i32_e32 vcc, 0, v140
	flat_load_dword v140, v[128:129]
	v_lshl_add_u64 v[128:129], s[0:1], 0, v[52:53]
	v_cndmask_b32_e32 v196, v137, v131, vcc
	v_not_b32_e32 v131, v141
	v_or_b32_e32 v137, 0x80000000, v141
	v_cmp_gt_i32_e32 vcc, 0, v141
	flat_load_dword v141, v[128:129]
	v_lshl_add_u64 v[128:129], s[0:1], 0, v[50:51]
	v_cndmask_b32_e32 v195, v137, v131, vcc
	v_not_b32_e32 v131, v130
	v_or_b32_e32 v137, 0x80000000, v130
	v_cmp_gt_i32_e32 vcc, 0, v130
	v_not_b32_e32 v130, v162
	s_nop 0
	v_cndmask_b32_e32 v194, v137, v131, vcc
	v_or_b32_e32 v131, 0x80000000, v162
	v_cmp_gt_i32_e32 vcc, 0, v162
	flat_load_dword v137, v[128:129]
	v_not_b32_e32 v128, v163
	v_cndmask_b32_e32 v193, v131, v130, vcc
	v_or_b32_e32 v129, 0x80000000, v163
	v_cmp_gt_i32_e32 vcc, 0, v163
	v_not_b32_e32 v130, v164
	s_nop 0
	v_cndmask_b32_e32 v192, v129, v128, vcc
	v_lshl_add_u64 v[128:129], s[0:1], 0, v[48:49]
	flat_load_dword v131, v[128:129]
	v_or_b32_e32 v128, 0x80000000, v164
	v_cmp_gt_i32_e32 vcc, 0, v164
	s_nop 1
	v_cndmask_b32_e32 v191, v128, v130, vcc
	v_lshl_add_u64 v[128:129], s[0:1], 0, v[46:47]
	v_not_b32_e32 v130, v166
	flat_load_dword v162, v[128:129]
	v_or_b32_e32 v128, 0x80000000, v166
	v_cmp_gt_i32_e32 vcc, 0, v166
	s_nop 1
	v_cndmask_b32_e32 v190, v128, v130, vcc
	v_lshl_add_u64 v[128:129], s[0:1], 0, v[44:45]
	flat_load_dword v163, v[128:129]
	v_not_b32_e32 v130, v132
	v_or_b32_e32 v128, 0x80000000, v132
	v_cmp_gt_i32_e32 vcc, 0, v132
	s_nop 1
	v_cndmask_b32_e32 v189, v128, v130, vcc
	v_lshl_add_u64 v[128:129], s[0:1], 0, v[42:43]
	v_not_b32_e32 v130, v133
	flat_load_dword v132, v[128:129]
	v_or_b32_e32 v128, 0x80000000, v133
	v_cmp_gt_i32_e32 vcc, 0, v133
	s_waitcnt vmcnt(0) lgkmcnt(0)
	v_or_b32_e32 v133, 0x80000000, v134
	v_cndmask_b32_e32 v188, v128, v130, vcc
	v_lshl_add_u64 v[128:129], s[0:1], 0, v[40:41]
	s_add_u32 s0, s12, 0x3000
	s_addc_u32 s1, s13, 0
	v_not_b32_e32 v130, v134
	flat_load_dword v164, v[128:129]
	v_cmp_gt_i32_e32 vcc, 0, v134
	v_lshl_add_u64 v[128:129], s[0:1], 0, v[0:1]
	s_nop 0
	v_cndmask_b32_e32 v187, v133, v130, vcc
	v_not_b32_e32 v130, v135
	flat_load_dword v133, v[128:129]
	v_or_b32_e32 v128, 0x80000000, v135
	v_cmp_gt_i32_e32 vcc, 0, v135
	v_or_b32_e32 v129, 0x80000000, v165
	v_or_b32_e32 v135, 0x80000000, v136
	v_cndmask_b32_e32 v186, v128, v130, vcc
	v_not_b32_e32 v128, v165
	v_cmp_gt_i32_e32 vcc, 0, v165
	v_not_b32_e32 v130, v136
	s_nop 0
	v_cndmask_b32_e32 v185, v129, v128, vcc
	v_lshl_add_u64 v[128:129], s[0:1], 0, v[38:39]
	flat_load_dword v134, v[128:129]
	v_lshl_add_u64 v[128:129], s[0:1], 0, v[36:37]
	flat_load_dword v165, v[128:129]
	v_cmp_gt_i32_e32 vcc, 0, v136
	v_lshl_add_u64 v[128:129], s[0:1], 0, v[34:35]
	flat_load_dword v136, v[128:129]
	v_cndmask_b32_e32 v184, v135, v130, vcc
	v_not_b32_e32 v130, v138
	v_or_b32_e32 v135, 0x80000000, v138
	v_cmp_gt_i32_e32 vcc, 0, v138
	v_lshl_add_u64 v[128:129], s[0:1], 0, v[62:63]
	flat_load_dword v138, v[128:129]
	v_cndmask_b32_e32 v183, v135, v130, vcc
	v_not_b32_e32 v130, v139
	v_or_b32_e32 v135, 0x80000000, v139
	v_cmp_gt_i32_e32 vcc, 0, v139
	v_lshl_add_u64 v[128:129], s[0:1], 0, v[60:61]
	s_nop 0
	v_cndmask_b32_e32 v182, v135, v130, vcc
	v_not_b32_e32 v130, v140
	flat_load_dword v135, v[128:129]
	v_or_b32_e32 v128, 0x80000000, v140
	v_cmp_gt_i32_e32 vcc, 0, v140
	s_nop 1
	v_cndmask_b32_e32 v181, v128, v130, vcc
	v_lshl_add_u64 v[128:129], s[0:1], 0, v[58:59]
	v_not_b32_e32 v130, v141
	flat_load_dword v139, v[128:129]
	v_or_b32_e32 v128, 0x80000000, v141
	v_cmp_gt_i32_e32 vcc, 0, v141
	v_or_b32_e32 v141, 0x80000000, v137
	s_nop 0
	v_cndmask_b32_e32 v180, v128, v130, vcc
	v_lshl_add_u64 v[128:129], s[0:1], 0, v[56:57]
	flat_load_dword v140, v[128:129]
	v_lshl_add_u64 v[128:129], s[0:1], 0, v[54:55]
	flat_load_dword v222, v[128:129]
	v_not_b32_e32 v130, v137
	v_cmp_gt_i32_e32 vcc, 0, v137
	v_lshl_add_u64 v[128:129], s[0:1], 0, v[52:53]
	v_or_b32_e32 v137, 0x80000000, v131
	v_cndmask_b32_e32 v179, v141, v130, vcc
	v_not_b32_e32 v130, v131
	flat_load_dword v141, v[128:129]
	v_cmp_gt_i32_e32 vcc, 0, v131
	v_lshl_add_u64 v[128:129], s[0:1], 0, v[50:51]
	v_or_b32_e32 v131, 0x80000000, v162
	v_cndmask_b32_e32 v178, v137, v130, vcc
	v_not_b32_e32 v130, v162
	flat_load_dword v137, v[128:129]
	v_cmp_gt_i32_e32 vcc, 0, v162
	v_lshl_add_u64 v[128:129], s[0:1], 0, v[48:49]
	v_or_b32_e32 v162, 0x80000000, v132
	v_cndmask_b32_e32 v177, v131, v130, vcc
	v_not_b32_e32 v130, v163
	flat_load_dword v131, v[128:129]
	v_or_b32_e32 v128, 0x80000000, v163
	v_cmp_gt_i32_e32 vcc, 0, v163
	s_nop 1
	v_cndmask_b32_e32 v176, v128, v130, vcc
	v_lshl_add_u64 v[128:129], s[0:1], 0, v[46:47]
	flat_load_dword v223, v[128:129]
	v_lshl_add_u64 v[128:129], s[0:1], 0, v[44:45]
	flat_load_dword v224, v[128:129]
	v_lshl_add_u64 v[128:129], s[0:1], 0, v[42:43]
	flat_load_dword v225, v[128:129]
	v_lshl_add_u64 v[128:129], s[0:1], 0, v[40:41]
	s_add_u32 s0, s12, 0x4000
	v_not_b32_e32 v130, v132
	v_cmp_gt_i32_e32 vcc, 0, v132
	flat_load_dword v226, v[128:129]
	s_addc_u32 s1, s13, 0
	v_cndmask_b32_e32 v175, v162, v130, vcc
	s_waitcnt vmcnt(0) lgkmcnt(0)
; DI unsigned f2key(float f) { const unsigned u = __float_as_uint(f); return (u & 0x80000000u) ? ~u : (u | 0x80000000u); }
; template <int NV>
; DI void topk_row(const float* row, int s, LAS int* lst, int lane) {
;     ...
;     for (int jo = 0; jo < NV / 16; ++jo) { const float* rb = row + jo * 1024;
; #pragma unroll
;         for (int ji = 0; ji < 16; ++ji) { const int j = jo * 16 + ji; const unsigned u = f2key(rb[ji * 64 + lane]); key[j] = (j * 64 + lane <= s) ? u : 0u; } }
	v_not_b32_e32 v130, v164
	v_or_b32_e32 v132, 0x80000000, v164
	v_cmp_gt_i32_e32 vcc, 0, v164
	v_lshl_add_u64 v[128:129], s[0:1], 0, v[0:1]
	flat_load_dword v227, v[128:129]
	v_cndmask_b32_e32 v173, v132, v130, vcc
	v_not_b32_e32 v130, v133
	v_or_b32_e32 v132, 0x80000000, v133
	v_cmp_gt_i32_e32 vcc, 0, v133
	v_not_b32_e32 v128, v134
	v_or_b32_e32 v129, 0x80000000, v134
	v_cndmask_b32_e32 v174, v132, v130, vcc
	v_cmp_gt_i32_e32 vcc, 0, v134
	v_not_b32_e32 v130, v165
	v_or_b32_e32 v133, 0x80000000, v136
	v_cndmask_b32_e32 v172, v129, v128, vcc
	v_lshl_add_u64 v[128:129], s[0:1], 0, v[38:39]
	flat_load_dword v132, v[128:129]
	v_or_b32_e32 v128, 0x80000000, v165
	v_cmp_gt_i32_e32 vcc, 0, v165
	s_nop 1
	v_cndmask_b32_e32 v171, v128, v130, vcc
	v_not_b32_e32 v130, v136
	v_lshl_add_u64 v[128:129], s[0:1], 0, v[36:37]
	v_cmp_gt_i32_e32 vcc, 0, v136
	flat_load_dword v134, v[128:129]
	v_not_b32_e32 v128, v138
	v_cndmask_b32_e32 v170, v133, v130, vcc
	v_or_b32_e32 v129, 0x80000000, v138
	v_cmp_gt_i32_e32 vcc, 0, v138
	v_not_b32_e32 v130, v135
	s_nop 0
	v_cndmask_b32_e32 v169, v129, v128, vcc
	v_lshl_add_u64 v[128:129], s[0:1], 0, v[34:35]
	flat_load_dword v133, v[128:129]
	v_or_b32_e32 v128, 0x80000000, v135
	v_cmp_gt_i32_e32 vcc, 0, v135
	v_or_b32_e32 v135, 0x80000000, v139
	s_nop 0
	v_cndmask_b32_e32 v168, v128, v130, vcc
	v_not_b32_e32 v130, v139
	v_lshl_add_u64 v[128:129], s[0:1], 0, v[62:63]
	v_cmp_gt_i32_e32 vcc, 0, v139
	flat_load_dword v228, v[128:129]
	v_not_b32_e32 v128, v140
	v_cndmask_b32_e32 v167, v135, v130, vcc
	v_or_b32_e32 v129, 0x80000000, v140
	v_cmp_gt_i32_e32 vcc, 0, v140
	v_not_b32_e32 v130, v222
	v_or_b32_e32 v135, 0x80000000, v141
	v_cndmask_b32_e32 v166, v129, v128, vcc
	v_lshl_add_u64 v[128:129], s[0:1], 0, v[60:61]
	flat_load_dword v229, v[128:129]
	v_or_b32_e32 v128, 0x80000000, v222
	v_cmp_gt_i32_e32 vcc, 0, v222
	s_nop 1
	v_cndmask_b32_e32 v165, v128, v130, vcc
	v_lshl_add_u64 v[128:129], s[0:1], 0, v[58:59]
	flat_load_dword v222, v[128:129]
	v_not_b32_e32 v130, v141
	v_cmp_gt_i32_e32 vcc, 0, v141
	v_not_b32_e32 v128, v137
	v_or_b32_e32 v129, 0x80000000, v137
	v_cndmask_b32_e32 v164, v135, v130, vcc
	v_cmp_gt_i32_e32 vcc, 0, v137
	v_not_b32_e32 v130, v131
	v_or_b32_e32 v135, 0x80000000, v131
	v_cndmask_b32_e32 v163, v129, v128, vcc
	v_lshl_add_u64 v[128:129], s[0:1], 0, v[56:57]
	v_cmp_gt_i32_e32 vcc, 0, v131
	flat_load_dword v230, v[128:129]
	v_not_b32_e32 v128, v223
	v_cndmask_b32_e32 v162, v135, v130, vcc
	v_or_b32_e32 v129, 0x80000000, v223
	v_cmp_gt_i32_e32 vcc, 0, v223
	v_not_b32_e32 v130, v224
	s_waitcnt vmcnt(0) lgkmcnt(0)
	v_or_b32_e32 v131, 0x80000000, v134
	v_cndmask_b32_e32 v141, v129, v128, vcc
	v_lshl_add_u64 v[128:129], s[0:1], 0, v[54:55]
	flat_load_dword v223, v[128:129]
	v_or_b32_e32 v128, 0x80000000, v224
	v_cmp_gt_i32_e32 vcc, 0, v224
	s_nop 1
	v_cndmask_b32_e32 v140, v128, v130, vcc
	v_lshl_add_u64 v[128:129], s[0:1], 0, v[52:53]
	v_not_b32_e32 v130, v225
	flat_load_dword v224, v[128:129]
	v_or_b32_e32 v128, 0x80000000, v225
	v_cmp_gt_i32_e32 vcc, 0, v225
	v_or_b32_e32 v129, 0x80000000, v226
	s_nop 0
	v_cndmask_b32_e32 v139, v128, v130, vcc
	v_not_b32_e32 v128, v226
	v_cmp_gt_i32_e32 vcc, 0, v226
	v_not_b32_e32 v130, v227
	s_nop 0
	v_cndmask_b32_e32 v138, v129, v128, vcc
	v_lshl_add_u64 v[128:129], s[0:1], 0, v[50:51]
	flat_load_dword v225, v[128:129]
	v_or_b32_e32 v128, 0x80000000, v227
	v_cmp_gt_i32_e32 vcc, 0, v227
	s_nop 1
	v_cndmask_b32_e32 v128, v128, v130, vcc
	v_cmp_lt_u32_e32 vcc, s2, v161
	v_not_b32_e32 v130, v132
	s_movk_i32 s2, 0x103f
	v_cndmask_b32_e32 v137, 0, v128, vcc
	v_lshl_add_u64 v[128:129], s[0:1], 0, v[48:49]
	flat_load_dword v226, v[128:129]
	v_or_b32_e32 v128, 0x80000000, v132
	v_cmp_gt_i32_e32 vcc, 0, v132
	s_nop 1
	v_cndmask_b32_e32 v128, v128, v130, vcc
	v_cmp_lt_u32_e32 vcc, s2, v161
	v_not_b32_e32 v130, v134
	s_movk_i32 s2, 0x107f
	v_cndmask_b32_e32 v136, 0, v128, vcc
	v_lshl_add_u64 v[128:129], s[0:1], 0, v[46:47]
	flat_load_dword v227, v[128:129]
	v_cmp_gt_i32_e32 vcc, 0, v134
	s_nop 1
	v_cndmask_b32_e32 v128, v131, v130, vcc
	v_cmp_lt_u32_e32 vcc, s2, v161
	v_not_b32_e32 v130, v133
	v_or_b32_e32 v131, 0x80000000, v133
	v_cndmask_b32_e32 v135, 0, v128, vcc
	v_lshl_add_u64 v[128:129], s[0:1], 0, v[44:45]
	v_cmp_gt_i32_e32 vcc, 0, v133
	s_movk_i32 s2, 0x10bf
	flat_load_dword v231, v[128:129]
	v_cndmask_b32_e32 v128, v131, v130, vcc
	v_cmp_lt_u32_e32 vcc, s2, v161
	v_or_b32_e32 v129, 0x80000000, v228
	s_movk_i32 s2, 0x10ff
	v_cndmask_b32_e32 v134, 0, v128, vcc
	v_not_b32_e32 v128, v228
	v_cmp_gt_i32_e32 vcc, 0, v228
	s_nop 1
	v_cndmask_b32_e32 v130, v129, v128, vcc
	v_lshl_add_u64 v[128:129], s[0:1], 0, v[42:43]
	v_cmp_lt_u32_e32 vcc, s2, v161
	flat_load_dword v228, v[128:129]
	v_not_b32_e32 v128, v229
	v_cndmask_b32_e32 v132, 0, v130, vcc
	v_or_b32_e32 v129, 0x80000000, v229
	v_cmp_gt_i32_e32 vcc, 0, v229
	s_movk_i32 s2, 0x117f
	s_nop 0
	v_cndmask_b32_e32 v130, v129, v128, vcc
	v_lshl_add_u64 v[128:129], s[0:1], 0, v[40:41]
	s_movk_i32 s0, 0x113f
	v_cmp_lt_u32_e32 vcc, s0, v161
	s_add_u32 s0, s12, 0x5000
	flat_load_dword v229, v[128:129]
	s_addc_u32 s1, s13, 0
	v_lshl_add_u64 v[38:39], s[0:1], 0, v[38:39]
	v_cndmask_b32_e32 v130, 0, v130, vcc
	v_cmp_gt_i32_e32 vcc, 0, v222
	flat_load_dword v38, v[38:39]
	v_not_b32_e32 v128, v222
	v_or_b32_e32 v129, 0x80000000, v222
	v_cndmask_b32_e32 v131, v129, v128, vcc
	v_lshl_add_u64 v[128:129], s[0:1], 0, v[0:1]
	flat_load_dword v0, v[128:129]
	v_cmp_lt_u32_e32 vcc, s2, v161
	v_not_b32_e32 v128, v230
	v_or_b32_e32 v129, 0x80000000, v230
	v_cndmask_b32_e32 v133, 0, v131, vcc
	v_cmp_gt_i32_e32 vcc, 0, v230
	s_movk_i32 s2, 0x11bf
	v_lshl_add_u64 v[36:37], s[0:1], 0, v[36:37]
	v_cndmask_b32_e32 v128, v129, v128, vcc
	v_cmp_lt_u32_e32 vcc, s2, v161
	s_movk_i32 s2, 0x11ff
	flat_load_dword v36, v[36:37]
	v_cndmask_b32_e32 v131, 0, v128, vcc
	s_waitcnt vmcnt(0) lgkmcnt(0)
; DI unsigned f2key(float f) { const unsigned u = __float_as_uint(f); return (u & 0x80000000u) ? ~u : (u | 0x80000000u); }
; template <int NV>
; DI void topk_row(const float* row, int s, LAS int* lst, int lane) {
;     ...
;     for (int jo = 0; jo < NV / 16; ++jo) { const float* rb = row + jo * 1024;
; #pragma unroll
;         for (int ji = 0; ji < 16; ++ji) { const int j = jo * 16 + ji; const unsigned u = f2key(rb[ji * 64 + lane]); key[j] = (j * 64 + lane <= s) ? u : 0u; } }
	v_not_b32_e32 v39, v223
	v_or_b32_e32 v128, 0x80000000, v223
	v_cmp_gt_i32_e32 vcc, 0, v223
	v_or_b32_e32 v37, 0x80000000, v224
	v_lshl_add_u64 v[34:35], s[0:1], 0, v[34:35]
	v_cndmask_b32_e32 v39, v128, v39, vcc
	v_cmp_lt_u32_e32 vcc, s2, v161
	s_movk_i32 s2, 0x123f
	v_or_b32_e32 v222, 0x80000000, v225
	v_cndmask_b32_e32 v128, 0, v39, vcc
	v_not_b32_e32 v39, v224
	v_cmp_gt_i32_e32 vcc, 0, v224
	s_nop 1
	v_cndmask_b32_e32 v37, v37, v39, vcc
	flat_load_dword v39, v[34:35]
	v_cmp_lt_u32_e32 vcc, s2, v161
	v_lshl_add_u64 v[34:35], s[0:1], 0, v[62:63]
	s_movk_i32 s2, 0x127f
	v_cndmask_b32_e32 v129, 0, v37, vcc
	v_not_b32_e32 v37, v225
	v_cmp_gt_i32_e32 vcc, 0, v225
	flat_load_dword v63, v[34:35]
	s_nop 0
	v_cndmask_b32_e32 v34, v222, v37, vcc
	v_cmp_lt_u32_e32 vcc, s2, v161
	v_not_b32_e32 v37, v226
	s_movk_i32 s2, 0x12bf
	v_cndmask_b32_e32 v62, 0, v34, vcc
	v_lshl_add_u64 v[34:35], s[0:1], 0, v[60:61]
	flat_load_dword v60, v[34:35]
	v_or_b32_e32 v34, 0x80000000, v226
	v_cmp_gt_i32_e32 vcc, 0, v226
	v_or_b32_e32 v61, 0x80000000, v227
	s_nop 0
	v_cndmask_b32_e32 v37, v34, v37, vcc
	v_lshl_add_u64 v[34:35], s[0:1], 0, v[58:59]
	flat_load_dword v59, v[34:35]
	v_cmp_lt_u32_e32 vcc, s2, v161
	v_lshl_add_u64 v[34:35], s[0:1], 0, v[56:57]
	s_movk_i32 s2, 0x12ff
	v_cndmask_b32_e32 v58, 0, v37, vcc
	v_not_b32_e32 v37, v227
	v_cmp_gt_i32_e32 vcc, 0, v227
	flat_load_dword v57, v[34:35]
	s_nop 0
	v_cndmask_b32_e32 v34, v61, v37, vcc
	v_cmp_lt_u32_e32 vcc, s2, v161
	v_not_b32_e32 v37, v231
	s_movk_i32 s2, 0x133f
	v_cndmask_b32_e32 v56, 0, v34, vcc
	v_lshl_add_u64 v[34:35], s[0:1], 0, v[54:55]
	flat_load_dword v54, v[34:35]
	v_or_b32_e32 v34, 0x80000000, v231
	v_cmp_gt_i32_e32 vcc, 0, v231
	v_or_b32_e32 v55, 0x80000000, v228
	s_nop 0
	v_cndmask_b32_e32 v37, v34, v37, vcc
	v_lshl_add_u64 v[34:35], s[0:1], 0, v[52:53]
	flat_load_dword v53, v[34:35]
	v_cmp_lt_u32_e32 vcc, s2, v161
	v_lshl_add_u64 v[34:35], s[0:1], 0, v[50:51]
	s_movk_i32 s2, 0x137f
	v_cndmask_b32_e32 v52, 0, v37, vcc
	v_not_b32_e32 v37, v228
	v_cmp_gt_i32_e32 vcc, 0, v228
	flat_load_dword v61, v[34:35]
	s_nop 0
	v_cndmask_b32_e32 v34, v55, v37, vcc
	v_cmp_lt_u32_e32 vcc, s2, v161
	v_not_b32_e32 v37, v229
	s_movk_i32 s2, 0x13bf
	v_cndmask_b32_e32 v50, 0, v34, vcc
	v_lshl_add_u64 v[34:35], s[0:1], 0, v[48:49]
	flat_load_dword v55, v[34:35]
	v_or_b32_e32 v34, 0x80000000, v229
	v_cmp_gt_i32_e32 vcc, 0, v229
	s_nop 1
	v_cndmask_b32_e32 v37, v34, v37, vcc
	v_lshl_add_u64 v[34:35], s[0:1], 0, v[46:47]
	flat_load_dword v222, v[34:35]
	v_cmp_lt_u32_e32 vcc, s2, v161
	v_lshl_add_u64 v[34:35], s[0:1], 0, v[44:45]
	v_or_b32_e32 v46, 0x80000000, v0
	v_cndmask_b32_e32 v49, 0, v37, vcc
	v_not_b32_e32 v37, v0
	flat_load_dword v223, v[34:35]
	v_cmp_gt_i32_e32 vcc, 0, v0
	s_movk_i32 s2, 0x13ff
	v_lshl_add_u64 v[34:35], s[0:1], 0, v[42:43]
	v_cndmask_b32_e32 v0, v46, v37, vcc
	v_cmp_lt_u32_e32 vcc, s2, v161
	flat_load_dword v224, v[34:35]
	v_or_b32_e32 v34, 0x80000000, v38
	v_cndmask_b32_e32 v48, 0, v0, vcc
	v_not_b32_e32 v0, v38
	v_cmp_gt_i32_e32 vcc, 0, v38
	s_nop 1
	v_cndmask_b32_e32 v0, v34, v0, vcc
	v_lshl_add_u64 v[34:35], s[0:1], 0, v[40:41]
	flat_load_dword v34, v[34:35]
	s_movk_i32 s0, 0x143f
	v_cmp_lt_u32_e32 vcc, s0, v161
	v_or_b32_e32 v35, 0x80000000, v36
	s_movk_i32 s0, 0x147f
	v_cndmask_b32_e32 v51, 0, v0, vcc
	v_not_b32_e32 v0, v36
	v_cmp_gt_i32_e32 vcc, 0, v36
	s_nop 1
	v_cndmask_b32_e32 v0, v35, v0, vcc
	v_cmp_lt_u32_e32 vcc, s0, v161
	s_waitcnt vmcnt(0) lgkmcnt(0)
	v_or_b32_e32 v35, 0x80000000, v39
	s_movk_i32 s0, 0x14bf
	v_cndmask_b32_e32 v47, 0, v0, vcc
	v_not_b32_e32 v0, v39
	v_cmp_gt_i32_e32 vcc, 0, v39
	s_nop 1
	v_cndmask_b32_e32 v0, v35, v0, vcc
	v_cmp_lt_u32_e32 vcc, s0, v161
	v_or_b32_e32 v35, 0x80000000, v63
	s_movk_i32 s0, 0x14ff
	v_cndmask_b32_e32 v46, 0, v0, vcc
	v_not_b32_e32 v0, v63
	v_cmp_gt_i32_e32 vcc, 0, v63
	s_nop 1
	v_cndmask_b32_e32 v0, v35, v0, vcc
	v_cmp_lt_u32_e32 vcc, s0, v161
	v_or_b32_e32 v35, 0x80000000, v60
	s_movk_i32 s0, 0x153f
	v_cndmask_b32_e32 v45, 0, v0, vcc
	v_not_b32_e32 v0, v60
	v_cmp_gt_i32_e32 vcc, 0, v60
	s_nop 1
	v_cndmask_b32_e32 v0, v35, v0, vcc
	v_cmp_lt_u32_e32 vcc, s0, v161
	v_or_b32_e32 v35, 0x80000000, v59
	s_movk_i32 s0, 0x157f
	v_cndmask_b32_e32 v44, 0, v0, vcc
	v_not_b32_e32 v0, v59
	v_cmp_gt_i32_e32 vcc, 0, v59
	s_nop 1
	v_cndmask_b32_e32 v0, v35, v0, vcc
	v_cmp_lt_u32_e32 vcc, s0, v161
	v_or_b32_e32 v35, 0x80000000, v57
	s_movk_i32 s0, 0x15bf
	v_cndmask_b32_e32 v43, 0, v0, vcc
	v_not_b32_e32 v0, v57
	v_cmp_gt_i32_e32 vcc, 0, v57
	s_nop 1
	v_cndmask_b32_e32 v0, v35, v0, vcc
	v_cmp_lt_u32_e32 vcc, s0, v161
	v_or_b32_e32 v35, 0x80000000, v54
	s_movk_i32 s0, 0x15ff
	v_cndmask_b32_e32 v42, 0, v0, vcc
	v_not_b32_e32 v0, v54
	v_cmp_gt_i32_e32 vcc, 0, v54
	s_nop 1
	v_cndmask_b32_e32 v0, v35, v0, vcc
	v_cmp_lt_u32_e32 vcc, s0, v161
	v_or_b32_e32 v35, 0x80000000, v53
	s_movk_i32 s0, 0x163f
	v_cndmask_b32_e32 v41, 0, v0, vcc
	v_not_b32_e32 v0, v53
	v_cmp_gt_i32_e32 vcc, 0, v53
	v_or_b32_e32 v53, 0x80000000, v34
	s_nop 0
	v_cndmask_b32_e32 v0, v35, v0, vcc
	v_cmp_lt_u32_e32 vcc, s0, v161
	v_or_b32_e32 v35, 0x80000000, v61
	s_movk_i32 s0, 0x167f
	v_cndmask_b32_e32 v40, 0, v0, vcc
	v_not_b32_e32 v0, v61
	v_cmp_gt_i32_e32 vcc, 0, v61
	s_nop 1
	v_cndmask_b32_e32 v0, v35, v0, vcc
	v_cmp_lt_u32_e32 vcc, s0, v161
	v_or_b32_e32 v35, 0x80000000, v55
	s_movk_i32 s0, 0x16bf
	v_cndmask_b32_e32 v39, 0, v0, vcc
	v_not_b32_e32 v0, v55
	v_cmp_gt_i32_e32 vcc, 0, v55
	s_nop 1
	v_cndmask_b32_e32 v0, v35, v0, vcc
	v_cmp_lt_u32_e32 vcc, s0, v161
	v_or_b32_e32 v35, 0x80000000, v222
	s_movk_i32 s0, 0x16ff
	v_cndmask_b32_e32 v38, 0, v0, vcc
	v_not_b32_e32 v0, v222
; DI unsigned f2key(float f) { const unsigned u = __float_as_uint(f); return (u & 0x80000000u) ? ~u : (u | 0x80000000u); }
; template <int NV>
; DI void topk_row(const float* row, int s, LAS int* lst, int lane) {
;     ...
;     for (int jo = 0; jo < NV / 16; ++jo) { const float* rb = row + jo * 1024;
; #pragma unroll
;         for (int ji = 0; ji < 16; ++ji) { const int j = jo * 16 + ji; const unsigned u = f2key(rb[ji * 64 + lane]); key[j] = (j * 64 + lane <= s) ? u : 0u; } }
;     unsigned T = 0u;
; #pragma unroll 1
	v_cmp_gt_i32_e32 vcc, 0, v222
	s_nop 1
	v_cndmask_b32_e32 v0, v35, v0, vcc
	v_cmp_lt_u32_e32 vcc, s0, v161
	v_or_b32_e32 v35, 0x80000000, v223
	s_movk_i32 s0, 0x173f
	v_cndmask_b32_e32 v37, 0, v0, vcc
	v_not_b32_e32 v0, v223
	v_cmp_gt_i32_e32 vcc, 0, v223
	s_nop 1
	v_cndmask_b32_e32 v0, v35, v0, vcc
	v_cmp_lt_u32_e32 vcc, s0, v161
	v_or_b32_e32 v35, 0x80000000, v224
	s_movk_i32 s0, 0x177f
	v_cndmask_b32_e32 v36, 0, v0, vcc
	v_not_b32_e32 v0, v224
	v_cmp_gt_i32_e32 vcc, 0, v224
	s_nop 1
	v_cndmask_b32_e32 v0, v35, v0, vcc
	v_cmp_lt_u32_e32 vcc, s0, v161
	s_movk_i32 s0, 0x17bf
	s_nop 0
	v_cndmask_b32_e32 v35, 0, v0, vcc
	v_not_b32_e32 v0, v34
	v_cmp_gt_i32_e32 vcc, 0, v34
	v_mov_b32_e32 v34, 0
	s_nop 0
	v_cndmask_b32_e32 v0, v53, v0, vcc
	v_cmp_lt_u32_e32 vcc, s0, v161
	v_mov_b32_e32 v53, 31
	s_nop 0
	v_cndmask_b32_e32 v0, 0, v0, vcc
	v_max_u32_e32 v255, v221, v220
	v_max_u32_e32 v255, v255, v219
	v_max_u32_e32 v255, v255, v218
	v_max_u32_e32 v255, v255, v217
	v_max_u32_e32 v255, v255, v216
	v_max_u32_e32 v255, v255, v215
	v_max_u32_e32 v255, v255, v214
	v_max_u32_e32 v255, v255, v213
	v_max_u32_e32 v255, v255, v211
	v_max_u32_e32 v255, v255, v206
	v_max_u32_e32 v255, v255, v203
	v_max_u32_e32 v255, v255, v200
	v_max_u32_e32 v255, v255, v202
	v_max_u32_e32 v255, v255, v204
	v_max_u32_e32 v255, v255, v207
	v_max_u32_e32 v255, v255, v208
	v_max_u32_e32 v255, v255, v212
	v_max_u32_e32 v255, v255, v210
	v_max_u32_e32 v255, v255, v209
	v_max_u32_e32 v255, v255, v205
	v_max_u32_e32 v255, v255, v201
	v_max_u32_e32 v255, v255, v199
	v_max_u32_e32 v255, v255, v198
	v_max_u32_e32 v255, v255, v197
	v_max_u32_e32 v255, v255, v196
	v_max_u32_e32 v255, v255, v195
	v_max_u32_e32 v255, v255, v194
	v_max_u32_e32 v255, v255, v193
	v_max_u32_e32 v255, v255, v192
	v_max_u32_e32 v255, v255, v191
	v_max_u32_e32 v255, v255, v190
	v_max_u32_e32 v255, v255, v189
	v_max_u32_e32 v255, v255, v188
	v_max_u32_e32 v255, v255, v187
	v_max_u32_e32 v255, v255, v186
	v_max_u32_e32 v255, v255, v185
	v_max_u32_e32 v255, v255, v184
	v_max_u32_e32 v255, v255, v183
	v_max_u32_e32 v255, v255, v182
	v_max_u32_e32 v255, v255, v181
	v_max_u32_e32 v255, v255, v180
	v_max_u32_e32 v255, v255, v179
	v_max_u32_e32 v255, v255, v178
	v_max_u32_e32 v255, v255, v177
	v_max_u32_e32 v255, v255, v176
	v_max_u32_e32 v255, v255, v175
	v_max_u32_e32 v255, v255, v173
	v_max_u32_e32 v255, v255, v174
	v_max_u32_e32 v255, v255, v172
	v_max_u32_e32 v255, v255, v171
	v_max_u32_e32 v255, v255, v170
	v_max_u32_e32 v255, v255, v169
	v_max_u32_e32 v255, v255, v168
	v_max_u32_e32 v255, v255, v167
	v_max_u32_e32 v255, v255, v166
	v_max_u32_e32 v255, v255, v165
	v_max_u32_e32 v255, v255, v164
	v_max_u32_e32 v255, v255, v163
	v_max_u32_e32 v255, v255, v162
	v_max_u32_e32 v255, v255, v141
	v_max_u32_e32 v255, v255, v140
	v_max_u32_e32 v255, v255, v139
	v_max_u32_e32 v255, v255, v138
	v_max_u32_e32 v255, v255, v137
	v_max_u32_e32 v255, v255, v136
	v_max_u32_e32 v255, v255, v135
	v_max_u32_e32 v255, v255, v134
	v_max_u32_e32 v255, v255, v132
	v_max_u32_e32 v255, v255, v130
	v_max_u32_e32 v255, v255, v133
	v_max_u32_e32 v255, v255, v131
	v_max_u32_e32 v255, v255, v128
	v_max_u32_e32 v255, v255, v129
	v_max_u32_e32 v255, v255, v62
	v_max_u32_e32 v255, v255, v58
	v_max_u32_e32 v255, v255, v56
	v_max_u32_e32 v255, v255, v52
	v_max_u32_e32 v255, v255, v50
	v_max_u32_e32 v255, v255, v49
	v_max_u32_e32 v255, v255, v48
	v_max_u32_e32 v255, v255, v51
	v_max_u32_e32 v255, v255, v47
	v_max_u32_e32 v255, v255, v46
	v_max_u32_e32 v255, v255, v45
	v_max_u32_e32 v255, v255, v44
	v_max_u32_e32 v255, v255, v43
	v_max_u32_e32 v255, v255, v42
	v_max_u32_e32 v255, v255, v41
	v_max_u32_e32 v255, v255, v40
	v_max_u32_e32 v255, v255, v39
	v_max_u32_e32 v255, v255, v38
	v_max_u32_e32 v255, v255, v37
	v_max_u32_e32 v255, v255, v36
	v_max_u32_e32 v255, v255, v35
	v_max_u32_e32 v255, v255, v0
	s_nop 1
	v_max_u32_dpp v255, v255, v255 quad_perm:[1,0,3,2] row_mask:0xf bank_mask:0xf bound_ctrl:1
	s_nop 1
	v_max_u32_dpp v255, v255, v255 quad_perm:[2,3,0,1] row_mask:0xf bank_mask:0xf bound_ctrl:1
	s_nop 1
	v_max_u32_dpp v255, v255, v255 row_half_mirror row_mask:0xf bank_mask:0xf bound_ctrl:1
	s_nop 1
	v_max_u32_dpp v255, v255, v255 row_mirror row_mask:0xf bank_mask:0xf bound_ctrl:1
	s_nop 0
	v_readlane_b32 s99, v255, 0
	v_readlane_b32 s100, v255, 16
	s_max_u32 s99, s99, s100
	v_readlane_b32 s100, v255, 32
	s_max_u32 s99, s99, s100
	v_readlane_b32 s100, v255, 48
	s_max_u32 s99, s99, s100
; DI int wave_sum_i(int v) {
;     v += __builtin_amdgcn_update_dpp(0, v, 0xB1, 0xF, 0xF, true);
;     v += __builtin_amdgcn_update_dpp(0, v, 0x4E, 0xF, 0xF, true);
;     v += __builtin_amdgcn_update_dpp(0, v, 0x141, 0xF, 0xF, true);
;     v += __builtin_amdgcn_update_dpp(0, v, 0x140, 0xF, 0xF, true);
;     return __builtin_amdgcn_readlane(v, 0) + __builtin_amdgcn_readlane(v, 16) + __builtin_amdgcn_readlane(v, 32) + __builtin_amdgcn_readlane(v, 48);
; template <int NV>
; DI void topk_row(const float* row, int s, LAS int* lst, int lane) {
;     ...
;         const unsigned cand = T | (1u << bit); int c = 0;
; #pragma unroll
;         for (int j = 0; j < NV; ++j) asm volatile("v_cmp_le_u32 vcc, %2, %1\n\tv_addc_co_u32 %0, vcc, 0, %0, vcc" : "+v"(c) : "v"(key[j]), "s"(cand) : "vcc");
;         const int tot = wave_sum_i(c);
;         if (tot >= 256) T = cand;
;         if (tot == 256) break;
;     }
.LBB0_2485:
	v_lshlrev_b32_e64 v54, v53, 1
	v_mov_b32_e32 v55, 0
	v_or_b32_e32 v54, v54, v34
	s_nop 0
	v_readfirstlane_b32 s100, v54
	s_mov_b32 s0, 0
	s_cmp_gt_u32 s100, s99
	s_cbranch_scc1 .Lp12_skip_2485
	v_cmp_le_u32 vcc, v54, v221
	v_addc_co_u32 v55, vcc, 0, v55, vcc
	s_nop 0
	v_cmp_le_u32 vcc, v54, v220
	v_addc_co_u32 v55, vcc, 0, v55, vcc
	s_nop 0
	v_cmp_le_u32 vcc, v54, v219
	v_addc_co_u32 v55, vcc, 0, v55, vcc
	s_nop 0
	v_cmp_le_u32 vcc, v54, v218
	v_addc_co_u32 v55, vcc, 0, v55, vcc
	s_nop 0
	v_cmp_le_u32 vcc, v54, v217
	v_addc_co_u32 v55, vcc, 0, v55, vcc
	s_nop 0
	v_cmp_le_u32 vcc, v54, v216
	v_addc_co_u32 v55, vcc, 0, v55, vcc
	s_nop 0
	v_cmp_le_u32 vcc, v54, v215
	v_addc_co_u32 v55, vcc, 0, v55, vcc
	s_nop 0
	v_cmp_le_u32 vcc, v54, v214
	v_addc_co_u32 v55, vcc, 0, v55, vcc
	s_nop 0
	v_cmp_le_u32 vcc, v54, v213
	v_addc_co_u32 v55, vcc, 0, v55, vcc
	s_nop 0
	v_cmp_le_u32 vcc, v54, v211
	v_addc_co_u32 v55, vcc, 0, v55, vcc
	s_nop 0
	v_cmp_le_u32 vcc, v54, v206
	v_addc_co_u32 v55, vcc, 0, v55, vcc
	s_nop 0
	v_cmp_le_u32 vcc, v54, v203
	v_addc_co_u32 v55, vcc, 0, v55, vcc
	s_nop 0
	v_cmp_le_u32 vcc, v54, v200
	v_addc_co_u32 v55, vcc, 0, v55, vcc
	s_nop 0
	v_cmp_le_u32 vcc, v54, v202
	v_addc_co_u32 v55, vcc, 0, v55, vcc
	s_nop 0
	v_cmp_le_u32 vcc, v54, v204
	v_addc_co_u32 v55, vcc, 0, v55, vcc
	s_nop 0
	v_cmp_le_u32 vcc, v54, v207
	v_addc_co_u32 v55, vcc, 0, v55, vcc
	s_nop 0
	v_cmp_le_u32 vcc, v54, v208
	v_addc_co_u32 v55, vcc, 0, v55, vcc
	s_nop 0
	v_cmp_le_u32 vcc, v54, v212
	v_addc_co_u32 v55, vcc, 0, v55, vcc
	s_nop 0
	v_cmp_le_u32 vcc, v54, v210
	v_addc_co_u32 v55, vcc, 0, v55, vcc
	s_nop 0
	v_cmp_le_u32 vcc, v54, v209
	v_addc_co_u32 v55, vcc, 0, v55, vcc
	s_nop 0
	v_cmp_le_u32 vcc, v54, v205
	v_addc_co_u32 v55, vcc, 0, v55, vcc
	s_nop 0
	v_cmp_le_u32 vcc, v54, v201
	v_addc_co_u32 v55, vcc, 0, v55, vcc
	s_nop 0
	v_cmp_le_u32 vcc, v54, v199
	v_addc_co_u32 v55, vcc, 0, v55, vcc
	s_nop 0
	v_cmp_le_u32 vcc, v54, v198
	v_addc_co_u32 v55, vcc, 0, v55, vcc
	s_nop 0
	v_cmp_le_u32 vcc, v54, v197
	v_addc_co_u32 v55, vcc, 0, v55, vcc
	s_nop 0
	v_cmp_le_u32 vcc, v54, v196
	v_addc_co_u32 v55, vcc, 0, v55, vcc
	s_nop 0
	v_cmp_le_u32 vcc, v54, v195
	v_addc_co_u32 v55, vcc, 0, v55, vcc
	s_nop 0
	v_cmp_le_u32 vcc, v54, v194
	v_addc_co_u32 v55, vcc, 0, v55, vcc
	s_nop 0
	v_cmp_le_u32 vcc, v54, v193
	v_addc_co_u32 v55, vcc, 0, v55, vcc
	s_nop 0
	v_cmp_le_u32 vcc, v54, v192
	v_addc_co_u32 v55, vcc, 0, v55, vcc
	s_nop 0
	v_cmp_le_u32 vcc, v54, v191
	v_addc_co_u32 v55, vcc, 0, v55, vcc
	s_nop 0
	v_cmp_le_u32 vcc, v54, v190
	v_addc_co_u32 v55, vcc, 0, v55, vcc
	s_nop 0
	v_cmp_le_u32 vcc, v54, v189
	v_addc_co_u32 v55, vcc, 0, v55, vcc
	s_nop 0
	v_cmp_le_u32 vcc, v54, v188
	v_addc_co_u32 v55, vcc, 0, v55, vcc
	s_nop 0
	v_cmp_le_u32 vcc, v54, v187
	v_addc_co_u32 v55, vcc, 0, v55, vcc
	s_nop 0
	v_cmp_le_u32 vcc, v54, v186
	v_addc_co_u32 v55, vcc, 0, v55, vcc
	s_nop 0
	v_cmp_le_u32 vcc, v54, v185
	v_addc_co_u32 v55, vcc, 0, v55, vcc
	s_nop 0
	v_cmp_le_u32 vcc, v54, v184
	v_addc_co_u32 v55, vcc, 0, v55, vcc
	s_nop 0
	v_cmp_le_u32 vcc, v54, v183
	v_addc_co_u32 v55, vcc, 0, v55, vcc
	s_nop 0
	v_cmp_le_u32 vcc, v54, v182
	v_addc_co_u32 v55, vcc, 0, v55, vcc
	s_nop 0
	v_cmp_le_u32 vcc, v54, v181
	v_addc_co_u32 v55, vcc, 0, v55, vcc
	s_nop 0
	v_cmp_le_u32 vcc, v54, v180
	v_addc_co_u32 v55, vcc, 0, v55, vcc
	s_nop 0
	v_cmp_le_u32 vcc, v54, v179
	v_addc_co_u32 v55, vcc, 0, v55, vcc
	s_nop 0
	v_cmp_le_u32 vcc, v54, v178
	v_addc_co_u32 v55, vcc, 0, v55, vcc
	s_nop 0
	v_cmp_le_u32 vcc, v54, v177
	v_addc_co_u32 v55, vcc, 0, v55, vcc
	s_nop 0
	v_cmp_le_u32 vcc, v54, v176
	v_addc_co_u32 v55, vcc, 0, v55, vcc
	s_nop 0
	v_cmp_le_u32 vcc, v54, v175
	v_addc_co_u32 v55, vcc, 0, v55, vcc
	s_nop 0
	v_cmp_le_u32 vcc, v54, v173
	v_addc_co_u32 v55, vcc, 0, v55, vcc
	s_nop 0
	v_cmp_le_u32 vcc, v54, v174
	v_addc_co_u32 v55, vcc, 0, v55, vcc
	s_nop 0
	v_cmp_le_u32 vcc, v54, v172
	v_addc_co_u32 v55, vcc, 0, v55, vcc
	s_nop 0
	v_cmp_le_u32 vcc, v54, v171
	v_addc_co_u32 v55, vcc, 0, v55, vcc
	s_nop 0
	v_cmp_le_u32 vcc, v54, v170
	v_addc_co_u32 v55, vcc, 0, v55, vcc
	s_nop 0
	v_cmp_le_u32 vcc, v54, v169
	v_addc_co_u32 v55, vcc, 0, v55, vcc
	s_nop 0
	v_cmp_le_u32 vcc, v54, v168
	v_addc_co_u32 v55, vcc, 0, v55, vcc
	s_nop 0
	v_cmp_le_u32 vcc, v54, v167
	v_addc_co_u32 v55, vcc, 0, v55, vcc
	s_nop 0
	v_cmp_le_u32 vcc, v54, v166
; DI int wave_sum_i(int v) {
;     v += __builtin_amdgcn_update_dpp(0, v, 0xB1, 0xF, 0xF, true);
;     v += __builtin_amdgcn_update_dpp(0, v, 0x4E, 0xF, 0xF, true);
;     v += __builtin_amdgcn_update_dpp(0, v, 0x141, 0xF, 0xF, true);
;     v += __builtin_amdgcn_update_dpp(0, v, 0x140, 0xF, 0xF, true);
;     return __builtin_amdgcn_readlane(v, 0) + __builtin_amdgcn_readlane(v, 16) + __builtin_amdgcn_readlane(v, 32) + __builtin_amdgcn_readlane(v, 48);
; template <int NV>
; DI void topk_row(const float* row, int s, LAS int* lst, int lane) {
;     ...
;         const unsigned cand = T | (1u << bit); int c = 0;
; #pragma unroll
;         for (int j = 0; j < NV; ++j) asm volatile("v_cmp_le_u32 vcc, %2, %1\n\tv_addc_co_u32 %0, vcc, 0, %0, vcc" : "+v"(c) : "v"(key[j]), "s"(cand) : "vcc");
;         const int tot = wave_sum_i(c);
;         if (tot >= 256) T = cand;
;         if (tot == 256) break;
;     }
	v_addc_co_u32 v55, vcc, 0, v55, vcc
	s_nop 0
	v_cmp_le_u32 vcc, v54, v165
	v_addc_co_u32 v55, vcc, 0, v55, vcc
	s_nop 0
	v_cmp_le_u32 vcc, v54, v164
	v_addc_co_u32 v55, vcc, 0, v55, vcc
	s_nop 0
	v_cmp_le_u32 vcc, v54, v163
	v_addc_co_u32 v55, vcc, 0, v55, vcc
	s_nop 0
	v_cmp_le_u32 vcc, v54, v162
	v_addc_co_u32 v55, vcc, 0, v55, vcc
	s_nop 0
	v_cmp_le_u32 vcc, v54, v141
	v_addc_co_u32 v55, vcc, 0, v55, vcc
	s_nop 0
	v_cmp_le_u32 vcc, v54, v140
	v_addc_co_u32 v55, vcc, 0, v55, vcc
	s_nop 0
	v_cmp_le_u32 vcc, v54, v139
	v_addc_co_u32 v55, vcc, 0, v55, vcc
	s_nop 0
	v_cmp_le_u32 vcc, v54, v138
	v_addc_co_u32 v55, vcc, 0, v55, vcc
	s_nop 0
	v_cmp_le_u32 vcc, v54, v137
	v_addc_co_u32 v55, vcc, 0, v55, vcc
	s_nop 0
	v_cmp_le_u32 vcc, v54, v136
	v_addc_co_u32 v55, vcc, 0, v55, vcc
	s_nop 0
	v_cmp_le_u32 vcc, v54, v135
	v_addc_co_u32 v55, vcc, 0, v55, vcc
	s_nop 0
	v_cmp_le_u32 vcc, v54, v134
	v_addc_co_u32 v55, vcc, 0, v55, vcc
	s_nop 0
	v_cmp_le_u32 vcc, v54, v132
	v_addc_co_u32 v55, vcc, 0, v55, vcc
	s_nop 0
	v_cmp_le_u32 vcc, v54, v130
	v_addc_co_u32 v55, vcc, 0, v55, vcc
	s_nop 0
	v_cmp_le_u32 vcc, v54, v133
	v_addc_co_u32 v55, vcc, 0, v55, vcc
	s_nop 0
	v_cmp_le_u32 vcc, v54, v131
	v_addc_co_u32 v55, vcc, 0, v55, vcc
	s_nop 0
	v_cmp_le_u32 vcc, v54, v128
	v_addc_co_u32 v55, vcc, 0, v55, vcc
	s_nop 0
	v_cmp_le_u32 vcc, v54, v129
	v_addc_co_u32 v55, vcc, 0, v55, vcc
	s_nop 0
	v_cmp_le_u32 vcc, v54, v62
	v_addc_co_u32 v55, vcc, 0, v55, vcc
	s_nop 0
	v_cmp_le_u32 vcc, v54, v58
	v_addc_co_u32 v55, vcc, 0, v55, vcc
	s_nop 0
	v_cmp_le_u32 vcc, v54, v56
	v_addc_co_u32 v55, vcc, 0, v55, vcc
	s_nop 0
	v_cmp_le_u32 vcc, v54, v52
	v_addc_co_u32 v55, vcc, 0, v55, vcc
	s_nop 0
	v_cmp_le_u32 vcc, v54, v50
	v_addc_co_u32 v55, vcc, 0, v55, vcc
	s_nop 0
	v_cmp_le_u32 vcc, v54, v49
	v_addc_co_u32 v55, vcc, 0, v55, vcc
	s_nop 0
	v_cmp_le_u32 vcc, v54, v48
	v_addc_co_u32 v55, vcc, 0, v55, vcc
	s_nop 0
	v_cmp_le_u32 vcc, v54, v51
	v_addc_co_u32 v55, vcc, 0, v55, vcc
	s_nop 0
	v_cmp_le_u32 vcc, v54, v47
	v_addc_co_u32 v55, vcc, 0, v55, vcc
	s_nop 0
	v_cmp_le_u32 vcc, v54, v46
	v_addc_co_u32 v55, vcc, 0, v55, vcc
	s_nop 0
	v_cmp_le_u32 vcc, v54, v45
	v_addc_co_u32 v55, vcc, 0, v55, vcc
	s_nop 0
	v_cmp_le_u32 vcc, v54, v44
	v_addc_co_u32 v55, vcc, 0, v55, vcc
	s_nop 0
	v_cmp_le_u32 vcc, v54, v43
	v_addc_co_u32 v55, vcc, 0, v55, vcc
	s_nop 0
	v_cmp_le_u32 vcc, v54, v42
	v_addc_co_u32 v55, vcc, 0, v55, vcc
	s_nop 0
	v_cmp_le_u32 vcc, v54, v41
	v_addc_co_u32 v55, vcc, 0, v55, vcc
	s_nop 0
	v_cmp_le_u32 vcc, v54, v40
	v_addc_co_u32 v55, vcc, 0, v55, vcc
	s_nop 0
	v_cmp_le_u32 vcc, v54, v39
	v_addc_co_u32 v55, vcc, 0, v55, vcc
	s_nop 0
	v_cmp_le_u32 vcc, v54, v38
	v_addc_co_u32 v55, vcc, 0, v55, vcc
	s_nop 0
	v_cmp_le_u32 vcc, v54, v37
	v_addc_co_u32 v55, vcc, 0, v55, vcc
	s_nop 0
	v_cmp_le_u32 vcc, v54, v36
	v_addc_co_u32 v55, vcc, 0, v55, vcc
	s_nop 0
	v_cmp_le_u32 vcc, v54, v35
	v_addc_co_u32 v55, vcc, 0, v55, vcc
	s_nop 0
	v_cmp_le_u32 vcc, v54, v0
	v_addc_co_u32 v55, vcc, 0, v55, vcc
	s_nop 1
	v_add_u32_dpp v55, v55, v55 quad_perm:[1,0,3,2] row_mask:0xf bank_mask:0xf bound_ctrl:1
	s_nop 1
	v_add_u32_dpp v55, v55, v55 quad_perm:[2,3,0,1] row_mask:0xf bank_mask:0xf bound_ctrl:1
	s_nop 1
	v_add_u32_dpp v55, v55, v55 row_half_mirror row_mask:0xf bank_mask:0xf bound_ctrl:1
	s_nop 1
	v_add_u32_dpp v55, v55, v55 row_mirror row_mask:0xf bank_mask:0xf bound_ctrl:1
	s_nop 0
	v_readlane_b32 s0, v55, 0
	v_readlane_b32 s1, v55, 16
	s_add_i32 s0, s1, s0
	v_readlane_b32 s1, v55, 32
	s_add_i32 s0, s0, s1
	v_readlane_b32 s1, v55, 48
	s_add_i32 s0, s0, s1
.Lp12_skip_2485:
	s_cmpk_gt_i32 s0, 0xff
	s_cselect_b64 vcc, -1, 0
	s_cmpk_eq_i32 s0, 0x100
	v_cndmask_b32_e32 v34, v34, v54, vcc
	s_cselect_b64 s[0:1], -1, 0
	v_subrev_co_u32_e32 v53, vcc, 1, v53
	s_or_b64 s[0:1], s[0:1], vcc
	s_andn2_b64 vcc, exec, s[0:1]
	s_cbranch_vccnz .LBB0_2485
	v_cmp_gt_u32_e32 vcc, v221, v34
	s_and_saveexec_b64 s[0:1], vcc
	s_nop 0
	v_mbcnt_lo_u32_b32 v53, vcc_lo, 0
	v_mbcnt_hi_u32_b32 v53, vcc_hi, v53
	v_lshl_add_u32 v53, v53, 2, s20
	ds_write_b32 v53, v2
	s_or_b64 exec, exec, s[0:1]
	s_bcnt1_i32_b64 s2, vcc
	v_cmp_gt_u32_e32 vcc, v220, v34
	s_and_saveexec_b64 s[0:1], vcc
	s_cbranch_execz .LBB0_2490
	s_lshl_b32 s3, s2, 2
	v_mbcnt_lo_u32_b32 v53, vcc_lo, 0
	s_add_i32 s3, s20, s3
	v_mbcnt_hi_u32_b32 v53, vcc_hi, v53
	v_lshl_add_u32 v53, v53, 2, s3
	ds_write_b32 v53, v4

; DI unsigned f2key(float f) { const unsigned u = __float_as_uint(f); return (u & 0x80000000u) ? ~u : (u | 0x80000000u); }
; template <int NV>
; DI void topk_row(const float* row, int s, LAS int* lst, int lane) {
;     ...
;     for (int jo = 0; jo < NV / 16; ++jo) { const float* rb = row + jo * 1024;
; #pragma unroll
;         for (int ji = 0; ji < 16; ++ji) { const int j = jo * 16 + ji; const unsigned u = f2key(rb[ji * 64 + lane]); key[j] = (j * 64 + lane <= s) ? u : 0u; } }
; DI void topk_phase(const float* SC, unsigned short* IDX, LAS unsigned char* lds, int tid, int bid, int G) {
;     ...
;             if (s < 2048) topk_row<32>(row, s, lst, lane);
;             else if (s < 4096) topk_row<64>(row, s, lst, lane);
.LBB0_2870:
	v_lshlrev_b32_e32 v0, 2, v2
	v_lshl_add_u64 v[40:41], s[12:13], 0, v[0:1]
	flat_load_dword v48, v[40:41]
	flat_load_dword v49, v[40:41] offset:256
	flat_load_dword v50, v[40:41] offset:512
	flat_load_dword v51, v[40:41] offset:768
	flat_load_dword v52, v[40:41] offset:1024
	flat_load_dword v53, v[40:41] offset:1280
	flat_load_dword v54, v[40:41] offset:1536
	flat_load_dword v55, v[40:41] offset:1792
	flat_load_dword v56, v[40:41] offset:2048
	flat_load_dword v57, v[40:41] offset:2304
	flat_load_dword v58, v[40:41] offset:2560
	flat_load_dword v59, v[40:41] offset:2816
	flat_load_dword v60, v[40:41] offset:3072
	flat_load_dword v128, v[40:41] offset:3328
	s_add_u32 s0, s12, 0x1000
	flat_load_dword v129, v[40:41] offset:3584
	flat_load_dword v130, v[40:41] offset:3840
	s_addc_u32 s1, s13, 0
	v_lshlrev_b32_e32 v38, 2, v4
	v_mov_b32_e32 v39, v1
	v_lshlrev_b32_e32 v36, 2, v6
	v_mov_b32_e32 v37, v1
	v_lshlrev_b32_e32 v34, 2, v8
	v_mov_b32_e32 v35, v1
	v_lshl_add_u64 v[40:41], s[0:1], 0, v[0:1]
	v_lshl_add_u64 v[42:43], s[0:1], 0, v[38:39]
	v_lshl_add_u64 v[44:45], s[0:1], 0, v[36:37]
	v_lshl_add_u64 v[46:47], s[0:1], 0, v[34:35]
	flat_load_dword v131, v[40:41]
	flat_load_dword v132, v[42:43]
	flat_load_dword v133, v[44:45]
	flat_load_dword v134, v[46:47]
	s_movk_i32 s2, 0x7ff
	s_waitcnt vmcnt(0) lgkmcnt(0)
	v_not_b32_e32 v40, v48
	v_or_b32_e32 v41, 0x80000000, v48
	v_cmp_gt_i32_e32 vcc, 0, v48
	v_not_b32_e32 v42, v49
	v_or_b32_e32 v43, 0x80000000, v49
	v_cndmask_b32_e32 v189, v41, v40, vcc
	v_cmp_gt_i32_e32 vcc, 0, v49
	v_not_b32_e32 v44, v50
	v_or_b32_e32 v45, 0x80000000, v50
	v_cndmask_b32_e32 v188, v43, v42, vcc
	v_cmp_gt_i32_e32 vcc, 0, v50
	v_not_b32_e32 v46, v51
	v_or_b32_e32 v47, 0x80000000, v51
	v_cndmask_b32_e32 v187, v45, v44, vcc
	v_cmp_gt_i32_e32 vcc, 0, v51
	v_not_b32_e32 v61, v52
	v_or_b32_e32 v62, 0x80000000, v52
	v_cndmask_b32_e32 v186, v47, v46, vcc
	v_cmp_gt_i32_e32 vcc, 0, v52
	v_not_b32_e32 v63, v53
	v_or_b32_e32 v135, 0x80000000, v53
	v_cndmask_b32_e32 v185, v62, v61, vcc
	v_cmp_gt_i32_e32 vcc, 0, v53
	v_not_b32_e32 v136, v54
	v_or_b32_e32 v137, 0x80000000, v54
	v_cndmask_b32_e32 v184, v135, v63, vcc
	v_cmp_gt_i32_e32 vcc, 0, v54
	v_not_b32_e32 v138, v55
	v_or_b32_e32 v139, 0x80000000, v55
	v_cndmask_b32_e32 v183, v137, v136, vcc
	v_cmp_gt_i32_e32 vcc, 0, v55
	v_not_b32_e32 v140, v56
	v_or_b32_e32 v141, 0x80000000, v56
	v_cndmask_b32_e32 v182, v139, v138, vcc
	v_cmp_gt_i32_e32 vcc, 0, v56
	v_not_b32_e32 v162, v57
	v_or_b32_e32 v163, 0x80000000, v57
	v_cndmask_b32_e32 v179, v141, v140, vcc
	v_cmp_gt_i32_e32 vcc, 0, v57
	v_not_b32_e32 v164, v58
	v_or_b32_e32 v165, 0x80000000, v58
	v_cndmask_b32_e32 v175, v163, v162, vcc
	v_cmp_gt_i32_e32 vcc, 0, v58
	v_lshlrev_b32_e32 v62, 2, v10
	v_mov_b32_e32 v63, v1
	v_not_b32_e32 v166, v59
	v_or_b32_e32 v167, 0x80000000, v59
	v_cndmask_b32_e32 v172, v165, v164, vcc
	v_cmp_gt_i32_e32 vcc, 0, v59
	v_lshl_add_u64 v[40:41], s[0:1], 0, v[62:63]
	v_not_b32_e32 v168, v60
	v_or_b32_e32 v169, 0x80000000, v60
	v_cndmask_b32_e32 v170, v167, v166, vcc
	v_cmp_gt_i32_e32 vcc, 0, v60
	flat_load_dword v135, v[40:41]
	v_lshlrev_b32_e32 v60, 2, v12
	v_mov_b32_e32 v61, v1
	v_lshl_add_u64 v[40:41], s[0:1], 0, v[60:61]
	v_lshlrev_b32_e32 v58, 2, v14
	v_mov_b32_e32 v59, v1
	flat_load_dword v136, v[40:41]
	v_lshl_add_u64 v[40:41], s[0:1], 0, v[58:59]
	v_lshlrev_b32_e32 v56, 2, v16
	v_mov_b32_e32 v57, v1
	flat_load_dword v137, v[40:41]
	v_lshl_add_u64 v[40:41], s[0:1], 0, v[56:57]
	flat_load_dword v138, v[40:41]
	v_lshlrev_b32_e32 v54, 2, v18
	v_mov_b32_e32 v55, v1
	v_lshl_add_u64 v[40:41], s[0:1], 0, v[54:55]
	flat_load_dword v139, v[40:41]
	v_lshlrev_b32_e32 v52, 2, v20
	v_mov_b32_e32 v53, v1
	v_lshl_add_u64 v[40:41], s[0:1], 0, v[52:53]
	v_lshlrev_b32_e32 v50, 2, v22
	v_mov_b32_e32 v51, v1
	flat_load_dword v140, v[40:41]
	v_lshl_add_u64 v[40:41], s[0:1], 0, v[50:51]
	v_lshlrev_b32_e32 v48, 2, v24
	v_mov_b32_e32 v49, v1
	v_cndmask_b32_e32 v167, v169, v168, vcc
	v_not_b32_e32 v42, v128
	v_or_b32_e32 v43, 0x80000000, v128
	v_cmp_gt_i32_e32 vcc, 0, v128
	flat_load_dword v141, v[40:41]
	v_lshl_add_u64 v[40:41], s[0:1], 0, v[48:49]
	v_lshlrev_b32_e32 v46, 2, v26
	v_mov_b32_e32 v47, v1
	v_cndmask_b32_e32 v169, v43, v42, vcc
	v_not_b32_e32 v42, v129
	v_or_b32_e32 v43, 0x80000000, v129
	v_cmp_gt_i32_e32 vcc, 0, v129
	flat_load_dword v162, v[40:41]
	v_lshl_add_u64 v[40:41], s[0:1], 0, v[46:47]
	v_cndmask_b32_e32 v174, v43, v42, vcc
	v_not_b32_e32 v42, v130
	v_or_b32_e32 v43, 0x80000000, v130
	flat_load_dword v190, v[40:41]
	v_lshlrev_b32_e32 v44, 2, v28
	v_mov_b32_e32 v45, v1
	v_cmp_gt_i32_e32 vcc, 0, v130
	v_lshl_add_u64 v[40:41], s[0:1], 0, v[44:45]
	flat_load_dword v191, v[40:41]
	v_cndmask_b32_e32 v178, v43, v42, vcc
	v_lshlrev_b32_e32 v42, 2, v30
	v_mov_b32_e32 v43, v1
	v_lshl_add_u64 v[40:41], s[0:1], 0, v[42:43]
	flat_load_dword v192, v[40:41]
	v_lshlrev_b32_e32 v40, 2, v32
	v_mov_b32_e32 v41, v1
	v_lshl_add_u64 v[128:129], s[0:1], 0, v[40:41]
	s_add_u32 s0, s12, 0x2000
	flat_load_dword v193, v[128:129]
	s_addc_u32 s1, s13, 0
	v_lshl_add_u64 v[128:129], s[0:1], 0, v[0:1]
	v_not_b32_e32 v130, v131
	v_or_b32_e32 v163, 0x80000000, v131
	flat_load_dword v194, v[128:129]
	v_cmp_gt_i32_e32 vcc, 0, v131
	v_not_b32_e32 v128, v132
	v_or_b32_e32 v129, 0x80000000, v132
	v_cndmask_b32_e32 v181, v163, v130, vcc
	v_cmp_gt_i32_e32 vcc, 0, v132
	v_not_b32_e32 v130, v133
	v_or_b32_e32 v132, 0x80000000, v134
	v_cndmask_b32_e32 v180, v129, v128, vcc
	v_lshl_add_u64 v[128:129], s[0:1], 0, v[38:39]
	flat_load_dword v131, v[128:129]
	v_or_b32_e32 v128, 0x80000000, v133
	v_cmp_gt_i32_e32 vcc, 0, v133
	s_nop 1
	v_cndmask_b32_e32 v177, v128, v130, vcc
	v_not_b32_e32 v130, v134
	v_lshl_add_u64 v[128:129], s[0:1], 0, v[36:37]
	v_cmp_gt_i32_e32 vcc, 0, v134
	flat_load_dword v133, v[128:129]
	s_waitcnt vmcnt(0) lgkmcnt(0)
; DI unsigned f2key(float f) { const unsigned u = __float_as_uint(f); return (u & 0x80000000u) ? ~u : (u | 0x80000000u); }
; template <int NV>
; DI void topk_row(const float* row, int s, LAS int* lst, int lane) {
;     ...
;     for (int jo = 0; jo < NV / 16; ++jo) { const float* rb = row + jo * 1024;
; #pragma unroll
;         for (int ji = 0; ji < 16; ++ji) { const int j = jo * 16 + ji; const unsigned u = f2key(rb[ji * 64 + lane]); key[j] = (j * 64 + lane <= s) ? u : 0u; } }
	v_not_b32_e32 v128, v135
	v_cndmask_b32_e32 v176, v132, v130, vcc
	v_or_b32_e32 v129, 0x80000000, v135
	v_cmp_gt_i32_e32 vcc, 0, v135
	v_not_b32_e32 v130, v136
	v_or_b32_e32 v134, 0x80000000, v137
	v_cndmask_b32_e32 v173, v129, v128, vcc
	v_lshl_add_u64 v[128:129], s[0:1], 0, v[34:35]
	flat_load_dword v132, v[128:129]
	v_or_b32_e32 v128, 0x80000000, v136
	v_cmp_gt_i32_e32 vcc, 0, v136
	s_nop 1
	v_cndmask_b32_e32 v171, v128, v130, vcc
	v_not_b32_e32 v130, v137
	v_lshl_add_u64 v[128:129], s[0:1], 0, v[62:63]
	v_cmp_gt_i32_e32 vcc, 0, v137
	flat_load_dword v195, v[128:129]
	v_not_b32_e32 v128, v138
	v_cndmask_b32_e32 v168, v134, v130, vcc
	v_or_b32_e32 v129, 0x80000000, v138
	v_cmp_gt_i32_e32 vcc, 0, v138
	v_not_b32_e32 v130, v139
	v_or_b32_e32 v134, 0x80000000, v140
	v_cndmask_b32_e32 v166, v129, v128, vcc
	v_lshl_add_u64 v[128:129], s[0:1], 0, v[60:61]
	flat_load_dword v196, v[128:129]
	v_or_b32_e32 v128, 0x80000000, v139
	v_cmp_gt_i32_e32 vcc, 0, v139
	s_nop 1
	v_cndmask_b32_e32 v165, v128, v130, vcc
	v_lshl_add_u64 v[128:129], s[0:1], 0, v[58:59]
	flat_load_dword v197, v[128:129]
	v_not_b32_e32 v130, v140
	v_cmp_gt_i32_e32 vcc, 0, v140
	v_not_b32_e32 v128, v141
	v_or_b32_e32 v129, 0x80000000, v141
	v_cndmask_b32_e32 v164, v134, v130, vcc
	v_cmp_gt_i32_e32 vcc, 0, v141
	v_not_b32_e32 v130, v162
	v_or_b32_e32 v134, 0x80000000, v162
	v_cndmask_b32_e32 v163, v129, v128, vcc
	v_lshl_add_u64 v[128:129], s[0:1], 0, v[56:57]
	v_cmp_gt_i32_e32 vcc, 0, v162
	flat_load_dword v198, v[128:129]
	v_not_b32_e32 v128, v190
	v_cndmask_b32_e32 v162, v134, v130, vcc
	v_or_b32_e32 v129, 0x80000000, v190
	v_cmp_gt_i32_e32 vcc, 0, v190
	v_not_b32_e32 v130, v191
	s_nop 0
	v_cndmask_b32_e32 v141, v129, v128, vcc
	v_lshl_add_u64 v[128:129], s[0:1], 0, v[54:55]
	flat_load_dword v190, v[128:129]
	v_or_b32_e32 v128, 0x80000000, v191
	v_cmp_gt_i32_e32 vcc, 0, v191
	s_nop 1
	v_cndmask_b32_e32 v140, v128, v130, vcc
	v_lshl_add_u64 v[128:129], s[0:1], 0, v[52:53]
	v_not_b32_e32 v130, v192
	flat_load_dword v191, v[128:129]
	v_or_b32_e32 v128, 0x80000000, v192
	v_cmp_gt_i32_e32 vcc, 0, v192
	v_or_b32_e32 v129, 0x80000000, v193
	s_nop 0
	v_cndmask_b32_e32 v139, v128, v130, vcc
	v_not_b32_e32 v128, v193
	v_cmp_gt_i32_e32 vcc, 0, v193
	v_not_b32_e32 v130, v194
	s_nop 0
	v_cndmask_b32_e32 v138, v129, v128, vcc
	v_lshl_add_u64 v[128:129], s[0:1], 0, v[50:51]
	flat_load_dword v192, v[128:129]
	v_or_b32_e32 v128, 0x80000000, v194
	v_cmp_gt_i32_e32 vcc, 0, v194
	s_nop 1
	v_cndmask_b32_e32 v128, v128, v130, vcc
	v_cmp_lt_u32_e32 vcc, s2, v161
	v_not_b32_e32 v130, v131
	s_movk_i32 s2, 0x83f
	v_cndmask_b32_e32 v137, 0, v128, vcc
	v_lshl_add_u64 v[128:129], s[0:1], 0, v[48:49]
	flat_load_dword v193, v[128:129]
	v_or_b32_e32 v128, 0x80000000, v131
	v_cmp_gt_i32_e32 vcc, 0, v131
	v_or_b32_e32 v131, 0x80000000, v133
	s_nop 0
	v_cndmask_b32_e32 v128, v128, v130, vcc
	v_cmp_lt_u32_e32 vcc, s2, v161
	v_not_b32_e32 v130, v133
	s_movk_i32 s2, 0x87f
	v_cndmask_b32_e32 v136, 0, v128, vcc
	v_lshl_add_u64 v[128:129], s[0:1], 0, v[46:47]
	flat_load_dword v194, v[128:129]
	v_cmp_gt_i32_e32 vcc, 0, v133
	s_nop 1
	v_cndmask_b32_e32 v128, v131, v130, vcc
	v_cmp_lt_u32_e32 vcc, s2, v161
	s_waitcnt vmcnt(0) lgkmcnt(0)
	v_not_b32_e32 v130, v132
	v_or_b32_e32 v131, 0x80000000, v132
	v_cndmask_b32_e32 v135, 0, v128, vcc
	v_lshl_add_u64 v[128:129], s[0:1], 0, v[44:45]
	v_cmp_gt_i32_e32 vcc, 0, v132
	s_movk_i32 s2, 0x8bf
	flat_load_dword v199, v[128:129]
	v_cndmask_b32_e32 v128, v131, v130, vcc
	v_cmp_lt_u32_e32 vcc, s2, v161
	v_or_b32_e32 v129, 0x80000000, v195
	s_movk_i32 s2, 0x8ff
	v_cndmask_b32_e32 v134, 0, v128, vcc
	v_not_b32_e32 v128, v195
	v_cmp_gt_i32_e32 vcc, 0, v195
	s_nop 1
	v_cndmask_b32_e32 v130, v129, v128, vcc
	v_lshl_add_u64 v[128:129], s[0:1], 0, v[42:43]
	v_cmp_lt_u32_e32 vcc, s2, v161
	flat_load_dword v195, v[128:129]
	v_not_b32_e32 v128, v196
	v_cndmask_b32_e32 v133, 0, v130, vcc
	v_or_b32_e32 v129, 0x80000000, v196
	v_cmp_gt_i32_e32 vcc, 0, v196
	s_nop 1
	v_cndmask_b32_e32 v130, v129, v128, vcc
	v_lshl_add_u64 v[128:129], s[0:1], 0, v[40:41]
	s_movk_i32 s0, 0x93f
	v_cmp_lt_u32_e32 vcc, s0, v161
	s_add_u32 s0, s12, 0x3000
	flat_load_dword v196, v[128:129]
	s_addc_u32 s1, s13, 0
	v_lshl_add_u64 v[38:39], s[0:1], 0, v[38:39]
	v_cndmask_b32_e32 v131, 0, v130, vcc
	v_cmp_gt_i32_e32 vcc, 0, v197
	flat_load_dword v38, v[38:39]
	v_not_b32_e32 v128, v197
	v_or_b32_e32 v129, 0x80000000, v197
	v_cndmask_b32_e32 v130, v129, v128, vcc
	v_lshl_add_u64 v[128:129], s[0:1], 0, v[0:1]
	flat_load_dword v0, v[128:129]
	v_cmp_lt_u32_e32 vcc, s22, v161
	v_not_b32_e32 v128, v198
	v_or_b32_e32 v129, 0x80000000, v198
	v_cndmask_b32_e32 v132, 0, v130, vcc
	v_cmp_gt_i32_e32 vcc, 0, v198
	v_lshl_add_u64 v[36:37], s[0:1], 0, v[36:37]
	flat_load_dword v36, v[36:37]
	v_cndmask_b32_e32 v128, v129, v128, vcc
	v_cmp_lt_u32_e32 vcc, s23, v161
	v_not_b32_e32 v39, v190
	v_or_b32_e32 v37, 0x80000000, v191
	v_cndmask_b32_e32 v130, 0, v128, vcc
	v_or_b32_e32 v128, 0x80000000, v190
	v_cmp_gt_i32_e32 vcc, 0, v190
	v_lshl_add_u64 v[34:35], s[0:1], 0, v[34:35]
	v_or_b32_e32 v190, 0x80000000, v192
	v_cndmask_b32_e32 v39, v128, v39, vcc
	v_cmp_lt_u32_e32 vcc, s24, v161
	s_nop 1
	v_cndmask_b32_e32 v128, 0, v39, vcc
	v_not_b32_e32 v39, v191
	v_cmp_gt_i32_e32 vcc, 0, v191
	s_nop 1
	v_cndmask_b32_e32 v37, v37, v39, vcc
	flat_load_dword v39, v[34:35]
	v_cmp_lt_u32_e32 vcc, s25, v161
	v_lshl_add_u64 v[34:35], s[0:1], 0, v[62:63]
	flat_load_dword v63, v[34:35]
	v_cndmask_b32_e32 v129, 0, v37, vcc
	v_not_b32_e32 v37, v192
	v_cmp_gt_i32_e32 vcc, 0, v192
	s_nop 1
	v_cndmask_b32_e32 v34, v190, v37, vcc
	v_cmp_lt_u32_e32 vcc, s26, v161
	v_not_b32_e32 v37, v193
	s_nop 0
	v_cndmask_b32_e32 v62, 0, v34, vcc
	v_lshl_add_u64 v[34:35], s[0:1], 0, v[60:61]
	flat_load_dword v60, v[34:35]
	v_or_b32_e32 v34, 0x80000000, v193
	v_cmp_gt_i32_e32 vcc, 0, v193
	v_or_b32_e32 v61, 0x80000000, v194
	s_nop 0
	v_cndmask_b32_e32 v37, v34, v37, vcc
	v_lshl_add_u64 v[34:35], s[0:1], 0, v[58:59]
	flat_load_dword v59, v[34:35]
	v_cmp_lt_u32_e32 vcc, s27, v161
	v_lshl_add_u64 v[34:35], s[0:1], 0, v[56:57]
	flat_load_dword v57, v[34:35]
	v_cndmask_b32_e32 v58, 0, v37, vcc
	v_not_b32_e32 v37, v194
	v_cmp_gt_i32_e32 vcc, 0, v194
	s_nop 1
	v_cndmask_b32_e32 v34, v61, v37, vcc
	v_cmp_lt_u32_e32 vcc, s28, v161
	s_waitcnt vmcnt(0) lgkmcnt(0)
; DI unsigned f2key(float f) { const unsigned u = __float_as_uint(f); return (u & 0x80000000u) ? ~u : (u | 0x80000000u); }
; template <int NV>
; DI void topk_row(const float* row, int s, LAS int* lst, int lane) {
;     ...
;     for (int jo = 0; jo < NV / 16; ++jo) { const float* rb = row + jo * 1024;
; #pragma unroll
;         for (int ji = 0; ji < 16; ++ji) { const int j = jo * 16 + ji; const unsigned u = f2key(rb[ji * 64 + lane]); key[j] = (j * 64 + lane <= s) ? u : 0u; } }
;     unsigned T = 0u;
; #pragma unroll 1
	v_not_b32_e32 v37, v199
	v_cndmask_b32_e32 v56, 0, v34, vcc
	v_lshl_add_u64 v[34:35], s[0:1], 0, v[54:55]
	flat_load_dword v54, v[34:35]
	v_or_b32_e32 v34, 0x80000000, v199
	v_cmp_gt_i32_e32 vcc, 0, v199
	v_or_b32_e32 v55, 0x80000000, v195
	s_nop 0
	v_cndmask_b32_e32 v37, v34, v37, vcc
	v_lshl_add_u64 v[34:35], s[0:1], 0, v[52:53]
	flat_load_dword v53, v[34:35]
	v_cmp_lt_u32_e32 vcc, s29, v161
	v_lshl_add_u64 v[34:35], s[0:1], 0, v[50:51]
	flat_load_dword v61, v[34:35]
	v_cndmask_b32_e32 v52, 0, v37, vcc
	v_not_b32_e32 v37, v195
	v_cmp_gt_i32_e32 vcc, 0, v195
	s_nop 1
	v_cndmask_b32_e32 v34, v55, v37, vcc
	v_cmp_lt_u32_e32 vcc, s30, v161
	v_not_b32_e32 v37, v196
	s_nop 0
	v_cndmask_b32_e32 v50, 0, v34, vcc
	v_lshl_add_u64 v[34:35], s[0:1], 0, v[48:49]
	flat_load_dword v55, v[34:35]
	v_or_b32_e32 v34, 0x80000000, v196
	v_cmp_gt_i32_e32 vcc, 0, v196
	s_nop 1
	v_cndmask_b32_e32 v37, v34, v37, vcc
	v_lshl_add_u64 v[34:35], s[0:1], 0, v[46:47]
	flat_load_dword v190, v[34:35]
	v_cmp_lt_u32_e32 vcc, s31, v161
	v_lshl_add_u64 v[34:35], s[0:1], 0, v[44:45]
	v_or_b32_e32 v46, 0x80000000, v0
	v_cndmask_b32_e32 v49, 0, v37, vcc
	v_not_b32_e32 v37, v0
	flat_load_dword v191, v[34:35]
	v_cmp_gt_i32_e32 vcc, 0, v0
	v_lshl_add_u64 v[34:35], s[0:1], 0, v[42:43]
	flat_load_dword v192, v[34:35]
	v_cndmask_b32_e32 v0, v46, v37, vcc
	v_cmp_lt_u32_e32 vcc, s36, v161
	v_or_b32_e32 v34, 0x80000000, v38
	s_nop 0
	v_cndmask_b32_e32 v48, 0, v0, vcc
	v_not_b32_e32 v0, v38
	v_cmp_gt_i32_e32 vcc, 0, v38
	s_nop 1
	v_cndmask_b32_e32 v0, v34, v0, vcc
	v_lshl_add_u64 v[34:35], s[0:1], 0, v[40:41]
	flat_load_dword v34, v[34:35]
	v_cmp_lt_u32_e32 vcc, s37, v161
	v_or_b32_e32 v35, 0x80000000, v36
	s_nop 0
	v_cndmask_b32_e32 v51, 0, v0, vcc
	v_not_b32_e32 v0, v36
	v_cmp_gt_i32_e32 vcc, 0, v36
	s_nop 1
	v_cndmask_b32_e32 v0, v35, v0, vcc
	v_cmp_lt_u32_e32 vcc, s38, v161
	v_or_b32_e32 v35, 0x80000000, v39
	s_nop 0
	v_cndmask_b32_e32 v47, 0, v0, vcc
	v_not_b32_e32 v0, v39
	v_cmp_gt_i32_e32 vcc, 0, v39
	s_nop 1
	v_cndmask_b32_e32 v0, v35, v0, vcc
	v_cmp_lt_u32_e32 vcc, s39, v161
	v_or_b32_e32 v35, 0x80000000, v63
	s_nop 0
	v_cndmask_b32_e32 v46, 0, v0, vcc
	v_not_b32_e32 v0, v63
	v_cmp_gt_i32_e32 vcc, 0, v63
	s_nop 1
	v_cndmask_b32_e32 v0, v35, v0, vcc
	v_cmp_lt_u32_e32 vcc, s40, v161
	v_or_b32_e32 v35, 0x80000000, v60
	s_nop 0
	v_cndmask_b32_e32 v45, 0, v0, vcc
	v_not_b32_e32 v0, v60
	v_cmp_gt_i32_e32 vcc, 0, v60
	s_nop 1
	v_cndmask_b32_e32 v0, v35, v0, vcc
	v_cmp_lt_u32_e32 vcc, s41, v161
	v_or_b32_e32 v35, 0x80000000, v59
	s_nop 0
	v_cndmask_b32_e32 v44, 0, v0, vcc
	v_not_b32_e32 v0, v59
	v_cmp_gt_i32_e32 vcc, 0, v59
	s_nop 1
	v_cndmask_b32_e32 v0, v35, v0, vcc
	v_cmp_lt_u32_e32 vcc, s42, v161
	v_or_b32_e32 v35, 0x80000000, v57
	s_nop 0
	v_cndmask_b32_e32 v43, 0, v0, vcc
	v_not_b32_e32 v0, v57
	v_cmp_gt_i32_e32 vcc, 0, v57
	s_nop 1
	v_cndmask_b32_e32 v0, v35, v0, vcc
	v_cmp_lt_u32_e32 vcc, s43, v161
	s_waitcnt vmcnt(0) lgkmcnt(0)
	v_or_b32_e32 v35, 0x80000000, v54
	v_cndmask_b32_e32 v42, 0, v0, vcc
	v_not_b32_e32 v0, v54
	v_cmp_gt_i32_e32 vcc, 0, v54
	s_nop 1
	v_cndmask_b32_e32 v0, v35, v0, vcc
	v_cmp_lt_u32_e32 vcc, s44, v161
	v_or_b32_e32 v35, 0x80000000, v53
	s_nop 0
	v_cndmask_b32_e32 v41, 0, v0, vcc
	v_not_b32_e32 v0, v53
	v_cmp_gt_i32_e32 vcc, 0, v53
	v_or_b32_e32 v53, 0x80000000, v34
	s_nop 0
	v_cndmask_b32_e32 v0, v35, v0, vcc
	v_cmp_lt_u32_e32 vcc, s45, v161
	v_or_b32_e32 v35, 0x80000000, v61
	s_nop 0
	v_cndmask_b32_e32 v40, 0, v0, vcc
	v_not_b32_e32 v0, v61
	v_cmp_gt_i32_e32 vcc, 0, v61
	s_nop 1
	v_cndmask_b32_e32 v0, v35, v0, vcc
	v_cmp_lt_u32_e32 vcc, s46, v161
	v_or_b32_e32 v35, 0x80000000, v55
	s_nop 0
	v_cndmask_b32_e32 v39, 0, v0, vcc
	v_not_b32_e32 v0, v55
	v_cmp_gt_i32_e32 vcc, 0, v55
	s_nop 1
	v_cndmask_b32_e32 v0, v35, v0, vcc
	v_cmp_lt_u32_e32 vcc, s47, v161
	v_or_b32_e32 v35, 0x80000000, v190
	s_nop 0
	v_cndmask_b32_e32 v38, 0, v0, vcc
	v_not_b32_e32 v0, v190
	v_cmp_gt_i32_e32 vcc, 0, v190
	s_nop 1
	v_cndmask_b32_e32 v0, v35, v0, vcc
	v_cmp_lt_u32_e32 vcc, s48, v161
	v_or_b32_e32 v35, 0x80000000, v191
	s_nop 0
	v_cndmask_b32_e32 v37, 0, v0, vcc
	v_not_b32_e32 v0, v191
	v_cmp_gt_i32_e32 vcc, 0, v191
	s_nop 1
	v_cndmask_b32_e32 v0, v35, v0, vcc
	v_cmp_lt_u32_e32 vcc, s49, v161
	v_or_b32_e32 v35, 0x80000000, v192
	s_nop 0
	v_cndmask_b32_e32 v36, 0, v0, vcc
	v_not_b32_e32 v0, v192
	v_cmp_gt_i32_e32 vcc, 0, v192
	s_nop 1
	v_cndmask_b32_e32 v0, v35, v0, vcc
	v_cmp_lt_u32_e32 vcc, s50, v161
	s_nop 1
	v_cndmask_b32_e32 v35, 0, v0, vcc
	v_not_b32_e32 v0, v34
	v_cmp_gt_i32_e32 vcc, 0, v34
	v_mov_b32_e32 v34, 0
	s_nop 0
	v_cndmask_b32_e32 v0, v53, v0, vcc
	v_cmp_lt_u32_e32 vcc, s51, v161
	v_mov_b32_e32 v53, 31
	s_nop 0
	v_cndmask_b32_e32 v0, 0, v0, vcc
	v_max_u32_e32 v255, v189, v188
	v_max_u32_e32 v255, v255, v187
	v_max_u32_e32 v255, v255, v186
	v_max_u32_e32 v255, v255, v185
	v_max_u32_e32 v255, v255, v184
	v_max_u32_e32 v255, v255, v183
	v_max_u32_e32 v255, v255, v182
	v_max_u32_e32 v255, v255, v179
	v_max_u32_e32 v255, v255, v175
	v_max_u32_e32 v255, v255, v172
	v_max_u32_e32 v255, v255, v170
	v_max_u32_e32 v255, v255, v167
	v_max_u32_e32 v255, v255, v169
	v_max_u32_e32 v255, v255, v174
	v_max_u32_e32 v255, v255, v178
	v_max_u32_e32 v255, v255, v181
	v_max_u32_e32 v255, v255, v180
	v_max_u32_e32 v255, v255, v177
	v_max_u32_e32 v255, v255, v176
	v_max_u32_e32 v255, v255, v173
	v_max_u32_e32 v255, v255, v171
	v_max_u32_e32 v255, v255, v168
	v_max_u32_e32 v255, v255, v166
	v_max_u32_e32 v255, v255, v165
	v_max_u32_e32 v255, v255, v164
	v_max_u32_e32 v255, v255, v163
	v_max_u32_e32 v255, v255, v162
	v_max_u32_e32 v255, v255, v141
	v_max_u32_e32 v255, v255, v140
; DI unsigned f2key(float f) { const unsigned u = __float_as_uint(f); return (u & 0x80000000u) ? ~u : (u | 0x80000000u); }
; template <int NV>
; DI void topk_row(const float* row, int s, LAS int* lst, int lane) {
;     ...
;     for (int jo = 0; jo < NV / 16; ++jo) { const float* rb = row + jo * 1024;
; #pragma unroll
;         for (int ji = 0; ji < 16; ++ji) { const int j = jo * 16 + ji; const unsigned u = f2key(rb[ji * 64 + lane]); key[j] = (j * 64 + lane <= s) ? u : 0u; } }
;     unsigned T = 0u;
; #pragma unroll 1
	v_max_u32_e32 v255, v255, v139
	v_max_u32_e32 v255, v255, v138
	v_max_u32_e32 v255, v255, v137
	v_max_u32_e32 v255, v255, v136
	v_max_u32_e32 v255, v255, v135
	v_max_u32_e32 v255, v255, v134
	v_max_u32_e32 v255, v255, v133
	v_max_u32_e32 v255, v255, v131
	v_max_u32_e32 v255, v255, v132
	v_max_u32_e32 v255, v255, v130
	v_max_u32_e32 v255, v255, v128
	v_max_u32_e32 v255, v255, v129
	v_max_u32_e32 v255, v255, v62
	v_max_u32_e32 v255, v255, v58
	v_max_u32_e32 v255, v255, v56
	v_max_u32_e32 v255, v255, v52
	v_max_u32_e32 v255, v255, v50
	v_max_u32_e32 v255, v255, v49
	v_max_u32_e32 v255, v255, v48
	v_max_u32_e32 v255, v255, v51
	v_max_u32_e32 v255, v255, v47
	v_max_u32_e32 v255, v255, v46
	v_max_u32_e32 v255, v255, v45
	v_max_u32_e32 v255, v255, v44
	v_max_u32_e32 v255, v255, v43
	v_max_u32_e32 v255, v255, v42
	v_max_u32_e32 v255, v255, v41
	v_max_u32_e32 v255, v255, v40
	v_max_u32_e32 v255, v255, v39
	v_max_u32_e32 v255, v255, v38
	v_max_u32_e32 v255, v255, v37
	v_max_u32_e32 v255, v255, v36
	v_max_u32_e32 v255, v255, v35
	v_max_u32_e32 v255, v255, v0
	s_nop 1
	v_max_u32_dpp v255, v255, v255 quad_perm:[1,0,3,2] row_mask:0xf bank_mask:0xf bound_ctrl:1
	s_nop 1
	v_max_u32_dpp v255, v255, v255 quad_perm:[2,3,0,1] row_mask:0xf bank_mask:0xf bound_ctrl:1
	s_nop 1
	v_max_u32_dpp v255, v255, v255 row_half_mirror row_mask:0xf bank_mask:0xf bound_ctrl:1
	s_nop 1
	v_max_u32_dpp v255, v255, v255 row_mirror row_mask:0xf bank_mask:0xf bound_ctrl:1
	s_nop 0
	v_readlane_b32 s99, v255, 0
	v_readlane_b32 s100, v255, 16
	s_max_u32 s99, s99, s100
	v_readlane_b32 s100, v255, 32
	s_max_u32 s99, s99, s100
	v_readlane_b32 s100, v255, 48
	s_max_u32 s99, s99, s100
; DI unsigned mbcnt64(unsigned long long m) { return __builtin_amdgcn_mbcnt_hi((unsigned)(m >> 32), __builtin_amdgcn_mbcnt_lo((unsigned)m, 0u)); }
; template <int NV>
; DI void topk_row(const float* row, int s, LAS int* lst, int lane) {
;     ...
; #pragma unroll 1
;     ...
;         const unsigned cand = T | (1u << bit); int c = 0;
; #pragma unroll
;         for (int j = 0; j < NV; ++j) asm volatile("v_cmp_le_u32 vcc, %2, %1\n\tv_addc_co_u32 %0, vcc, 0, %0, vcc" : "+v"(c) : "v"(key[j]), "s"(cand) : "vcc");
;         const int tot = wave_sum_i(c);
;         if (tot >= 256) T = cand;
;         if (tot == 256) break;
;     }
;     int bgt = 0;
; #pragma unroll
;     for (int j = 0; j < NV; ++j) { const bool sg = key[j] > T; const unsigned long long mg = __ballot(sg); if (sg) lst[bgt + (int)mbcnt64(mg)] = j * 64 + lane; bgt += __builtin_popcountll(mg); }
.LBB0_2871:
	v_lshlrev_b32_e64 v54, v53, 1
	v_mov_b32_e32 v55, 0
	v_or_b32_e32 v54, v54, v34
	s_nop 0
	v_readfirstlane_b32 s100, v54
	s_mov_b32 s0, 0
	s_cmp_gt_u32 s100, s99
	s_cbranch_scc1 .Lp12_skip_2871
	v_cmp_le_u32 vcc, v54, v189
	v_addc_co_u32 v55, vcc, 0, v55, vcc
	s_nop 0
	v_cmp_le_u32 vcc, v54, v188
	v_addc_co_u32 v55, vcc, 0, v55, vcc
	s_nop 0
	v_cmp_le_u32 vcc, v54, v187
	v_addc_co_u32 v55, vcc, 0, v55, vcc
	s_nop 0
	v_cmp_le_u32 vcc, v54, v186
	v_addc_co_u32 v55, vcc, 0, v55, vcc
	s_nop 0
	v_cmp_le_u32 vcc, v54, v185
	v_addc_co_u32 v55, vcc, 0, v55, vcc
	s_nop 0
	v_cmp_le_u32 vcc, v54, v184
	v_addc_co_u32 v55, vcc, 0, v55, vcc
	s_nop 0
	v_cmp_le_u32 vcc, v54, v183
	v_addc_co_u32 v55, vcc, 0, v55, vcc
	s_nop 0
	v_cmp_le_u32 vcc, v54, v182
	v_addc_co_u32 v55, vcc, 0, v55, vcc
	s_nop 0
	v_cmp_le_u32 vcc, v54, v179
	v_addc_co_u32 v55, vcc, 0, v55, vcc
	s_nop 0
	v_cmp_le_u32 vcc, v54, v175
	v_addc_co_u32 v55, vcc, 0, v55, vcc
	s_nop 0
	v_cmp_le_u32 vcc, v54, v172
	v_addc_co_u32 v55, vcc, 0, v55, vcc
	s_nop 0
	v_cmp_le_u32 vcc, v54, v170
	v_addc_co_u32 v55, vcc, 0, v55, vcc
	s_nop 0
	v_cmp_le_u32 vcc, v54, v167
	v_addc_co_u32 v55, vcc, 0, v55, vcc
	s_nop 0
	v_cmp_le_u32 vcc, v54, v169
	v_addc_co_u32 v55, vcc, 0, v55, vcc
	s_nop 0
	v_cmp_le_u32 vcc, v54, v174
	v_addc_co_u32 v55, vcc, 0, v55, vcc
	s_nop 0
	v_cmp_le_u32 vcc, v54, v178
	v_addc_co_u32 v55, vcc, 0, v55, vcc
	s_nop 0
	v_cmp_le_u32 vcc, v54, v181
	v_addc_co_u32 v55, vcc, 0, v55, vcc
	s_nop 0
	v_cmp_le_u32 vcc, v54, v180
	v_addc_co_u32 v55, vcc, 0, v55, vcc
	s_nop 0
	v_cmp_le_u32 vcc, v54, v177
	v_addc_co_u32 v55, vcc, 0, v55, vcc
	s_nop 0
	v_cmp_le_u32 vcc, v54, v176
	v_addc_co_u32 v55, vcc, 0, v55, vcc
	s_nop 0
	v_cmp_le_u32 vcc, v54, v173
	v_addc_co_u32 v55, vcc, 0, v55, vcc
	s_nop 0
	v_cmp_le_u32 vcc, v54, v171
	v_addc_co_u32 v55, vcc, 0, v55, vcc
	s_nop 0
	v_cmp_le_u32 vcc, v54, v168
	v_addc_co_u32 v55, vcc, 0, v55, vcc
	s_nop 0
	v_cmp_le_u32 vcc, v54, v166
	v_addc_co_u32 v55, vcc, 0, v55, vcc
	s_nop 0
	v_cmp_le_u32 vcc, v54, v165
	v_addc_co_u32 v55, vcc, 0, v55, vcc
	s_nop 0
	v_cmp_le_u32 vcc, v54, v164
	v_addc_co_u32 v55, vcc, 0, v55, vcc
	s_nop 0
	v_cmp_le_u32 vcc, v54, v163
	v_addc_co_u32 v55, vcc, 0, v55, vcc
	s_nop 0
	v_cmp_le_u32 vcc, v54, v162
	v_addc_co_u32 v55, vcc, 0, v55, vcc
	s_nop 0
	v_cmp_le_u32 vcc, v54, v141
	v_addc_co_u32 v55, vcc, 0, v55, vcc
	s_nop 0
	v_cmp_le_u32 vcc, v54, v140
	v_addc_co_u32 v55, vcc, 0, v55, vcc
	s_nop 0
	v_cmp_le_u32 vcc, v54, v139
	v_addc_co_u32 v55, vcc, 0, v55, vcc
	s_nop 0
	v_cmp_le_u32 vcc, v54, v138
	v_addc_co_u32 v55, vcc, 0, v55, vcc
	s_nop 0
	v_cmp_le_u32 vcc, v54, v137
	v_addc_co_u32 v55, vcc, 0, v55, vcc
	s_nop 0
	v_cmp_le_u32 vcc, v54, v136
	v_addc_co_u32 v55, vcc, 0, v55, vcc
	s_nop 0
	v_cmp_le_u32 vcc, v54, v135
	v_addc_co_u32 v55, vcc, 0, v55, vcc
	s_nop 0
	v_cmp_le_u32 vcc, v54, v134
	v_addc_co_u32 v55, vcc, 0, v55, vcc
	s_nop 0
	v_cmp_le_u32 vcc, v54, v133
	v_addc_co_u32 v55, vcc, 0, v55, vcc
	s_nop 0
	v_cmp_le_u32 vcc, v54, v131
	v_addc_co_u32 v55, vcc, 0, v55, vcc
	s_nop 0
	v_cmp_le_u32 vcc, v54, v132
	v_addc_co_u32 v55, vcc, 0, v55, vcc
	s_nop 0
	v_cmp_le_u32 vcc, v54, v130
	v_addc_co_u32 v55, vcc, 0, v55, vcc
	s_nop 0
	v_cmp_le_u32 vcc, v54, v128
	v_addc_co_u32 v55, vcc, 0, v55, vcc
	s_nop 0
	v_cmp_le_u32 vcc, v54, v129
	v_addc_co_u32 v55, vcc, 0, v55, vcc
	s_nop 0
	v_cmp_le_u32 vcc, v54, v62
	v_addc_co_u32 v55, vcc, 0, v55, vcc
	s_nop 0
	v_cmp_le_u32 vcc, v54, v58
	v_addc_co_u32 v55, vcc, 0, v55, vcc
	s_nop 0
	v_cmp_le_u32 vcc, v54, v56
	v_addc_co_u32 v55, vcc, 0, v55, vcc
	s_nop 0
	v_cmp_le_u32 vcc, v54, v52
	v_addc_co_u32 v55, vcc, 0, v55, vcc
	s_nop 0
	v_cmp_le_u32 vcc, v54, v50
	v_addc_co_u32 v55, vcc, 0, v55, vcc
	s_nop 0
	v_cmp_le_u32 vcc, v54, v49
	v_addc_co_u32 v55, vcc, 0, v55, vcc
	s_nop 0
	v_cmp_le_u32 vcc, v54, v48
	v_addc_co_u32 v55, vcc, 0, v55, vcc
	s_nop 0
	v_cmp_le_u32 vcc, v54, v51
	v_addc_co_u32 v55, vcc, 0, v55, vcc
	s_nop 0
	v_cmp_le_u32 vcc, v54, v47
	v_addc_co_u32 v55, vcc, 0, v55, vcc
	s_nop 0
	v_cmp_le_u32 vcc, v54, v46
	v_addc_co_u32 v55, vcc, 0, v55, vcc
	s_nop 0
	v_cmp_le_u32 vcc, v54, v45
	v_addc_co_u32 v55, vcc, 0, v55, vcc
	s_nop 0
	v_cmp_le_u32 vcc, v54, v44
	v_addc_co_u32 v55, vcc, 0, v55, vcc
	s_nop 0
	v_cmp_le_u32 vcc, v54, v43
	v_addc_co_u32 v55, vcc, 0, v55, vcc
	s_nop 0
	v_cmp_le_u32 vcc, v54, v42
	v_addc_co_u32 v55, vcc, 0, v55, vcc
	s_nop 0
	v_cmp_le_u32 vcc, v54, v41
	v_addc_co_u32 v55, vcc, 0, v55, vcc
	s_nop 0
	v_cmp_le_u32 vcc, v54, v40
	v_addc_co_u32 v55, vcc, 0, v55, vcc
	s_nop 0
	v_cmp_le_u32 vcc, v54, v39
	v_addc_co_u32 v55, vcc, 0, v55, vcc
	s_nop 0
	v_cmp_le_u32 vcc, v54, v38
	v_addc_co_u32 v55, vcc, 0, v55, vcc
	s_nop 0
	v_cmp_le_u32 vcc, v54, v37
	v_addc_co_u32 v55, vcc, 0, v55, vcc
	s_nop 0
	v_cmp_le_u32 vcc, v54, v36
	v_addc_co_u32 v55, vcc, 0, v55, vcc
	s_nop 0
	v_cmp_le_u32 vcc, v54, v35
	v_addc_co_u32 v55, vcc, 0, v55, vcc
	s_nop 0
	v_cmp_le_u32 vcc, v54, v0
	v_addc_co_u32 v55, vcc, 0, v55, vcc
	s_nop 1
	v_add_u32_dpp v55, v55, v55 quad_perm:[1,0,3,2] row_mask:0xf bank_mask:0xf bound_ctrl:1
	s_nop 1
	v_add_u32_dpp v55, v55, v55 quad_perm:[2,3,0,1] row_mask:0xf bank_mask:0xf bound_ctrl:1
	s_nop 1
	v_add_u32_dpp v55, v55, v55 row_half_mirror row_mask:0xf bank_mask:0xf bound_ctrl:1
	s_nop 1
	v_add_u32_dpp v55, v55, v55 row_mirror row_mask:0xf bank_mask:0xf bound_ctrl:1
	s_nop 0
	v_readlane_b32 s0, v55, 0
	v_readlane_b32 s1, v55, 16
	s_add_i32 s0, s1, s0
	v_readlane_b32 s1, v55, 32
	s_add_i32 s0, s0, s1
	v_readlane_b32 s1, v55, 48
	s_add_i32 s0, s0, s1
.Lp12_skip_2871:
	s_cmpk_gt_i32 s0, 0xff
	s_cselect_b64 vcc, -1, 0
	s_cmpk_eq_i32 s0, 0x100
	v_cndmask_b32_e32 v34, v34, v54, vcc
	s_cselect_b64 s[0:1], -1, 0
	v_subrev_co_u32_e32 v53, vcc, 1, v53
	s_or_b64 s[0:1], s[0:1], vcc
	s_andn2_b64 vcc, exec, s[0:1]
	s_cbranch_vccnz .LBB0_2871
	v_cmp_gt_u32_e32 vcc, v189, v34
	s_and_saveexec_b64 s[0:1], vcc
	s_nop 0
	v_mbcnt_lo_u32_b32 v53, vcc_lo, 0
	v_mbcnt_hi_u32_b32 v53, vcc_hi, v53
	v_lshl_add_u32 v53, v53, 2, s20
	ds_write_b32 v53, v2
	s_or_b64 exec, exec, s[0:1]
	s_bcnt1_i32_b64 s2, vcc
	v_cmp_gt_u32_e32 vcc, v188, v34
	s_and_saveexec_b64 s[0:1], vcc
	s_cbranch_execz .LBB0_2876
	s_lshl_b32 s3, s2, 2
	v_mbcnt_lo_u32_b32 v53, vcc_lo, 0
	s_add_i32 s3, s20, s3
	v_mbcnt_hi_u32_b32 v53, vcc_hi, v53
	v_lshl_add_u32 v53, v53, 2, s3
	ds_write_b32 v53, v4

; DI unsigned f2key(float f) { const unsigned u = __float_as_uint(f); return (u & 0x80000000u) ? ~u : (u | 0x80000000u); }
; template <int NV>
; DI void topk_row(const float* row, int s, LAS int* lst, int lane) {
;     ...
;     { const unsigned long long ra = (unsigned long long)row; const unsigned rlo = __builtin_amdgcn_readfirstlane((unsigned)ra), rhi = __builtin_amdgcn_readfirstlane((unsigned)(ra >> 32));
;       row = (const float*)(((unsigned long long)rhi << 32) | rlo); }
; #pragma unroll
;     for (int jo = 0; jo < NV / 16; ++jo) { const float* rb = row + jo * 1024;
; #pragma unroll
;         for (int ji = 0; ji < 16; ++ji) { const int j = jo * 16 + ji; const unsigned u = f2key(rb[ji * 64 + lane]); key[j] = (j * 64 + lane <= s) ? u : 0u; } }
.LBB0_3128:
	v_lshlrev_b32_e32 v0, 2, v2
	v_lshl_add_u64 v[34:35], s[12:13], 0, v[0:1]
	flat_load_dword v38, v[34:35]
	flat_load_dword v39, v[34:35] offset:256
	flat_load_dword v40, v[34:35] offset:512
	flat_load_dword v41, v[34:35] offset:768
	flat_load_dword v45, v[34:35] offset:1024
	flat_load_dword v46, v[34:35] offset:1280
	flat_load_dword v47, v[34:35] offset:1536
	flat_load_dword v52, v[34:35] offset:1792
	flat_load_dword v53, v[34:35] offset:2048
	flat_load_dword v54, v[34:35] offset:2304
	flat_load_dword v55, v[34:35] offset:2560
	flat_load_dword v56, v[34:35] offset:2816
	flat_load_dword v57, v[34:35] offset:3072
	s_add_u32 s0, s12, 0x1000
	s_addc_u32 s1, s13, 0
	flat_load_dword v58, v[34:35] offset:3328
	flat_load_dword v48, v[34:35] offset:3584
	flat_load_dword v51, v[34:35] offset:3840
	v_lshl_add_u64 v[34:35], s[0:1], 0, v[0:1]
	v_lshlrev_b32_e32 v0, 2, v4
	v_lshl_add_u64 v[36:37], s[0:1], 0, v[0:1]
	flat_load_dword v50, v[34:35]
	flat_load_dword v49, v[36:37]
	s_movk_i32 s2, 0xff
	s_waitcnt vmcnt(0) lgkmcnt(0)
	v_not_b32_e32 v0, v38
	v_or_b32_e32 v34, 0x80000000, v38
	v_cmp_gt_i32_e32 vcc, 0, v38
	v_not_b32_e32 v35, v39
	v_or_b32_e32 v36, 0x80000000, v39
	v_cndmask_b32_e32 v44, v34, v0, vcc
	v_cmp_gt_i32_e32 vcc, 0, v39
	v_not_b32_e32 v37, v40
	v_or_b32_e32 v42, 0x80000000, v40
	v_cndmask_b32_e32 v43, v36, v35, vcc
	v_cmp_gt_i32_e32 vcc, 0, v40
	v_not_b32_e32 v59, v41
	v_or_b32_e32 v60, 0x80000000, v41
	v_cndmask_b32_e32 v42, v42, v37, vcc
	v_cmp_gt_i32_e32 vcc, 0, v41
	v_not_b32_e32 v61, v45
	v_or_b32_e32 v62, 0x80000000, v45
	v_cndmask_b32_e32 v41, v60, v59, vcc
	v_cmp_gt_i32_e32 vcc, 0, v45
	v_not_b32_e32 v63, v46
	v_or_b32_e32 v128, 0x80000000, v46
	v_cndmask_b32_e32 v0, v62, v61, vcc
	v_cmp_gt_i32_e32 vcc, 0, v46
	v_not_b32_e32 v129, v47
	v_or_b32_e32 v130, 0x80000000, v47
	v_cndmask_b32_e32 v34, v128, v63, vcc
	v_cmp_gt_i32_e32 vcc, 0, v47
	v_not_b32_e32 v131, v52
	v_or_b32_e32 v132, 0x80000000, v52
	v_cndmask_b32_e32 v35, v130, v129, vcc
	v_cmp_gt_i32_e32 vcc, 0, v52
	v_not_b32_e32 v133, v53
	v_or_b32_e32 v134, 0x80000000, v53
	v_cndmask_b32_e32 v36, v132, v131, vcc
	v_cmp_gt_i32_e32 vcc, 0, v53
	v_not_b32_e32 v135, v54
	v_or_b32_e32 v136, 0x80000000, v54
	v_cndmask_b32_e32 v45, v134, v133, vcc
	v_cmp_gt_i32_e32 vcc, 0, v54
	v_not_b32_e32 v137, v55
	v_or_b32_e32 v138, 0x80000000, v55
	v_cndmask_b32_e32 v46, v136, v135, vcc
	v_cmp_gt_i32_e32 vcc, 0, v55
	v_not_b32_e32 v139, v56
	v_not_b32_e32 v54, v57
	v_cndmask_b32_e32 v47, v138, v137, vcc
	v_cmp_lt_u32_e32 vcc, s2, v161
	v_or_b32_e32 v55, 0x80000000, v57
	s_nop 0
	v_cndmask_b32_e32 v40, 0, v0, vcc
	v_cmp_lt_u32_e32 vcc, s52, v161
	v_lshlrev_b32_e32 v0, 2, v6
	s_nop 0
	v_cndmask_b32_e32 v39, 0, v34, vcc
	v_cmp_lt_u32_e32 vcc, s53, v161
	s_nop 1
	v_cndmask_b32_e32 v38, 0, v35, vcc
	v_cmp_lt_u32_e32 vcc, s54, v161
	s_nop 1
	v_cndmask_b32_e32 v37, 0, v36, vcc
	v_cmp_lt_u32_e32 vcc, s55, v161
	s_nop 1
	v_cndmask_b32_e32 v36, 0, v45, vcc
	v_cmp_lt_u32_e32 vcc, s56, v161
	v_or_b32_e32 v45, 0x80000000, v56
	s_nop 0
	v_cndmask_b32_e32 v35, 0, v46, vcc
	v_cmp_lt_u32_e32 vcc, s57, v161
	s_nop 1
	v_cndmask_b32_e32 v34, 0, v47, vcc
	v_lshl_add_u64 v[46:47], s[0:1], 0, v[0:1]
	flat_load_dword v52, v[46:47]
	v_lshlrev_b32_e32 v0, 2, v8
	v_lshl_add_u64 v[46:47], s[0:1], 0, v[0:1]
	flat_load_dword v53, v[46:47]
	v_lshlrev_b32_e32 v0, 2, v10
	v_cmp_gt_i32_e32 vcc, 0, v56
	v_lshl_add_u64 v[46:47], s[0:1], 0, v[0:1]
	flat_load_dword v56, v[46:47]
	v_cndmask_b32_e32 v45, v45, v139, vcc
	v_cmp_lt_u32_e32 vcc, s59, v161
	v_lshlrev_b32_e32 v0, 2, v12
	v_lshl_add_u64 v[46:47], s[0:1], 0, v[0:1]
	v_cndmask_b32_e32 v45, 0, v45, vcc
	v_cmp_gt_i32_e32 vcc, 0, v57
	flat_load_dword v59, v[46:47]
	v_lshlrev_b32_e32 v0, 2, v14
	v_cndmask_b32_e32 v54, v55, v54, vcc
	v_cmp_lt_u32_e32 vcc, s60, v161
	v_not_b32_e32 v47, v58
	v_or_b32_e32 v57, 0x80000000, v58
	v_cndmask_b32_e32 v46, 0, v54, vcc
	v_lshl_add_u64 v[54:55], s[0:1], 0, v[0:1]
	flat_load_dword v128, v[54:55]
	v_lshlrev_b32_e32 v0, 2, v16
	v_lshl_add_u64 v[54:55], s[0:1], 0, v[0:1]
	flat_load_dword v129, v[54:55]
	v_lshlrev_b32_e32 v0, 2, v18
	v_lshl_add_u64 v[54:55], s[0:1], 0, v[0:1]
	flat_load_dword v130, v[54:55]
	v_lshlrev_b32_e32 v0, 2, v20
	v_lshl_add_u64 v[54:55], s[0:1], 0, v[0:1]
	flat_load_dword v131, v[54:55]
	v_lshlrev_b32_e32 v0, 2, v22
	v_lshl_add_u64 v[54:55], s[0:1], 0, v[0:1]
	flat_load_dword v132, v[54:55]
	v_lshlrev_b32_e32 v0, 2, v24
	v_lshl_add_u64 v[54:55], s[0:1], 0, v[0:1]
	flat_load_dword v133, v[54:55]
	v_lshlrev_b32_e32 v0, 2, v26
	v_lshl_add_u64 v[54:55], s[0:1], 0, v[0:1]
	flat_load_dword v134, v[54:55]
	v_lshlrev_b32_e32 v0, 2, v28
	v_lshl_add_u64 v[54:55], s[0:1], 0, v[0:1]
	flat_load_dword v135, v[54:55]
	v_lshlrev_b32_e32 v0, 2, v30
	v_lshl_add_u64 v[54:55], s[0:1], 0, v[0:1]
	flat_load_dword v136, v[54:55]
	v_lshlrev_b32_e32 v0, 2, v32
	v_lshl_add_u64 v[54:55], s[0:1], 0, v[0:1]
	flat_load_dword v137, v[54:55]
	v_cmp_gt_i32_e32 vcc, 0, v58
	v_or_b32_e32 v58, 0x80000000, v48
	s_waitcnt vmcnt(0) lgkmcnt(0)
; DI unsigned f2key(float f) { const unsigned u = __float_as_uint(f); return (u & 0x80000000u) ? ~u : (u | 0x80000000u); }
; template <int NV>
; DI void topk_row(const float* row, int s, LAS int* lst, int lane) {
;     ...
;         for (int ji = 0; ji < 16; ++ji) { const int j = jo * 16 + ji; const unsigned u = f2key(rb[ji * 64 + lane]); key[j] = (j * 64 + lane <= s) ? u : 0u; } }
;     ...
; #pragma unroll 1
	v_not_b32_e32 v0, v52
	v_cndmask_b32_e32 v47, v57, v47, vcc
	v_cmp_lt_u32_e32 vcc, s61, v161
	v_not_b32_e32 v57, v48
	s_nop 0
	v_cndmask_b32_e32 v47, 0, v47, vcc
	v_cmp_gt_i32_e32 vcc, 0, v48
	s_nop 1
	v_cndmask_b32_e32 v48, v58, v57, vcc
	v_cmp_lt_u32_e32 vcc, s62, v161
	v_not_b32_e32 v57, v51
	v_or_b32_e32 v58, 0x80000000, v51
	v_cndmask_b32_e32 v48, 0, v48, vcc
	v_cmp_gt_i32_e32 vcc, 0, v51
	s_nop 1
	v_cndmask_b32_e32 v51, v58, v57, vcc
	v_cmp_lt_u32_e32 vcc, s63, v161
	v_not_b32_e32 v57, v50
	v_or_b32_e32 v58, 0x80000000, v50
	v_cndmask_b32_e32 v51, 0, v51, vcc
	v_cmp_gt_i32_e32 vcc, 0, v50
	s_nop 1
	v_cndmask_b32_e32 v50, v58, v57, vcc
	v_cmp_lt_u32_e32 vcc, s64, v161
	v_or_b32_e32 v58, 0x80000000, v49
	s_nop 0
	v_cndmask_b32_e32 v57, 0, v50, vcc
	v_not_b32_e32 v50, v49
	v_cmp_gt_i32_e32 vcc, 0, v49
	s_nop 1
	v_cndmask_b32_e32 v49, v58, v50, vcc
	v_cmp_lt_u32_e32 vcc, s65, v161
	s_nop 1
	v_cndmask_b32_e32 v63, 0, v49, vcc
	v_or_b32_e32 v49, 0x80000000, v52
	v_cmp_gt_i32_e32 vcc, 0, v52
	s_nop 1
	v_cndmask_b32_e32 v0, v49, v0, vcc
	v_cmp_lt_u32_e32 vcc, s66, v161
	v_or_b32_e32 v49, 0x80000000, v53
	s_nop 0
	v_cndmask_b32_e32 v62, 0, v0, vcc
	v_not_b32_e32 v0, v53
	v_cmp_gt_i32_e32 vcc, 0, v53
	s_nop 1
	v_cndmask_b32_e32 v0, v49, v0, vcc
	v_cmp_lt_u32_e32 vcc, s67, v161
	v_or_b32_e32 v49, 0x80000000, v56
	s_nop 0
	v_cndmask_b32_e32 v61, 0, v0, vcc
	v_not_b32_e32 v0, v56
	v_cmp_gt_i32_e32 vcc, 0, v56
	s_nop 1
	v_cndmask_b32_e32 v0, v49, v0, vcc
	v_cmp_lt_u32_e32 vcc, s68, v161
	v_or_b32_e32 v49, 0x80000000, v59
	s_nop 0
	v_cndmask_b32_e32 v60, 0, v0, vcc
	v_not_b32_e32 v0, v59
	v_cmp_gt_i32_e32 vcc, 0, v59
	s_nop 1
	v_cndmask_b32_e32 v0, v49, v0, vcc
	v_cmp_lt_u32_e32 vcc, s69, v161
	v_or_b32_e32 v49, 0x80000000, v128
	s_nop 0
	v_cndmask_b32_e32 v59, 0, v0, vcc
	v_not_b32_e32 v0, v128
	v_cmp_gt_i32_e32 vcc, 0, v128
	v_or_b32_e32 v128, 0x80000000, v136
	s_nop 0
	v_cndmask_b32_e32 v0, v49, v0, vcc
	v_cmp_lt_u32_e32 vcc, s70, v161
	v_or_b32_e32 v49, 0x80000000, v129
	s_nop 0
	v_cndmask_b32_e32 v58, 0, v0, vcc
	v_not_b32_e32 v0, v129
	v_cmp_gt_i32_e32 vcc, 0, v129
	v_or_b32_e32 v129, 0x80000000, v137
	s_nop 0
	v_cndmask_b32_e32 v0, v49, v0, vcc
	v_cmp_lt_u32_e32 vcc, s71, v161
	v_or_b32_e32 v49, 0x80000000, v130
	s_nop 0
	v_cndmask_b32_e32 v56, 0, v0, vcc
	v_not_b32_e32 v0, v130
	v_cmp_gt_i32_e32 vcc, 0, v130
	v_mov_b32_e32 v130, 31
	s_nop 0
	v_cndmask_b32_e32 v0, v49, v0, vcc
	v_cmp_lt_u32_e32 vcc, s72, v161
	v_or_b32_e32 v49, 0x80000000, v131
	s_nop 0
	v_cndmask_b32_e32 v55, 0, v0, vcc
	v_not_b32_e32 v0, v131
	v_cmp_gt_i32_e32 vcc, 0, v131
	s_nop 1
	v_cndmask_b32_e32 v0, v49, v0, vcc
	v_cmp_lt_u32_e32 vcc, s73, v161
	v_or_b32_e32 v49, 0x80000000, v132
	s_nop 0
	v_cndmask_b32_e32 v54, 0, v0, vcc
	v_not_b32_e32 v0, v132
	v_cmp_gt_i32_e32 vcc, 0, v132
	s_nop 1
	v_cndmask_b32_e32 v0, v49, v0, vcc
	v_cmp_lt_u32_e32 vcc, s74, v161
	v_or_b32_e32 v49, 0x80000000, v133
	s_nop 0
	v_cndmask_b32_e32 v53, 0, v0, vcc
	v_not_b32_e32 v0, v133
	v_cmp_gt_i32_e32 vcc, 0, v133
	s_nop 1
	v_cndmask_b32_e32 v0, v49, v0, vcc
	v_cmp_lt_u32_e32 vcc, s75, v161
	v_or_b32_e32 v49, 0x80000000, v134
	s_nop 0
	v_cndmask_b32_e32 v52, 0, v0, vcc
	v_not_b32_e32 v0, v134
	v_cmp_gt_i32_e32 vcc, 0, v134
	s_nop 1
	v_cndmask_b32_e32 v0, v49, v0, vcc
	v_cmp_lt_u32_e32 vcc, s76, v161
	v_or_b32_e32 v49, 0x80000000, v135
	s_nop 0
	v_cndmask_b32_e32 v50, 0, v0, vcc
	v_not_b32_e32 v0, v135
	v_cmp_gt_i32_e32 vcc, 0, v135
	s_nop 1
	v_cndmask_b32_e32 v0, v49, v0, vcc
	v_cmp_lt_u32_e32 vcc, s77, v161
	s_nop 1
	v_cndmask_b32_e32 v49, 0, v0, vcc
	v_not_b32_e32 v0, v136
	v_cmp_gt_i32_e32 vcc, 0, v136
	s_nop 1
	v_cndmask_b32_e32 v0, v128, v0, vcc
	v_cmp_lt_u32_e32 vcc, s78, v161
	v_not_b32_e32 v128, v137
	s_nop 0
	v_cndmask_b32_e32 v0, 0, v0, vcc
	v_cmp_gt_i32_e32 vcc, 0, v137
	s_nop 1
	v_cndmask_b32_e32 v128, v129, v128, vcc
	v_cmp_lt_u32_e32 vcc, s79, v161
	v_mov_b32_e32 v129, 0
	s_nop 0
	v_cndmask_b32_e32 v128, 0, v128, vcc
	v_max_u32_e32 v255, v44, v43
	v_max_u32_e32 v255, v255, v42
	v_max_u32_e32 v255, v255, v41
	v_max_u32_e32 v255, v255, v40
	v_max_u32_e32 v255, v255, v39
	v_max_u32_e32 v255, v255, v38
	v_max_u32_e32 v255, v255, v37
	v_max_u32_e32 v255, v255, v36
	v_max_u32_e32 v255, v255, v35
	v_max_u32_e32 v255, v255, v34
	v_max_u32_e32 v255, v255, v45
	v_max_u32_e32 v255, v255, v46
	v_max_u32_e32 v255, v255, v47
	v_max_u32_e32 v255, v255, v48
	v_max_u32_e32 v255, v255, v51
	v_max_u32_e32 v255, v255, v57
	v_max_u32_e32 v255, v255, v63
	v_max_u32_e32 v255, v255, v62
	v_max_u32_e32 v255, v255, v61
	v_max_u32_e32 v255, v255, v60
	v_max_u32_e32 v255, v255, v59
	v_max_u32_e32 v255, v255, v58
	v_max_u32_e32 v255, v255, v56
	v_max_u32_e32 v255, v255, v55
	v_max_u32_e32 v255, v255, v54
	v_max_u32_e32 v255, v255, v53
	v_max_u32_e32 v255, v255, v52
	v_max_u32_e32 v255, v255, v50
	v_max_u32_e32 v255, v255, v49
	v_max_u32_e32 v255, v255, v0
	v_max_u32_e32 v255, v255, v128
	s_nop 1
	v_max_u32_dpp v255, v255, v255 quad_perm:[1,0,3,2] row_mask:0xf bank_mask:0xf bound_ctrl:1
	s_nop 1
	v_max_u32_dpp v255, v255, v255 quad_perm:[2,3,0,1] row_mask:0xf bank_mask:0xf bound_ctrl:1
	s_nop 1
	v_max_u32_dpp v255, v255, v255 row_half_mirror row_mask:0xf bank_mask:0xf bound_ctrl:1
	s_nop 1
	v_max_u32_dpp v255, v255, v255 row_mirror row_mask:0xf bank_mask:0xf bound_ctrl:1
	s_nop 0
	v_readlane_b32 s99, v255, 0
	v_readlane_b32 s100, v255, 16
	s_max_u32 s99, s99, s100
	v_readlane_b32 s100, v255, 32
	s_max_u32 s99, s99, s100
	v_readlane_b32 s100, v255, 48
	s_max_u32 s99, s99, s100
; DI unsigned mbcnt64(unsigned long long m) { return __builtin_amdgcn_mbcnt_hi((unsigned)(m >> 32), __builtin_amdgcn_mbcnt_lo((unsigned)m, 0u)); }
; template <int NV>
; DI void topk_row(const float* row, int s, LAS int* lst, int lane) {
;     ...
; #pragma unroll 1
;     ...
;         const unsigned cand = T | (1u << bit); int c = 0;
; #pragma unroll
;         for (int j = 0; j < NV; ++j) asm volatile("v_cmp_le_u32 vcc, %2, %1\n\tv_addc_co_u32 %0, vcc, 0, %0, vcc" : "+v"(c) : "v"(key[j]), "s"(cand) : "vcc");
;         const int tot = wave_sum_i(c);
;         if (tot >= 256) T = cand;
;         if (tot == 256) break;
;     }
;     int bgt = 0;
; #pragma unroll
;     for (int j = 0; j < NV; ++j) { const bool sg = key[j] > T; const unsigned long long mg = __ballot(sg); if (sg) lst[bgt + (int)mbcnt64(mg)] = j * 64 + lane; bgt += __builtin_popcountll(mg); }
.LBB0_3129:
	v_lshlrev_b32_e64 v131, v130, 1
	v_mov_b32_e32 v132, 0
	v_or_b32_e32 v131, v131, v129
	s_nop 0
	v_readfirstlane_b32 s100, v131
	s_mov_b32 s0, 0
	s_cmp_gt_u32 s100, s99
	s_cbranch_scc1 .Lp12_skip_3129
	v_cmp_le_u32 vcc, v131, v44
	v_addc_co_u32 v132, vcc, 0, v132, vcc
	s_nop 0
	v_cmp_le_u32 vcc, v131, v43
	v_addc_co_u32 v132, vcc, 0, v132, vcc
	s_nop 0
	v_cmp_le_u32 vcc, v131, v42
	v_addc_co_u32 v132, vcc, 0, v132, vcc
	s_nop 0
	v_cmp_le_u32 vcc, v131, v41
	v_addc_co_u32 v132, vcc, 0, v132, vcc
	s_nop 0
	v_cmp_le_u32 vcc, v131, v40
	v_addc_co_u32 v132, vcc, 0, v132, vcc
	s_nop 0
	v_cmp_le_u32 vcc, v131, v39
	v_addc_co_u32 v132, vcc, 0, v132, vcc
	s_nop 0
	v_cmp_le_u32 vcc, v131, v38
	v_addc_co_u32 v132, vcc, 0, v132, vcc
	s_nop 0
	v_cmp_le_u32 vcc, v131, v37
	v_addc_co_u32 v132, vcc, 0, v132, vcc
	s_nop 0
	v_cmp_le_u32 vcc, v131, v36
	v_addc_co_u32 v132, vcc, 0, v132, vcc
	s_nop 0
	v_cmp_le_u32 vcc, v131, v35
	v_addc_co_u32 v132, vcc, 0, v132, vcc
	s_nop 0
	v_cmp_le_u32 vcc, v131, v34
	v_addc_co_u32 v132, vcc, 0, v132, vcc
	s_nop 0
	v_cmp_le_u32 vcc, v131, v45
	v_addc_co_u32 v132, vcc, 0, v132, vcc
	s_nop 0
	v_cmp_le_u32 vcc, v131, v46
	v_addc_co_u32 v132, vcc, 0, v132, vcc
	s_nop 0
	v_cmp_le_u32 vcc, v131, v47
	v_addc_co_u32 v132, vcc, 0, v132, vcc
	s_nop 0
	v_cmp_le_u32 vcc, v131, v48
	v_addc_co_u32 v132, vcc, 0, v132, vcc
	s_nop 0
	v_cmp_le_u32 vcc, v131, v51
	v_addc_co_u32 v132, vcc, 0, v132, vcc
	s_nop 0
	v_cmp_le_u32 vcc, v131, v57
	v_addc_co_u32 v132, vcc, 0, v132, vcc
	s_nop 0
	v_cmp_le_u32 vcc, v131, v63
	v_addc_co_u32 v132, vcc, 0, v132, vcc
	s_nop 0
	v_cmp_le_u32 vcc, v131, v62
	v_addc_co_u32 v132, vcc, 0, v132, vcc
	s_nop 0
	v_cmp_le_u32 vcc, v131, v61
	v_addc_co_u32 v132, vcc, 0, v132, vcc
	s_nop 0
	v_cmp_le_u32 vcc, v131, v60
	v_addc_co_u32 v132, vcc, 0, v132, vcc
	s_nop 0
	v_cmp_le_u32 vcc, v131, v59
	v_addc_co_u32 v132, vcc, 0, v132, vcc
	s_nop 0
	v_cmp_le_u32 vcc, v131, v58
	v_addc_co_u32 v132, vcc, 0, v132, vcc
	s_nop 0
	v_cmp_le_u32 vcc, v131, v56
	v_addc_co_u32 v132, vcc, 0, v132, vcc
	s_nop 0
	v_cmp_le_u32 vcc, v131, v55
	v_addc_co_u32 v132, vcc, 0, v132, vcc
	s_nop 0
	v_cmp_le_u32 vcc, v131, v54
	v_addc_co_u32 v132, vcc, 0, v132, vcc
	s_nop 0
	v_cmp_le_u32 vcc, v131, v53
	v_addc_co_u32 v132, vcc, 0, v132, vcc
	s_nop 0
	v_cmp_le_u32 vcc, v131, v52
	v_addc_co_u32 v132, vcc, 0, v132, vcc
	s_nop 0
	v_cmp_le_u32 vcc, v131, v50
	v_addc_co_u32 v132, vcc, 0, v132, vcc
	s_nop 0
	v_cmp_le_u32 vcc, v131, v49
	v_addc_co_u32 v132, vcc, 0, v132, vcc
	s_nop 0
	v_cmp_le_u32 vcc, v131, v0
	v_addc_co_u32 v132, vcc, 0, v132, vcc
	s_nop 0
	v_cmp_le_u32 vcc, v131, v128
	v_addc_co_u32 v132, vcc, 0, v132, vcc
	s_nop 1
	v_add_u32_dpp v132, v132, v132 quad_perm:[1,0,3,2] row_mask:0xf bank_mask:0xf bound_ctrl:1
	s_nop 1
	v_add_u32_dpp v132, v132, v132 quad_perm:[2,3,0,1] row_mask:0xf bank_mask:0xf bound_ctrl:1
	s_nop 1
	v_add_u32_dpp v132, v132, v132 row_half_mirror row_mask:0xf bank_mask:0xf bound_ctrl:1
	s_nop 1
	v_add_u32_dpp v132, v132, v132 row_mirror row_mask:0xf bank_mask:0xf bound_ctrl:1
	s_nop 0
	v_readlane_b32 s0, v132, 0
	v_readlane_b32 s1, v132, 16
	s_add_i32 s0, s1, s0
	v_readlane_b32 s1, v132, 32
	s_add_i32 s0, s0, s1
	v_readlane_b32 s1, v132, 48
	s_add_i32 s0, s0, s1
.Lp12_skip_3129:
	s_cmpk_gt_i32 s0, 0xff
	s_cselect_b64 vcc, -1, 0
	s_cmpk_eq_i32 s0, 0x100
	v_cndmask_b32_e32 v129, v129, v131, vcc
	s_cselect_b64 s[0:1], -1, 0
	v_subrev_co_u32_e32 v130, vcc, 1, v130
	s_or_b64 s[0:1], s[0:1], vcc
	s_andn2_b64 vcc, exec, s[0:1]
	s_cbranch_vccnz .LBB0_3129
	v_cmp_gt_u32_e32 vcc, v44, v129
	s_and_saveexec_b64 s[0:1], vcc
	s_nop 0
	v_mbcnt_lo_u32_b32 v130, vcc_lo, 0
	v_mbcnt_hi_u32_b32 v130, vcc_hi, v130
	v_lshl_add_u32 v130, v130, 2, s20
	ds_write_b32 v130, v2
	s_or_b64 exec, exec, s[0:1]
	s_bcnt1_i32_b64 s2, vcc
	v_cmp_gt_u32_e32 vcc, v43, v129
	s_and_saveexec_b64 s[0:1], vcc
	s_cbranch_execz .LBB0_3134
	s_lshl_b32 s3, s2, 2
	v_mbcnt_lo_u32_b32 v130, vcc_lo, 0
	s_add_i32 s3, s20, s3
	v_mbcnt_hi_u32_b32 v130, vcc_hi, v130
	v_lshl_add_u32 v130, v130, 2, s3
	ds_write_b32 v130, v4
